# GEMM main loops: removed the duplicate s_waitcnt lgkmcnt(0) after each s_setprio 1 (30 sites)
# speedup vs baseline: 1.0044x; 1.0044x over previous
; #define PG8_STAGE(bufoff, gbase, voff) do { _Pragma("unroll") for (int _i = 0; _i < 2; ++_i) \
;         __builtin_amdgcn_global_load_lds((const unsigned*)((const char*)(gbase) + (voff)[_i]), (LAS unsigned*)(lds + (bufoff) + ldsw + _i * 8192), 16, 0, 0); } while (0)
; #define PG8_LDA(dst, b, h) do { _Pragma("unroll") for (int m = 0; m < 4; ++m) _Pragma("unroll") for (int k = 0; k < 2; ++k) dst[m][k] = *(const LAS bf16x8*)(lds + PG8_SA(b, h) + aoff + m * 2048 + k * 1024); } while (0)
; #define PG8_LDB(dst, b, h) do { _Pragma("unroll") for (int n = 0; n < 2; ++n) _Pragma("unroll") for (int k = 0; k < 2; ++k) dst[n][k] = *(const LAS bf16x8*)(lds + PG8_SB(b, h) + boff + n * 2048 + k * 1024); } while (0)
; #define PG8_MMA(ai, bj, At, Bt) do { __builtin_amdgcn_s_setprio(1); _Pragma("unroll") for (int m = 0; m < 4; ++m) _Pragma("unroll") for (int n = 0; n < 2; ++n) _Pragma("unroll") for (int k = 0; k < 2; ++k) \
;         acc[ai][bj][m][n] = __builtin_amdgcn_mfma_f32_16x16x32_bf16(Bt[n][k], At[m][k], acc[ai][bj][m][n], 0, 0, 0); __builtin_amdgcn_s_setprio(0); } while (0)
; #define PG8_WAIT_V(n) asm volatile("s_waitcnt vmcnt(" #n ")" ::: "memory")
; #define PG8_WAIT_L(n) asm volatile("s_waitcnt lgkmcnt(" #n ")" ::: "memory")
; template <class Epi>
; __device__ __forceinline__ void gemm_phase(const int TID, const int BID, LAS unsigned char* lds, const Gemm g, const StaticOrder& S, const Epi& E) {
;     ...
;         for (int t = 0; t < nt; t += 2) {
;             const bool last = (t == nt - 2);
;             const char* a1 = cA + (size_t)(t + 1) * kstep;
;             const char* a2 = last ? nA : cA + (size_t)(t + 2) * kstep; const char* b2 = last ? nB : cB + (size_t)(t + 2) * kstep;
;             const char* a3 = a2 + kstep; const char* b3 = b2 + kstep;
;             PG8_LDB(B0, 0, 0); PG8_SCHED; PG8_LDA(At, 0, 0); PG8_STAGE(PG8_SA(1, 1), a1 + hstepA, voffA);
;             PG8_WAIT_L(8); PG8_BAR; PG8_WAIT_L(0); PG8_MMA(0, 0, At, B0); PG8_BAR; PG8_SCHED;
;             PG8_LDB(B1, 0, 1); PG8_STAGE(PG8_SB(0, 0), b2, voffB);
;             PG8_BAR; PG8_WAIT_L(0); PG8_MMA(0, 1, At, B1); PG8_BAR;
;             PG8_LDA(At, 0, 1); PG8_STAGE(PG8_SA(0, 0), a2, voffA);
;             PG8_BAR; PG8_WAIT_L(0); PG8_MMA(1, 0, At, B0); PG8_BAR; PG8_SCHED;
;             PG8_STAGE(PG8_SB(0, 1), b2 + hstepB, voffB);
;             PG8_WAIT_V(6); PG8_BAR; PG8_MMA(1, 1, At, B1); PG8_BAR;
.LBB0_799:
	v_add_u32_e32 v173, s23, v170
	ds_read_b128 v[138:141], v173
	ds_read_b128 v[142:145], v173 offset:1024
	ds_read_b128 v[174:177], v173 offset:2048
	ds_read_b128 v[178:181], v173 offset:3072
	s_add_u32 s26, s24, 0xfff80080
	s_addc_u32 s27, s25, -1
	s_cmp_eq_u32 s56, 28
	s_cselect_b32 s29, s17, s27
	s_cselect_b32 s28, s52, s26
	s_cselect_b32 s27, s15, s55
	s_cselect_b32 s26, s53, s54
	v_lshl_add_u64 v[200:201], s[24:25], 0, v[134:135]
	s_add_i32 m0, s35, 0xc000
	ds_read_b128 v[182:185], v172
	ds_read_b128 v[196:199], v172 offset:1024
	ds_read_b128 v[208:211], v172 offset:2048
	ds_read_b128 v[212:215], v172 offset:3072
	ds_read_b128 v[216:219], v172 offset:4096
	ds_read_b128 v[220:223], v172 offset:5120
	ds_read_b128 v[224:227], v172 offset:6144
	ds_read_b128 v[228:231], v172 offset:7168
	global_load_lds_dwordx4 v[200:201], off
	v_lshl_add_u64 v[200:201], s[24:25], 0, v[136:137]
	s_add_i32 m0, s35, 0xe000
	s_nop 0
	global_load_lds_dwordx4 v[200:201], off
	s_waitcnt lgkmcnt(8)
	s_barrier
	s_waitcnt lgkmcnt(0)
	s_setprio 1
	v_mfma_f32_16x16x32_bf16 v[124:127], v[138:141], v[182:185], v[124:127]
	v_mfma_f32_16x16x32_bf16 v[120:123], v[174:177], v[182:185], v[120:123]
	v_mfma_f32_16x16x32_bf16 v[108:111], v[138:141], v[208:211], v[108:111]
	v_mfma_f32_16x16x32_bf16 v[104:107], v[174:177], v[208:211], v[104:107]
	v_mfma_f32_16x16x32_bf16 v[92:95], v[138:141], v[216:219], v[92:95]
	v_mfma_f32_16x16x32_bf16 v[88:91], v[174:177], v[216:219], v[88:91]
	v_mfma_f32_16x16x32_bf16 v[76:79], v[138:141], v[224:227], v[76:79]
	v_mfma_f32_16x16x32_bf16 v[72:75], v[174:177], v[224:227], v[72:75]
	v_mfma_f32_16x16x32_bf16 v[124:127], v[142:145], v[196:199], v[124:127]
	v_mfma_f32_16x16x32_bf16 v[120:123], v[178:181], v[196:199], v[120:123]
	v_mfma_f32_16x16x32_bf16 v[108:111], v[142:145], v[212:215], v[108:111]
	v_mfma_f32_16x16x32_bf16 v[104:107], v[178:181], v[212:215], v[104:107]
	v_mfma_f32_16x16x32_bf16 v[92:95], v[142:145], v[220:223], v[92:95]
	v_mfma_f32_16x16x32_bf16 v[88:91], v[178:181], v[220:223], v[88:91]
	v_mfma_f32_16x16x32_bf16 v[76:79], v[142:145], v[228:231], v[76:79]
	v_mfma_f32_16x16x32_bf16 v[72:75], v[178:181], v[228:231], v[72:75]
	s_setprio 0
	s_barrier
	s_mov_b32 m0, s31
	v_add_u32_e32 v173, s37, v170
	v_lshl_add_u64 v[200:201], s[26:27], 0, v[160:161]
	ds_read_b128 v[232:235], v173
	ds_read_b128 v[236:239], v173 offset:1024
	ds_read_b128 v[240:243], v173 offset:2048
	ds_read_b128 v[244:247], v173 offset:3072
	global_load_lds_dwordx4 v[200:201], off
	v_lshl_add_u64 v[248:249], s[26:27], 0, v[132:133]
	s_mov_b32 m0, s34
	s_nop 0
	global_load_lds_dwordx4 v[248:249], off
	s_barrier
	s_waitcnt lgkmcnt(0)
	s_setprio 1
	v_mfma_f32_16x16x32_bf16 v[116:119], v[232:235], v[182:185], v[116:119]
	v_mfma_f32_16x16x32_bf16 v[112:115], v[240:243], v[182:185], v[112:115]
	v_mfma_f32_16x16x32_bf16 v[100:103], v[232:235], v[208:211], v[100:103]
	v_mfma_f32_16x16x32_bf16 v[96:99], v[240:243], v[208:211], v[96:99]
	v_mfma_f32_16x16x32_bf16 v[84:87], v[232:235], v[216:219], v[84:87]
	v_mfma_f32_16x16x32_bf16 v[80:83], v[240:243], v[216:219], v[80:83]
	v_mfma_f32_16x16x32_bf16 v[68:71], v[232:235], v[224:227], v[68:71]
	v_mfma_f32_16x16x32_bf16 v[64:67], v[240:243], v[224:227], v[64:67]
	v_mfma_f32_16x16x32_bf16 v[116:119], v[236:239], v[196:199], v[116:119]
	v_mfma_f32_16x16x32_bf16 v[112:115], v[244:247], v[196:199], v[112:115]
	v_mfma_f32_16x16x32_bf16 v[100:103], v[236:239], v[212:215], v[100:103]
	v_mfma_f32_16x16x32_bf16 v[96:99], v[244:247], v[212:215], v[96:99]
	v_mfma_f32_16x16x32_bf16 v[84:87], v[236:239], v[220:223], v[84:87]
	v_mfma_f32_16x16x32_bf16 v[80:83], v[244:247], v[220:223], v[80:83]
	v_mfma_f32_16x16x32_bf16 v[68:71], v[236:239], v[228:231], v[68:71]
	v_mfma_f32_16x16x32_bf16 v[64:67], v[244:247], v[228:231], v[64:67]
	s_setprio 0
	s_mov_b32 m0, s35
	v_lshl_add_u64 v[250:251], s[28:29], 0, v[128:129]
	s_barrier
	ds_read_b128 v[182:185], v172 offset:16384
	ds_read_b128 v[196:199], v172 offset:17408
	ds_read_b128 v[208:211], v172 offset:18432
	ds_read_b128 v[212:215], v172 offset:19456
	ds_read_b128 v[216:219], v172 offset:20480
	ds_read_b128 v[220:223], v172 offset:21504
	ds_read_b128 v[224:227], v172 offset:22528
	ds_read_b128 v[228:231], v172 offset:23552
	global_load_lds_dwordx4 v[250:251], off
	v_lshl_add_u64 v[252:253], s[28:29], 0, v[130:131]
	s_mov_b32 m0, s36
	s_nop 0
	global_load_lds_dwordx4 v[252:253], off
	s_barrier
	s_waitcnt lgkmcnt(0)
	s_setprio 1
	v_mfma_f32_16x16x32_bf16 v[60:63], v[138:141], v[182:185], v[60:63]
	v_mfma_f32_16x16x32_bf16 v[56:59], v[174:177], v[182:185], v[56:59]
	v_mfma_f32_16x16x32_bf16 v[44:47], v[138:141], v[208:211], v[44:47]
	v_mfma_f32_16x16x32_bf16 v[40:43], v[174:177], v[208:211], v[40:43]
	v_mfma_f32_16x16x32_bf16 v[28:31], v[138:141], v[216:219], v[28:31]
	v_mfma_f32_16x16x32_bf16 v[24:27], v[174:177], v[216:219], v[24:27]
	v_mfma_f32_16x16x32_bf16 v[12:15], v[138:141], v[224:227], v[12:15]
	v_mfma_f32_16x16x32_bf16 v[8:11], v[174:177], v[224:227], v[8:11]
	v_mfma_f32_16x16x32_bf16 v[60:63], v[142:145], v[196:199], v[60:63]
	v_mfma_f32_16x16x32_bf16 v[56:59], v[178:181], v[196:199], v[56:59]
	v_mfma_f32_16x16x32_bf16 v[44:47], v[142:145], v[212:215], v[44:47]
	v_mfma_f32_16x16x32_bf16 v[40:43], v[178:181], v[212:215], v[40:43]
	v_mfma_f32_16x16x32_bf16 v[28:31], v[142:145], v[220:223], v[28:31]
	v_mfma_f32_16x16x32_bf16 v[24:27], v[178:181], v[220:223], v[24:27]
	v_mfma_f32_16x16x32_bf16 v[12:15], v[142:145], v[228:231], v[12:15]
	v_mfma_f32_16x16x32_bf16 v[8:11], v[178:181], v[228:231], v[8:11]
	s_setprio 0
	s_barrier
; #define PG8_STAGE(bufoff, gbase, voff) do { _Pragma("unroll") for (int _i = 0; _i < 2; ++_i) \
;         __builtin_amdgcn_global_load_lds((const unsigned*)((const char*)(gbase) + (voff)[_i]), (LAS unsigned*)(lds + (bufoff) + ldsw + _i * 8192), 16, 0, 0); } while (0)
; #define PG8_LDA(dst, b, h) do { _Pragma("unroll") for (int m = 0; m < 4; ++m) _Pragma("unroll") for (int k = 0; k < 2; ++k) dst[m][k] = *(const LAS bf16x8*)(lds + PG8_SA(b, h) + aoff + m * 2048 + k * 1024); } while (0)
; #define PG8_LDB(dst, b, h) do { _Pragma("unroll") for (int n = 0; n < 2; ++n) _Pragma("unroll") for (int k = 0; k < 2; ++k) dst[n][k] = *(const LAS bf16x8*)(lds + PG8_SB(b, h) + boff + n * 2048 + k * 1024); } while (0)
; #define PG8_MMA(ai, bj, At, Bt) do { __builtin_amdgcn_s_setprio(1); _Pragma("unroll") for (int m = 0; m < 4; ++m) _Pragma("unroll") for (int n = 0; n < 2; ++n) _Pragma("unroll") for (int k = 0; k < 2; ++k) \
;         acc[ai][bj][m][n] = __builtin_amdgcn_mfma_f32_16x16x32_bf16(Bt[n][k], At[m][k], acc[ai][bj][m][n], 0, 0, 0); __builtin_amdgcn_s_setprio(0); } while (0)
; #define PG8_WAIT_V(n) asm volatile("s_waitcnt vmcnt(" #n ")" ::: "memory")
; #define PG8_WAIT_L(n) asm volatile("s_waitcnt lgkmcnt(" #n ")" ::: "memory")
; #define PG8_BAR __builtin_amdgcn_s_barrier()
; #define PG8_SCHED __builtin_amdgcn_sched_barrier(0)
; template <class Epi>
; __device__ __forceinline__ void gemm_phase(const int TID, const int BID, LAS unsigned char* lds, const Gemm g, const StaticOrder& S, const Epi& E) {
;     ...
;             PG8_STAGE(PG8_SB(0, 1), b2 + hstepB, voffB);
;             PG8_WAIT_V(6); PG8_BAR; PG8_MMA(1, 1, At, B1); PG8_BAR;
;             PG8_LDB(B0, 1, 0); PG8_SCHED; PG8_LDA(At, 1, 0); PG8_STAGE(PG8_SA(0, 1), a2 + hstepA, voffA);
;             PG8_WAIT_L(8); PG8_BAR; PG8_WAIT_L(0); PG8_MMA(0, 0, At, B0); PG8_BAR; PG8_SCHED;
;             PG8_LDB(B1, 1, 1); PG8_STAGE(PG8_SB(1, 0), b3, voffB);
;             PG8_BAR; PG8_WAIT_L(0); PG8_MMA(0, 1, At, B1); PG8_BAR;
;             PG8_LDA(At, 1, 1); PG8_STAGE(PG8_SA(1, 0), a3, voffA);
;             PG8_BAR; PG8_WAIT_L(0); PG8_MMA(1, 0, At, B0); PG8_BAR; PG8_SCHED;
	s_add_u32 s58, s26, 0x80000
	s_addc_u32 s59, s27, 0
	s_mov_b32 m0, s38
	v_lshl_add_u64 v[138:139], s[58:59], 0, v[160:161]
	global_load_lds_dwordx4 v[138:139], off
	v_lshl_add_u64 v[138:139], s[58:59], 0, v[132:133]
	s_mov_b32 m0, s39
	s_nop 0
	global_load_lds_dwordx4 v[138:139], off
	s_waitcnt vmcnt(6)
	s_barrier
	s_setprio 1
	v_mfma_f32_16x16x32_bf16 v[52:55], v[232:235], v[182:185], v[52:55]
	v_mfma_f32_16x16x32_bf16 v[48:51], v[240:243], v[182:185], v[48:51]
	v_mfma_f32_16x16x32_bf16 v[36:39], v[232:235], v[208:211], v[36:39]
	v_mfma_f32_16x16x32_bf16 v[32:35], v[240:243], v[208:211], v[32:35]
	v_mfma_f32_16x16x32_bf16 v[20:23], v[232:235], v[216:219], v[20:23]
	v_mfma_f32_16x16x32_bf16 v[16:19], v[240:243], v[216:219], v[16:19]
	v_mfma_f32_16x16x32_bf16 v[4:7], v[232:235], v[224:227], v[4:7]
	v_mfma_f32_16x16x32_bf16 v[0:3], v[240:243], v[224:227], v[0:3]
	v_mfma_f32_16x16x32_bf16 v[52:55], v[236:239], v[196:199], v[52:55]
	v_mfma_f32_16x16x32_bf16 v[48:51], v[244:247], v[196:199], v[48:51]
	v_mfma_f32_16x16x32_bf16 v[36:39], v[236:239], v[212:215], v[36:39]
	v_mfma_f32_16x16x32_bf16 v[32:35], v[244:247], v[212:215], v[32:35]
	v_mfma_f32_16x16x32_bf16 v[20:23], v[236:239], v[220:223], v[20:23]
	v_mfma_f32_16x16x32_bf16 v[16:19], v[244:247], v[220:223], v[16:19]
	v_mfma_f32_16x16x32_bf16 v[4:7], v[236:239], v[228:231], v[4:7]
	v_mfma_f32_16x16x32_bf16 v[0:3], v[244:247], v[228:231], v[0:3]
	s_setprio 0
	v_add_u32_e32 v173, s42, v170
	s_barrier
	ds_read_b128 v[138:141], v173
	ds_read_b128 v[142:145], v173 offset:1024
	ds_read_b128 v[174:177], v173 offset:2048
	ds_read_b128 v[178:181], v173 offset:3072
	s_add_u32 s28, s28, 0x80000
	s_addc_u32 s29, s29, 0
	s_mov_b32 m0, s40
	v_lshl_add_u64 v[232:233], s[28:29], 0, v[128:129]
	ds_read_b128 v[182:185], v172 offset:32768
	ds_read_b128 v[196:199], v172 offset:33792
	ds_read_b128 v[208:211], v172 offset:34816
	ds_read_b128 v[212:215], v172 offset:35840
	ds_read_b128 v[216:219], v172 offset:36864
	ds_read_b128 v[220:223], v172 offset:37888
	ds_read_b128 v[224:227], v172 offset:38912
	ds_read_b128 v[228:231], v172 offset:39936
	global_load_lds_dwordx4 v[232:233], off
	v_lshl_add_u64 v[232:233], s[28:29], 0, v[130:131]
	s_mov_b32 m0, s41
	s_nop 0
	global_load_lds_dwordx4 v[232:233], off
	s_waitcnt lgkmcnt(8)
	s_barrier
	s_waitcnt lgkmcnt(0)
	s_setprio 1
	v_mfma_f32_16x16x32_bf16 v[124:127], v[138:141], v[182:185], v[124:127]
	v_mfma_f32_16x16x32_bf16 v[120:123], v[174:177], v[182:185], v[120:123]
	v_mfma_f32_16x16x32_bf16 v[108:111], v[138:141], v[208:211], v[108:111]
	v_mfma_f32_16x16x32_bf16 v[104:107], v[174:177], v[208:211], v[104:107]
	v_mfma_f32_16x16x32_bf16 v[92:95], v[138:141], v[216:219], v[92:95]
	v_mfma_f32_16x16x32_bf16 v[88:91], v[174:177], v[216:219], v[88:91]
	v_mfma_f32_16x16x32_bf16 v[76:79], v[138:141], v[224:227], v[76:79]
	v_mfma_f32_16x16x32_bf16 v[72:75], v[174:177], v[224:227], v[72:75]
	v_mfma_f32_16x16x32_bf16 v[124:127], v[142:145], v[196:199], v[124:127]
	v_mfma_f32_16x16x32_bf16 v[120:123], v[178:181], v[196:199], v[120:123]
	v_mfma_f32_16x16x32_bf16 v[108:111], v[142:145], v[212:215], v[108:111]
	v_mfma_f32_16x16x32_bf16 v[104:107], v[178:181], v[212:215], v[104:107]
	v_mfma_f32_16x16x32_bf16 v[92:95], v[142:145], v[220:223], v[92:95]
	v_mfma_f32_16x16x32_bf16 v[88:91], v[178:181], v[220:223], v[88:91]
	v_mfma_f32_16x16x32_bf16 v[76:79], v[142:145], v[228:231], v[76:79]
	v_mfma_f32_16x16x32_bf16 v[72:75], v[178:181], v[228:231], v[72:75]
	s_setprio 0
	s_barrier
	s_mov_b32 m0, s43
	v_add_u32_e32 v173, s47, v170
	v_lshl_add_u64 v[200:201], v[200:201], 0, s[90:91]
	ds_read_b128 v[232:235], v173
	ds_read_b128 v[236:239], v173 offset:1024
	ds_read_b128 v[240:243], v173 offset:2048
	ds_read_b128 v[244:247], v173 offset:3072
	global_load_lds_dwordx4 v[200:201], off
	v_lshl_add_u64 v[200:201], v[248:249], 0, s[90:91]
	s_mov_b32 m0, s44
	s_nop 0
	global_load_lds_dwordx4 v[200:201], off
	s_barrier
	s_waitcnt lgkmcnt(0)
	s_setprio 1
	v_mfma_f32_16x16x32_bf16 v[116:119], v[232:235], v[182:185], v[116:119]
	v_mfma_f32_16x16x32_bf16 v[112:115], v[240:243], v[182:185], v[112:115]
	v_mfma_f32_16x16x32_bf16 v[100:103], v[232:235], v[208:211], v[100:103]
	v_mfma_f32_16x16x32_bf16 v[96:99], v[240:243], v[208:211], v[96:99]
	v_mfma_f32_16x16x32_bf16 v[84:87], v[232:235], v[216:219], v[84:87]
	v_mfma_f32_16x16x32_bf16 v[80:83], v[240:243], v[216:219], v[80:83]
	v_mfma_f32_16x16x32_bf16 v[68:71], v[232:235], v[224:227], v[68:71]
	v_mfma_f32_16x16x32_bf16 v[64:67], v[240:243], v[224:227], v[64:67]
	v_mfma_f32_16x16x32_bf16 v[116:119], v[236:239], v[196:199], v[116:119]
	v_mfma_f32_16x16x32_bf16 v[112:115], v[244:247], v[196:199], v[112:115]
	v_mfma_f32_16x16x32_bf16 v[100:103], v[236:239], v[212:215], v[100:103]
	v_mfma_f32_16x16x32_bf16 v[96:99], v[244:247], v[212:215], v[96:99]
	v_mfma_f32_16x16x32_bf16 v[84:87], v[236:239], v[220:223], v[84:87]
	v_mfma_f32_16x16x32_bf16 v[80:83], v[244:247], v[220:223], v[80:83]
	v_mfma_f32_16x16x32_bf16 v[68:71], v[236:239], v[228:231], v[68:71]
	v_mfma_f32_16x16x32_bf16 v[64:67], v[244:247], v[228:231], v[64:67]
	s_setprio 0
	s_mov_b32 m0, s45
	v_lshl_add_u64 v[200:201], v[250:251], 0, s[90:91]
	s_barrier
	ds_read_b128 v[182:185], v172 offset:49152
	ds_read_b128 v[196:199], v172 offset:50176
	ds_read_b128 v[208:211], v172 offset:51200
	ds_read_b128 v[212:215], v172 offset:52224
	ds_read_b128 v[216:219], v172 offset:53248
	ds_read_b128 v[220:223], v172 offset:54272
	ds_read_b128 v[224:227], v172 offset:55296
	ds_read_b128 v[228:231], v172 offset:56320
	global_load_lds_dwordx4 v[200:201], off
	v_lshl_add_u64 v[200:201], v[252:253], 0, s[90:91]
	s_mov_b32 m0, s46
	s_nop 0
	global_load_lds_dwordx4 v[200:201], off
	s_barrier
; __device__ __forceinline__ float rinv_st(stat_t s, float invn) { return rsqrtf((float)((double)s * (1.0 / 4294967296.0)) * invn + 1e-6f); }
; #define PG8_STAGE(bufoff, gbase, voff) do { _Pragma("unroll") for (int _i = 0; _i < 2; ++_i) \
;         __builtin_amdgcn_global_load_lds((const unsigned*)((const char*)(gbase) + (voff)[_i]), (LAS unsigned*)(lds + (bufoff) + ldsw + _i * 8192), 16, 0, 0); } while (0)
; #define PG8_MMA(ai, bj, At, Bt) do { __builtin_amdgcn_s_setprio(1); _Pragma("unroll") for (int m = 0; m < 4; ++m) _Pragma("unroll") for (int n = 0; n < 2; ++n) _Pragma("unroll") for (int k = 0; k < 2; ++k) \
;         acc[ai][bj][m][n] = __builtin_amdgcn_mfma_f32_16x16x32_bf16(Bt[n][k], At[m][k], acc[ai][bj][m][n], 0, 0, 0); __builtin_amdgcn_s_setprio(0); } while (0)
; #define PG8_WAIT_V(n) asm volatile("s_waitcnt vmcnt(" #n ")" ::: "memory")
; #define PG8_WAIT_L(n) asm volatile("s_waitcnt lgkmcnt(" #n ")" ::: "memory")
; #define PG8_BAR __builtin_amdgcn_s_barrier()
; #define PG8_SCHED __builtin_amdgcn_sched_barrier(0)
; template <class Epi>
; __device__ __forceinline__ void gemm_phase(const int TID, const int BID, LAS unsigned char* lds, const Gemm g, const StaticOrder& S, const Epi& E) {
;     ...
;             PG8_BAR; PG8_WAIT_L(0); PG8_MMA(1, 0, At, B0); PG8_BAR; PG8_SCHED;
;             PG8_STAGE(PG8_SB(1, 1), b3 + hstepB, voffB);
;             PG8_WAIT_V(6); PG8_BAR; PG8_MMA(1, 1, At, B1); PG8_BAR;
;         }
;         E(acc, cur, wr, wc, fr, fq);
;     __device__ __forceinline__ void operator()(const f32x4 (&acc)[2][2][4][2], const Unit& u, int wr, int wc, int fr, int fq) const {
;         const int row0 = u.pm * BM + wr * 64 + fr, col0 = u.pn * BM + wc * 32 + 8 * fq;
; #pragma unroll
;         for (int ai = 0; ai < 2; ++ai)
; #pragma unroll
;             for (int m = 0; m < 4; ++m) {
;                 const int row = row0 + ai * HALF + m * 16; const float r = rinv_st(stats[row], 1.0f / 2048.0f);
;                 bf16_t* rowp = raw + (size_t)row * NINP + col0;
; #pragma unroll
	s_waitcnt lgkmcnt(0)
	s_setprio 1
	v_mfma_f32_16x16x32_bf16 v[60:63], v[138:141], v[182:185], v[60:63]
	v_mfma_f32_16x16x32_bf16 v[56:59], v[174:177], v[182:185], v[56:59]
	v_mfma_f32_16x16x32_bf16 v[44:47], v[138:141], v[208:211], v[44:47]
	v_mfma_f32_16x16x32_bf16 v[40:43], v[174:177], v[208:211], v[40:43]
	v_mfma_f32_16x16x32_bf16 v[28:31], v[138:141], v[216:219], v[28:31]
	v_mfma_f32_16x16x32_bf16 v[24:27], v[174:177], v[216:219], v[24:27]
	v_mfma_f32_16x16x32_bf16 v[12:15], v[138:141], v[224:227], v[12:15]
	v_mfma_f32_16x16x32_bf16 v[8:11], v[174:177], v[224:227], v[8:11]
	v_mfma_f32_16x16x32_bf16 v[60:63], v[142:145], v[196:199], v[60:63]
	v_mfma_f32_16x16x32_bf16 v[56:59], v[178:181], v[196:199], v[56:59]
	v_mfma_f32_16x16x32_bf16 v[44:47], v[142:145], v[212:215], v[44:47]
	v_mfma_f32_16x16x32_bf16 v[40:43], v[178:181], v[212:215], v[40:43]
	v_mfma_f32_16x16x32_bf16 v[28:31], v[142:145], v[220:223], v[28:31]
	v_mfma_f32_16x16x32_bf16 v[24:27], v[178:181], v[220:223], v[24:27]
	v_mfma_f32_16x16x32_bf16 v[12:15], v[142:145], v[228:231], v[12:15]
	v_mfma_f32_16x16x32_bf16 v[8:11], v[178:181], v[228:231], v[8:11]
	s_setprio 0
	s_barrier
	s_add_u32 s26, s26, 0x80080
	s_addc_u32 s27, s27, 0
	s_mov_b32 m0, s48
	v_lshl_add_u64 v[138:139], s[26:27], 0, v[160:161]
	global_load_lds_dwordx4 v[138:139], off
	v_lshl_add_u64 v[138:139], s[26:27], 0, v[132:133]
	s_mov_b32 m0, s49
	s_nop 0
	global_load_lds_dwordx4 v[138:139], off
	s_waitcnt vmcnt(6)
	s_barrier
	s_setprio 1
	v_mfma_f32_16x16x32_bf16 v[52:55], v[232:235], v[182:185], v[52:55]
	v_mfma_f32_16x16x32_bf16 v[48:51], v[240:243], v[182:185], v[48:51]
	v_mfma_f32_16x16x32_bf16 v[36:39], v[232:235], v[208:211], v[36:39]
	v_mfma_f32_16x16x32_bf16 v[32:35], v[240:243], v[208:211], v[32:35]
	v_mfma_f32_16x16x32_bf16 v[20:23], v[232:235], v[216:219], v[20:23]
	v_mfma_f32_16x16x32_bf16 v[16:19], v[240:243], v[216:219], v[16:19]
	v_mfma_f32_16x16x32_bf16 v[4:7], v[232:235], v[224:227], v[4:7]
	v_mfma_f32_16x16x32_bf16 v[0:3], v[240:243], v[224:227], v[0:3]
	v_mfma_f32_16x16x32_bf16 v[52:55], v[236:239], v[196:199], v[52:55]
	v_mfma_f32_16x16x32_bf16 v[48:51], v[244:247], v[196:199], v[48:51]
	v_mfma_f32_16x16x32_bf16 v[36:39], v[236:239], v[212:215], v[36:39]
	v_mfma_f32_16x16x32_bf16 v[32:35], v[244:247], v[212:215], v[32:35]
	v_mfma_f32_16x16x32_bf16 v[20:23], v[236:239], v[220:223], v[20:23]
	v_mfma_f32_16x16x32_bf16 v[16:19], v[244:247], v[220:223], v[16:19]
	v_mfma_f32_16x16x32_bf16 v[4:7], v[236:239], v[228:231], v[4:7]
	v_mfma_f32_16x16x32_bf16 v[0:3], v[244:247], v[228:231], v[0:3]
	s_setprio 0
	s_add_i32 s56, s56, 2
	s_add_u32 s24, s24, 0x100
	s_addc_u32 s25, s25, 0
	s_add_u32 s54, s54, 0x100
	s_addc_u32 s55, s55, 0
	s_cmp_gt_u32 s56, 29
	s_barrier
	s_cbranch_scc0 .LBB0_799
	v_lshl_add_u32 v138, s22, 8, v169
	v_ashrrev_i32_e32 v139, 31, v138
	v_lshl_add_u64 v[140:141], v[138:139], 3, s[10:11]
	global_load_dwordx2 v[142:143], v[140:141], off
	global_load_dwordx2 v[208:209], v[140:141], off offset:128
	global_load_dwordx2 v[210:211], v[140:141], off offset:256
	global_load_dwordx2 v[212:213], v[140:141], off offset:384
	global_load_dwordx2 v[214:215], v[140:141], off offset:1024
	global_load_dwordx2 v[216:217], v[140:141], off offset:1152
	global_load_dwordx2 v[218:219], v[140:141], off offset:1280
	global_load_dwordx2 v[220:221], v[140:141], off offset:1408
	v_lshl_or_b32 v144, s51, 8, v171
	v_ashrrev_i32_e32 v145, 31, v144
	s_movk_i32 s15, 0x2200
	v_lshlrev_b64 v[144:145], 1, v[144:145]
	s_mov_b32 s51, s14
	s_mov_b32 s22, s16
	s_mov_b64 s[26:27], s[20:21]
	s_waitcnt vmcnt(0)
	v_cvt_f64_u32_e32 v[174:175], v143
	v_ldexp_f64 v[174:175], v[174:175], 32
	v_cvt_f64_u32_e32 v[142:143], v142
	v_add_f64 v[142:143], v[174:175], v[142:143]
	v_ldexp_f64 v[142:143], v[142:143], s93
	v_cvt_f32_f64_e32 v139, v[142:143]
	v_fmamk_f32 v139, v139, 0x3a000000, v189
	v_cmp_gt_f32_e32 vcc, s78, v139
	v_mul_f32_e32 v142, 0x4b800000, v139
	s_nop 0
	v_cndmask_b32_e32 v139, v139, v142, vcc
	v_rsq_f32_e32 v139, v139
	s_nop 0
	v_mul_f32_e32 v142, 0x45800000, v139
	v_cndmask_b32_e32 v174, v139, v142, vcc
	v_mov_b64_e32 v[142:143], s[12:13]
	v_mad_i64_i32 v[176:177], s[24:25], v138, s15, v[142:143]
	v_lshl_add_u64 v[176:177], v[176:177], 0, v[144:145]
	v_pk_mul_f32 v[126:127], v[126:127], v[174:175] op_sel_hi:[1,0]
	v_pk_mul_f32 v[124:125], v[124:125], v[174:175] op_sel_hi:[1,0]
	v_pk_mul_f32 v[178:179], v[122:123], v[174:175] op_sel_hi:[1,0]
	v_pk_mul_f32 v[122:123], v[120:121], v[174:175] op_sel_hi:[1,0]
	v_cvt_pk_bf16_f32 v120, v124, v125
	v_cvt_pk_bf16_f32 v121, v126, v127
	v_pk_mul_f32 v[116:117], v[116:117], v[174:175] op_sel_hi:[1,0]
	v_cvt_pk_bf16_f32 v122, v122, v123
	v_cvt_pk_bf16_f32 v123, v178, v179
	global_store_dwordx4 v[176:177], v[120:123], off
	v_pk_mul_f32 v[118:119], v[118:119], v[174:175] op_sel_hi:[1,0]
	s_nop 0
	v_pk_mul_f32 v[120:121], v[114:115], v[174:175] op_sel_hi:[1,0]
	v_pk_mul_f32 v[114:115], v[112:113], v[174:175] op_sel_hi:[1,0]
	v_cvt_pk_bf16_f32 v112, v116, v117
	v_cvt_pk_bf16_f32 v113, v118, v119
	s_nop 0
	v_cvt_pk_bf16_f32 v114, v114, v115
	v_cvt_pk_bf16_f32 v115, v120, v121
	global_store_dwordx4 v[176:177], v[112:115], off offset:256
	s_nop 1
	v_or_b32_e32 v112, 16, v138
	v_ashrrev_i32_e32 v113, 31, v112
	v_lshl_add_u64 v[114:115], v[112:113], 3, s[10:11]
	s_nop 1
	v_mov_b64_e32 v[114:115], v[208:209]
	v_cvt_f64_u32_e32 v[116:117], v115
	v_ldexp_f64 v[116:117], v[116:117], 32
	v_cvt_f64_u32_e32 v[114:115], v114
	v_add_f64 v[114:115], v[116:117], v[114:115]
	v_ldexp_f64 v[114:115], v[114:115], s93
	v_cvt_f32_f64_e32 v113, v[114:115]
	v_fmamk_f32 v113, v113, 0x3a000000, v189
; __device__ __forceinline__ unsigned cvt_pk_bf16(float lo, float hi) { unsigned r; asm volatile("v_cvt_pk_bf16_f32 %0, %1, %2" : "=v"(r) : "v"(lo), "v"(hi)); return r; }
; __device__ __forceinline__ float rinv_st(stat_t s, float invn) { return rsqrtf((float)((double)s * (1.0 / 4294967296.0)) * invn + 1e-6f); }
;     __device__ __forceinline__ void operator()(const f32x4 (&acc)[2][2][4][2], const Unit& u, int wr, int wc, int fr, int fq) const {
;     ...
;         for (int ai = 0; ai < 2; ++ai)
; #pragma unroll
;             for (int m = 0; m < 4; ++m) {
;                 const int row = row0 + ai * HALF + m * 16; const float r = rinv_st(stats[row], 1.0f / 2048.0f);
;                 bf16_t* rowp = raw + (size_t)row * NINP + col0;
; #pragma unroll
;                 for (int bj = 0; bj < 2; ++bj) {
;                     const f32x4 v0 = acc[ai][bj][m][0] * r, v1 = acc[ai][bj][m][1] * r;
;                     u32x4 w; w.x = cvt_pk_bf16(v0[0], v0[1]); w.y = cvt_pk_bf16(v0[2], v0[3]); w.z = cvt_pk_bf16(v1[0], v1[1]); w.w = cvt_pk_bf16(v1[2], v1[3]);
;                     *(u32x4*)(rowp + bj * HALF) = w;
;                 }
;             }
	v_cmp_gt_f32_e32 vcc, s78, v113
	v_mul_f32_e32 v114, 0x4b800000, v113
	s_nop 0
	v_cndmask_b32_e32 v113, v113, v114, vcc
	v_rsq_f32_e32 v113, v113
	s_nop 0
	v_mul_f32_e32 v114, 0x45800000, v113
	v_cndmask_b32_e32 v114, v113, v114, vcc
	v_mad_i64_i32 v[112:113], s[24:25], v112, s15, v[142:143]
	v_lshl_add_u64 v[112:113], v[112:113], 0, v[144:145]
	v_pk_mul_f32 v[110:111], v[110:111], v[114:115] op_sel_hi:[1,0]
	v_pk_mul_f32 v[108:109], v[108:109], v[114:115] op_sel_hi:[1,0]
	v_pk_mul_f32 v[116:117], v[106:107], v[114:115] op_sel_hi:[1,0]
	v_pk_mul_f32 v[106:107], v[104:105], v[114:115] op_sel_hi:[1,0]
	v_cvt_pk_bf16_f32 v104, v108, v109
	v_cvt_pk_bf16_f32 v105, v110, v111
	v_pk_mul_f32 v[100:101], v[100:101], v[114:115] op_sel_hi:[1,0]
	v_cvt_pk_bf16_f32 v106, v106, v107
	v_cvt_pk_bf16_f32 v107, v116, v117
	global_store_dwordx4 v[112:113], v[104:107], off
	v_pk_mul_f32 v[102:103], v[102:103], v[114:115] op_sel_hi:[1,0]
	s_nop 0
	v_pk_mul_f32 v[104:105], v[98:99], v[114:115] op_sel_hi:[1,0]
	v_pk_mul_f32 v[98:99], v[96:97], v[114:115] op_sel_hi:[1,0]
	v_cvt_pk_bf16_f32 v96, v100, v101
	v_cvt_pk_bf16_f32 v97, v102, v103
	s_nop 0
	v_cvt_pk_bf16_f32 v98, v98, v99
	v_cvt_pk_bf16_f32 v99, v104, v105
	global_store_dwordx4 v[112:113], v[96:99], off offset:256
	s_nop 1
	v_or_b32_e32 v96, 32, v138
	v_ashrrev_i32_e32 v97, 31, v96
	v_lshl_add_u64 v[98:99], v[96:97], 3, s[10:11]
	s_nop 1
	v_mov_b64_e32 v[98:99], v[210:211]
	v_cvt_f64_u32_e32 v[100:101], v99
	v_ldexp_f64 v[100:101], v[100:101], 32
	v_cvt_f64_u32_e32 v[98:99], v98
	v_add_f64 v[98:99], v[100:101], v[98:99]
	v_ldexp_f64 v[98:99], v[98:99], s93
	v_cvt_f32_f64_e32 v97, v[98:99]
	v_fmamk_f32 v97, v97, 0x3a000000, v189
	v_cmp_gt_f32_e32 vcc, s78, v97
	v_mul_f32_e32 v98, 0x4b800000, v97
	s_nop 0
	v_cndmask_b32_e32 v97, v97, v98, vcc
	v_rsq_f32_e32 v97, v97
	s_nop 0
	v_mul_f32_e32 v98, 0x45800000, v97
	v_cndmask_b32_e32 v98, v97, v98, vcc
	v_mad_i64_i32 v[96:97], s[24:25], v96, s15, v[142:143]
	v_lshl_add_u64 v[96:97], v[96:97], 0, v[144:145]
	v_pk_mul_f32 v[94:95], v[94:95], v[98:99] op_sel_hi:[1,0]
	v_pk_mul_f32 v[92:93], v[92:93], v[98:99] op_sel_hi:[1,0]
	v_pk_mul_f32 v[100:101], v[90:91], v[98:99] op_sel_hi:[1,0]
	v_pk_mul_f32 v[90:91], v[88:89], v[98:99] op_sel_hi:[1,0]
	v_cvt_pk_bf16_f32 v88, v92, v93
	v_cvt_pk_bf16_f32 v89, v94, v95
	v_pk_mul_f32 v[84:85], v[84:85], v[98:99] op_sel_hi:[1,0]
	v_cvt_pk_bf16_f32 v90, v90, v91
	v_cvt_pk_bf16_f32 v91, v100, v101
	global_store_dwordx4 v[96:97], v[88:91], off
	v_pk_mul_f32 v[86:87], v[86:87], v[98:99] op_sel_hi:[1,0]
	s_nop 0
	v_pk_mul_f32 v[88:89], v[82:83], v[98:99] op_sel_hi:[1,0]
	v_pk_mul_f32 v[82:83], v[80:81], v[98:99] op_sel_hi:[1,0]
	v_cvt_pk_bf16_f32 v80, v84, v85
	v_cvt_pk_bf16_f32 v81, v86, v87
	s_nop 0
	v_cvt_pk_bf16_f32 v82, v82, v83
	v_cvt_pk_bf16_f32 v83, v88, v89
	global_store_dwordx4 v[96:97], v[80:83], off offset:256
	s_nop 1
	v_or_b32_e32 v80, 48, v138
	v_ashrrev_i32_e32 v81, 31, v80
	v_lshl_add_u64 v[82:83], v[80:81], 3, s[10:11]
	s_nop 1
	v_mov_b64_e32 v[82:83], v[212:213]
	v_cvt_f64_u32_e32 v[84:85], v83
	v_ldexp_f64 v[84:85], v[84:85], 32
	v_cvt_f64_u32_e32 v[82:83], v82
	v_add_f64 v[82:83], v[84:85], v[82:83]
	v_ldexp_f64 v[82:83], v[82:83], s93
	v_cvt_f32_f64_e32 v81, v[82:83]
	v_fmamk_f32 v81, v81, 0x3a000000, v189
	v_cmp_gt_f32_e32 vcc, s78, v81
	v_mul_f32_e32 v82, 0x4b800000, v81
	s_nop 0
	v_cndmask_b32_e32 v81, v81, v82, vcc
	v_rsq_f32_e32 v81, v81
	s_nop 0
	v_mul_f32_e32 v82, 0x45800000, v81
	v_cndmask_b32_e32 v82, v81, v82, vcc
	v_mad_i64_i32 v[80:81], s[24:25], v80, s15, v[142:143]
	v_lshl_add_u64 v[80:81], v[80:81], 0, v[144:145]
	v_pk_mul_f32 v[78:79], v[78:79], v[82:83] op_sel_hi:[1,0]
	v_pk_mul_f32 v[76:77], v[76:77], v[82:83] op_sel_hi:[1,0]
	v_pk_mul_f32 v[84:85], v[74:75], v[82:83] op_sel_hi:[1,0]
	v_pk_mul_f32 v[74:75], v[72:73], v[82:83] op_sel_hi:[1,0]
	v_cvt_pk_bf16_f32 v72, v76, v77
	v_cvt_pk_bf16_f32 v73, v78, v79
	v_pk_mul_f32 v[70:71], v[70:71], v[82:83] op_sel_hi:[1,0]
	v_cvt_pk_bf16_f32 v74, v74, v75
	v_cvt_pk_bf16_f32 v75, v84, v85
	global_store_dwordx4 v[80:81], v[72:75], off
	v_pk_mul_f32 v[68:69], v[68:69], v[82:83] op_sel_hi:[1,0]
	s_nop 0
	v_pk_mul_f32 v[72:73], v[66:67], v[82:83] op_sel_hi:[1,0]
	v_pk_mul_f32 v[66:67], v[64:65], v[82:83] op_sel_hi:[1,0]
	v_cvt_pk_bf16_f32 v64, v68, v69
	v_cvt_pk_bf16_f32 v65, v70, v71
	v_add_u32_e32 v68, 0x80, v138
	v_cvt_pk_bf16_f32 v66, v66, v67
	v_cvt_pk_bf16_f32 v67, v72, v73
	global_store_dwordx4 v[80:81], v[64:67], off offset:256
	s_nop 1
	v_mov_b64_e32 v[64:65], v[214:215]
	v_cvt_f64_u32_e32 v[66:67], v65
	v_ldexp_f64 v[66:67], v[66:67], 32
	v_cvt_f64_u32_e32 v[64:65], v64
	v_add_f64 v[64:65], v[66:67], v[64:65]
	v_ldexp_f64 v[64:65], v[64:65], s93
	v_cvt_f32_f64_e32 v64, v[64:65]
	v_fmamk_f32 v64, v64, 0x3a000000, v189
	v_cmp_gt_f32_e32 vcc, s78, v64
	v_mul_f32_e32 v65, 0x4b800000, v64
	v_mad_i64_i32 v[66:67], s[24:25], v68, s15, v[142:143]
	v_cndmask_b32_e32 v64, v64, v65, vcc
	v_rsq_f32_e32 v64, v64
	v_lshl_add_u64 v[66:67], v[66:67], 0, v[144:145]
	v_mul_f32_e32 v65, 0x45800000, v64
	v_cndmask_b32_e32 v64, v64, v65, vcc
	v_pk_mul_f32 v[62:63], v[62:63], v[64:65] op_sel_hi:[1,0]
	v_pk_mul_f32 v[60:61], v[60:61], v[64:65] op_sel_hi:[1,0]
	v_pk_mul_f32 v[68:69], v[58:59], v[64:65] op_sel_hi:[1,0]
; __device__ __forceinline__ unsigned cvt_pk_bf16(float lo, float hi) { unsigned r; asm volatile("v_cvt_pk_bf16_f32 %0, %1, %2" : "=v"(r) : "v"(lo), "v"(hi)); return r; }
; __device__ __forceinline__ float rinv_st(stat_t s, float invn) { return rsqrtf((float)((double)s * (1.0 / 4294967296.0)) * invn + 1e-6f); }
; #define PG8_WAIT_V(n) asm volatile("s_waitcnt vmcnt(" #n ")" ::: "memory")
; #define PG8_BAR __builtin_amdgcn_s_barrier()
; template <class Epi>
; __device__ __forceinline__ void gemm_phase(const int TID, const int BID, LAS unsigned char* lds, const Gemm g, const StaticOrder& S, const Epi& E) {
;     ...
;         if (!has_next) break;
; #pragma unroll
;         for (int a = 0; a < 2; ++a)
; #pragma unroll
;             for (int b = 0; b < 2; ++b)
; #pragma unroll
;                 for (int m = 0; m < 4; ++m)
; #pragma unroll
;                     for (int n = 0; n < 2; ++n) acc[a][b][m][n] = (f32x4){0.f, 0.f, 0.f, 0.f};
;         cur = nxt; cA = nA; cB = nB; ++ui;
;     }
;     PG8_WAIT_V(0);
;     if (wr == 0) PG8_BAR;
;     PG8_BAR;
;     __device__ __forceinline__ void operator()(const f32x4 (&acc)[2][2][4][2], const Unit& u, int wr, int wc, int fr, int fq) const {
;     ...
;         for (int ai = 0; ai < 2; ++ai)
; #pragma unroll
;             for (int m = 0; m < 4; ++m) {
;                 const int row = row0 + ai * HALF + m * 16; const float r = rinv_st(stats[row], 1.0f / 2048.0f);
;                 bf16_t* rowp = raw + (size_t)row * NINP + col0;
; #pragma unroll
;                 for (int bj = 0; bj < 2; ++bj) {
;                     const f32x4 v0 = acc[ai][bj][m][0] * r, v1 = acc[ai][bj][m][1] * r;
;                     u32x4 w; w.x = cvt_pk_bf16(v0[0], v0[1]); w.y = cvt_pk_bf16(v0[2], v0[3]); w.z = cvt_pk_bf16(v1[0], v1[1]); w.w = cvt_pk_bf16(v1[2], v1[3]);
;                     *(u32x4*)(rowp + bj * HALF) = w;
;                 }
;             }
	v_pk_mul_f32 v[58:59], v[56:57], v[64:65] op_sel_hi:[1,0]
	v_cvt_pk_bf16_f32 v56, v60, v61
	v_cvt_pk_bf16_f32 v57, v62, v63
	v_pk_mul_f32 v[54:55], v[54:55], v[64:65] op_sel_hi:[1,0]
	v_cvt_pk_bf16_f32 v58, v58, v59
	v_cvt_pk_bf16_f32 v59, v68, v69
	global_store_dwordx4 v[66:67], v[56:59], off
	v_pk_mul_f32 v[52:53], v[52:53], v[64:65] op_sel_hi:[1,0]
	s_nop 0
	v_pk_mul_f32 v[56:57], v[50:51], v[64:65] op_sel_hi:[1,0]
	v_pk_mul_f32 v[50:51], v[48:49], v[64:65] op_sel_hi:[1,0]
	v_cvt_pk_bf16_f32 v48, v52, v53
	v_cvt_pk_bf16_f32 v49, v54, v55
	v_add_u32_e32 v52, 0x90, v138
	v_cvt_pk_bf16_f32 v50, v50, v51
	v_cvt_pk_bf16_f32 v51, v56, v57
	global_store_dwordx4 v[66:67], v[48:51], off offset:256
	s_nop 1
	v_mov_b64_e32 v[48:49], v[216:217]
	v_cvt_f64_u32_e32 v[50:51], v49
	v_ldexp_f64 v[50:51], v[50:51], 32
	v_cvt_f64_u32_e32 v[48:49], v48
	v_add_f64 v[48:49], v[50:51], v[48:49]
	v_ldexp_f64 v[48:49], v[48:49], s93
	v_cvt_f32_f64_e32 v48, v[48:49]
	v_fmamk_f32 v48, v48, 0x3a000000, v189
	v_cmp_gt_f32_e32 vcc, s78, v48
	v_mul_f32_e32 v49, 0x4b800000, v48
	v_mad_i64_i32 v[50:51], s[24:25], v52, s15, v[142:143]
	v_cndmask_b32_e32 v48, v48, v49, vcc
	v_rsq_f32_e32 v48, v48
	v_lshl_add_u64 v[50:51], v[50:51], 0, v[144:145]
	v_mul_f32_e32 v49, 0x45800000, v48
	v_cndmask_b32_e32 v48, v48, v49, vcc
	v_pk_mul_f32 v[46:47], v[46:47], v[48:49] op_sel_hi:[1,0]
	v_pk_mul_f32 v[44:45], v[44:45], v[48:49] op_sel_hi:[1,0]
	v_pk_mul_f32 v[52:53], v[42:43], v[48:49] op_sel_hi:[1,0]
	v_pk_mul_f32 v[42:43], v[40:41], v[48:49] op_sel_hi:[1,0]
	v_cvt_pk_bf16_f32 v40, v44, v45
	v_cvt_pk_bf16_f32 v41, v46, v47
	v_pk_mul_f32 v[38:39], v[38:39], v[48:49] op_sel_hi:[1,0]
	v_cvt_pk_bf16_f32 v42, v42, v43
	v_cvt_pk_bf16_f32 v43, v52, v53
	global_store_dwordx4 v[50:51], v[40:43], off
	v_pk_mul_f32 v[36:37], v[36:37], v[48:49] op_sel_hi:[1,0]
	s_nop 0
	v_pk_mul_f32 v[40:41], v[34:35], v[48:49] op_sel_hi:[1,0]
	v_pk_mul_f32 v[34:35], v[32:33], v[48:49] op_sel_hi:[1,0]
	v_cvt_pk_bf16_f32 v32, v36, v37
	v_cvt_pk_bf16_f32 v33, v38, v39
	v_add_u32_e32 v36, 0xa0, v138
	v_cvt_pk_bf16_f32 v34, v34, v35
	v_cvt_pk_bf16_f32 v35, v40, v41
	global_store_dwordx4 v[50:51], v[32:35], off offset:256
	s_nop 1
	v_mov_b64_e32 v[32:33], v[218:219]
	v_cvt_f64_u32_e32 v[34:35], v33
	v_ldexp_f64 v[34:35], v[34:35], 32
	v_cvt_f64_u32_e32 v[32:33], v32
	v_add_f64 v[32:33], v[34:35], v[32:33]
	v_ldexp_f64 v[32:33], v[32:33], s93
	v_cvt_f32_f64_e32 v32, v[32:33]
	v_fmamk_f32 v32, v32, 0x3a000000, v189
	v_cmp_gt_f32_e32 vcc, s78, v32
	v_mul_f32_e32 v33, 0x4b800000, v32
	v_mad_i64_i32 v[34:35], s[24:25], v36, s15, v[142:143]
	v_cndmask_b32_e32 v32, v32, v33, vcc
	v_rsq_f32_e32 v32, v32
	v_lshl_add_u64 v[34:35], v[34:35], 0, v[144:145]
	v_mul_f32_e32 v33, 0x45800000, v32
	v_cndmask_b32_e32 v32, v32, v33, vcc
	v_pk_mul_f32 v[30:31], v[30:31], v[32:33] op_sel_hi:[1,0]
	v_pk_mul_f32 v[28:29], v[28:29], v[32:33] op_sel_hi:[1,0]
	v_pk_mul_f32 v[36:37], v[26:27], v[32:33] op_sel_hi:[1,0]
	v_pk_mul_f32 v[26:27], v[24:25], v[32:33] op_sel_hi:[1,0]
	v_cvt_pk_bf16_f32 v24, v28, v29
	v_cvt_pk_bf16_f32 v25, v30, v31
	v_pk_mul_f32 v[22:23], v[22:23], v[32:33] op_sel_hi:[1,0]
	v_cvt_pk_bf16_f32 v26, v26, v27
	v_cvt_pk_bf16_f32 v27, v36, v37
	global_store_dwordx4 v[34:35], v[24:27], off
	v_pk_mul_f32 v[20:21], v[20:21], v[32:33] op_sel_hi:[1,0]
	s_nop 0
	v_pk_mul_f32 v[24:25], v[18:19], v[32:33] op_sel_hi:[1,0]
	v_pk_mul_f32 v[18:19], v[16:17], v[32:33] op_sel_hi:[1,0]
	v_cvt_pk_bf16_f32 v16, v20, v21
	v_cvt_pk_bf16_f32 v17, v22, v23
	v_add_u32_e32 v20, 0xb0, v138
	v_cvt_pk_bf16_f32 v18, v18, v19
	v_cvt_pk_bf16_f32 v19, v24, v25
	global_store_dwordx4 v[34:35], v[16:19], off offset:256
	s_nop 1
	v_mov_b64_e32 v[16:17], v[220:221]
	v_cvt_f64_u32_e32 v[18:19], v17
	v_ldexp_f64 v[18:19], v[18:19], 32
	v_cvt_f64_u32_e32 v[16:17], v16
	v_add_f64 v[16:17], v[18:19], v[16:17]
	v_ldexp_f64 v[16:17], v[16:17], s93
	v_cvt_f32_f64_e32 v16, v[16:17]
	v_fmamk_f32 v16, v16, 0x3a000000, v189
	v_cmp_gt_f32_e32 vcc, s78, v16
	v_mul_f32_e32 v17, 0x4b800000, v16
	v_mad_i64_i32 v[18:19], s[24:25], v20, s15, v[142:143]
	v_cndmask_b32_e32 v16, v16, v17, vcc
	v_rsq_f32_e32 v16, v16
	v_lshl_add_u64 v[18:19], v[18:19], 0, v[144:145]
	s_mov_b64 s[24:25], s[18:19]
	v_mul_f32_e32 v17, 0x45800000, v16
	v_cndmask_b32_e32 v16, v16, v17, vcc
	v_pk_mul_f32 v[14:15], v[14:15], v[16:17] op_sel_hi:[1,0]
	v_pk_mul_f32 v[12:13], v[12:13], v[16:17] op_sel_hi:[1,0]
	v_pk_mul_f32 v[20:21], v[10:11], v[16:17] op_sel_hi:[1,0]
	v_pk_mul_f32 v[10:11], v[8:9], v[16:17] op_sel_hi:[1,0]
	v_cvt_pk_bf16_f32 v8, v12, v13
	v_cvt_pk_bf16_f32 v9, v14, v15
	s_and_b64 vcc, exec, s[8:9]
	v_cvt_pk_bf16_f32 v10, v10, v11
	v_cvt_pk_bf16_f32 v11, v20, v21
	global_store_dwordx4 v[18:19], v[8:11], off
	v_pk_mul_f32 v[6:7], v[6:7], v[16:17] op_sel_hi:[1,0]
	v_pk_mul_f32 v[4:5], v[4:5], v[16:17] op_sel_hi:[1,0]
	v_pk_mul_f32 v[8:9], v[2:3], v[16:17] op_sel_hi:[1,0]
	v_pk_mul_f32 v[2:3], v[0:1], v[16:17] op_sel_hi:[1,0]
	v_cvt_pk_bf16_f32 v0, v4, v5
	v_cvt_pk_bf16_f32 v1, v6, v7
	s_nop 0
	v_cvt_pk_bf16_f32 v2, v2, v3
	v_cvt_pk_bf16_f32 v3, v8, v9
	global_store_dwordx4 v[18:19], v[0:3], off offset:256
	s_cbranch_vccz .LBB0_792
	s_waitcnt vmcnt(0)
	s_cmpk_gt_u32 s0, 0xff
	s_cbranch_scc1 .LBB0_803
	s_barrier

; #define PG8_STAGE(bufoff, gbase, voff) do { _Pragma("unroll") for (int _i = 0; _i < 2; ++_i) \
;         __builtin_amdgcn_global_load_lds((const unsigned*)((const char*)(gbase) + (voff)[_i]), (LAS unsigned*)(lds + (bufoff) + ldsw + _i * 8192), 16, 0, 0); } while (0)
; #define PG8_LDA(dst, b, h) do { _Pragma("unroll") for (int m = 0; m < 4; ++m) _Pragma("unroll") for (int k = 0; k < 2; ++k) dst[m][k] = *(const LAS bf16x8*)(lds + PG8_SA(b, h) + aoff + m * 2048 + k * 1024); } while (0)
; #define PG8_LDB(dst, b, h) do { _Pragma("unroll") for (int n = 0; n < 2; ++n) _Pragma("unroll") for (int k = 0; k < 2; ++k) dst[n][k] = *(const LAS bf16x8*)(lds + PG8_SB(b, h) + boff + n * 2048 + k * 1024); } while (0)
; #define PG8_MMA(ai, bj, At, Bt) do { __builtin_amdgcn_s_setprio(1); _Pragma("unroll") for (int m = 0; m < 4; ++m) _Pragma("unroll") for (int n = 0; n < 2; ++n) _Pragma("unroll") for (int k = 0; k < 2; ++k) \
;         acc[ai][bj][m][n] = __builtin_amdgcn_mfma_f32_16x16x32_bf16(Bt[n][k], At[m][k], acc[ai][bj][m][n], 0, 0, 0); __builtin_amdgcn_s_setprio(0); } while (0)
; #define PG8_WAIT_V(n) asm volatile("s_waitcnt vmcnt(" #n ")" ::: "memory")
; #define PG8_WAIT_L(n) asm volatile("s_waitcnt lgkmcnt(" #n ")" ::: "memory")
; template <class Epi>
; __device__ __forceinline__ void gemm_phase(const int TID, const int BID, LAS unsigned char* lds, const Gemm g, const StaticOrder& S, const Epi& E) {
;     ...
;         for (int t = 0; t < nt; t += 2) {
;             const bool last = (t == nt - 2);
;             const char* a1 = cA + (size_t)(t + 1) * kstep;
;             const char* a2 = last ? nA : cA + (size_t)(t + 2) * kstep; const char* b2 = last ? nB : cB + (size_t)(t + 2) * kstep;
;             const char* a3 = a2 + kstep; const char* b3 = b2 + kstep;
;             PG8_LDB(B0, 0, 0); PG8_SCHED; PG8_LDA(At, 0, 0); PG8_STAGE(PG8_SA(1, 1), a1 + hstepA, voffA);
;             PG8_WAIT_L(8); PG8_BAR; PG8_WAIT_L(0); PG8_MMA(0, 0, At, B0); PG8_BAR; PG8_SCHED;
;             PG8_LDB(B1, 0, 1); PG8_STAGE(PG8_SB(0, 0), b2, voffB);
;             PG8_BAR; PG8_WAIT_L(0); PG8_MMA(0, 1, At, B1); PG8_BAR;
;             PG8_LDA(At, 0, 1); PG8_STAGE(PG8_SA(0, 0), a2, voffA);
;             PG8_BAR; PG8_WAIT_L(0); PG8_MMA(1, 0, At, B0); PG8_BAR; PG8_SCHED;
;             PG8_STAGE(PG8_SB(0, 1), b2 + hstepB, voffB);
;             PG8_WAIT_V(6); PG8_BAR; PG8_MMA(1, 1, At, B1); PG8_BAR;
.LBB0_822:
	v_add_u32_e32 v154, s36, v147
	ds_read_b128 v[134:137], v154
	ds_read_b128 v[138:141], v154 offset:1024
	ds_read_b128 v[150:153], v154 offset:2048
	ds_read_b128 v[154:157], v154 offset:3072
	s_add_u32 s28, s26, 0xfff80080
	s_addc_u32 s29, s27, -1
	s_cmp_eq_u32 s66, 4
	s_cselect_b32 s31, s17, s29
	s_cselect_b32 s30, s61, s28
	s_cselect_b32 s29, s15, s64
	s_cselect_b32 s28, s62, s63
	v_lshl_add_u64 v[158:159], s[26:27], 0, v[130:131]
	s_add_i32 m0, s47, 0xc000
	ds_read_b128 v[166:169], v149
	ds_read_b128 v[170:173], v149 offset:1024
	ds_read_b128 v[174:177], v149 offset:2048
	ds_read_b128 v[178:181], v149 offset:3072
	ds_read_b128 v[182:185], v149 offset:4096
	ds_read_b128 v[196:199], v149 offset:5120
	ds_read_b128 v[208:211], v149 offset:6144
	ds_read_b128 v[212:215], v149 offset:7168
	global_load_lds_dwordx4 v[158:159], off
	v_lshl_add_u64 v[158:159], s[26:27], 0, v[132:133]
	s_add_i32 m0, s47, 0xe000
	s_nop 0
	global_load_lds_dwordx4 v[158:159], off
	s_waitcnt lgkmcnt(8)
	s_barrier
	s_waitcnt lgkmcnt(0)
	s_setprio 1
	v_mfma_f32_16x16x32_bf16 v[124:127], v[134:137], v[166:169], v[124:127]
	v_mfma_f32_16x16x32_bf16 v[120:123], v[150:153], v[166:169], v[120:123]
	v_mfma_f32_16x16x32_bf16 v[108:111], v[134:137], v[174:177], v[108:111]
	v_mfma_f32_16x16x32_bf16 v[104:107], v[150:153], v[174:177], v[104:107]
	v_mfma_f32_16x16x32_bf16 v[92:95], v[134:137], v[182:185], v[92:95]
	v_mfma_f32_16x16x32_bf16 v[88:91], v[150:153], v[182:185], v[88:91]
	v_mfma_f32_16x16x32_bf16 v[76:79], v[134:137], v[208:211], v[76:79]
	v_mfma_f32_16x16x32_bf16 v[72:75], v[150:153], v[208:211], v[72:75]
	v_mfma_f32_16x16x32_bf16 v[124:127], v[138:141], v[170:173], v[124:127]
	v_mfma_f32_16x16x32_bf16 v[120:123], v[154:157], v[170:173], v[120:123]
	v_mfma_f32_16x16x32_bf16 v[108:111], v[138:141], v[178:181], v[108:111]
	v_mfma_f32_16x16x32_bf16 v[104:107], v[154:157], v[178:181], v[104:107]
	v_mfma_f32_16x16x32_bf16 v[92:95], v[138:141], v[196:199], v[92:95]
	v_mfma_f32_16x16x32_bf16 v[88:91], v[154:157], v[196:199], v[88:91]
	v_mfma_f32_16x16x32_bf16 v[76:79], v[138:141], v[212:215], v[76:79]
	v_mfma_f32_16x16x32_bf16 v[72:75], v[154:157], v[212:215], v[72:75]
	s_setprio 0
	s_barrier
	v_add_u32_e32 v158, s37, v147
	s_mov_b32 m0, s25
	ds_read_b128 v[216:219], v158
	ds_read_b128 v[220:223], v158 offset:1024
	ds_read_b128 v[224:227], v158 offset:2048
	ds_read_b128 v[228:231], v158 offset:3072
	v_lshl_add_u64 v[158:159], s[28:29], 0, v[160:161]
	global_load_lds_dwordx4 v[158:159], off
	v_lshl_add_u64 v[200:201], s[28:29], 0, v[128:129]
	s_mov_b32 m0, s46
	s_nop 0
	global_load_lds_dwordx4 v[200:201], off
	s_barrier
	s_waitcnt lgkmcnt(0)
	s_setprio 1
	v_mfma_f32_16x16x32_bf16 v[116:119], v[216:219], v[166:169], v[116:119]
	v_mfma_f32_16x16x32_bf16 v[112:115], v[224:227], v[166:169], v[112:115]
	v_mfma_f32_16x16x32_bf16 v[100:103], v[216:219], v[174:177], v[100:103]
	v_mfma_f32_16x16x32_bf16 v[96:99], v[224:227], v[174:177], v[96:99]
	v_mfma_f32_16x16x32_bf16 v[84:87], v[216:219], v[182:185], v[84:87]
	v_mfma_f32_16x16x32_bf16 v[80:83], v[224:227], v[182:185], v[80:83]
	v_mfma_f32_16x16x32_bf16 v[68:71], v[216:219], v[208:211], v[68:71]
	v_mfma_f32_16x16x32_bf16 v[64:67], v[224:227], v[208:211], v[64:67]
	v_mfma_f32_16x16x32_bf16 v[116:119], v[220:223], v[170:173], v[116:119]
	v_mfma_f32_16x16x32_bf16 v[112:115], v[228:231], v[170:173], v[112:115]
	v_mfma_f32_16x16x32_bf16 v[100:103], v[220:223], v[178:181], v[100:103]
	v_mfma_f32_16x16x32_bf16 v[96:99], v[228:231], v[178:181], v[96:99]
	v_mfma_f32_16x16x32_bf16 v[84:87], v[220:223], v[196:199], v[84:87]
	v_mfma_f32_16x16x32_bf16 v[80:83], v[228:231], v[196:199], v[80:83]
	v_mfma_f32_16x16x32_bf16 v[68:71], v[220:223], v[212:215], v[68:71]
	v_mfma_f32_16x16x32_bf16 v[64:67], v[228:231], v[212:215], v[64:67]
	s_setprio 0
	s_mov_b32 m0, s47
	v_lshl_add_u64 v[232:233], s[30:31], 0, v[160:161]
	s_barrier
	ds_read_b128 v[166:169], v149 offset:16384
	ds_read_b128 v[170:173], v149 offset:17408
	ds_read_b128 v[174:177], v149 offset:18432
	ds_read_b128 v[178:181], v149 offset:19456
	ds_read_b128 v[182:185], v149 offset:20480
	ds_read_b128 v[196:199], v149 offset:21504
	ds_read_b128 v[208:211], v149 offset:22528
	ds_read_b128 v[212:215], v149 offset:23552
	global_load_lds_dwordx4 v[232:233], off
	v_lshl_add_u64 v[234:235], s[30:31], 0, v[128:129]
	s_mov_b32 m0, s48
	s_nop 0
	global_load_lds_dwordx4 v[234:235], off
	s_barrier
	s_waitcnt lgkmcnt(0)
	s_setprio 1
	v_mfma_f32_16x16x32_bf16 v[60:63], v[134:137], v[166:169], v[60:63]
	v_mfma_f32_16x16x32_bf16 v[56:59], v[150:153], v[166:169], v[56:59]
	v_mfma_f32_16x16x32_bf16 v[44:47], v[134:137], v[174:177], v[44:47]
	v_mfma_f32_16x16x32_bf16 v[40:43], v[150:153], v[174:177], v[40:43]
	v_mfma_f32_16x16x32_bf16 v[28:31], v[134:137], v[182:185], v[28:31]
	v_mfma_f32_16x16x32_bf16 v[24:27], v[150:153], v[182:185], v[24:27]
	v_mfma_f32_16x16x32_bf16 v[12:15], v[134:137], v[208:211], v[12:15]
	v_mfma_f32_16x16x32_bf16 v[8:11], v[150:153], v[208:211], v[8:11]
	v_mfma_f32_16x16x32_bf16 v[60:63], v[138:141], v[170:173], v[60:63]
	v_mfma_f32_16x16x32_bf16 v[56:59], v[154:157], v[170:173], v[56:59]
	v_mfma_f32_16x16x32_bf16 v[44:47], v[138:141], v[178:181], v[44:47]
	v_mfma_f32_16x16x32_bf16 v[40:43], v[154:157], v[178:181], v[40:43]
	v_mfma_f32_16x16x32_bf16 v[28:31], v[138:141], v[196:199], v[28:31]
	v_mfma_f32_16x16x32_bf16 v[24:27], v[154:157], v[196:199], v[24:27]
	v_mfma_f32_16x16x32_bf16 v[12:15], v[138:141], v[212:215], v[12:15]
	v_mfma_f32_16x16x32_bf16 v[8:11], v[154:157], v[212:215], v[8:11]
	s_setprio 0
	s_barrier
; #define PG8_STAGE(bufoff, gbase, voff) do { _Pragma("unroll") for (int _i = 0; _i < 2; ++_i) \
;         __builtin_amdgcn_global_load_lds((const unsigned*)((const char*)(gbase) + (voff)[_i]), (LAS unsigned*)(lds + (bufoff) + ldsw + _i * 8192), 16, 0, 0); } while (0)
; #define PG8_LDA(dst, b, h) do { _Pragma("unroll") for (int m = 0; m < 4; ++m) _Pragma("unroll") for (int k = 0; k < 2; ++k) dst[m][k] = *(const LAS bf16x8*)(lds + PG8_SA(b, h) + aoff + m * 2048 + k * 1024); } while (0)
; #define PG8_LDB(dst, b, h) do { _Pragma("unroll") for (int n = 0; n < 2; ++n) _Pragma("unroll") for (int k = 0; k < 2; ++k) dst[n][k] = *(const LAS bf16x8*)(lds + PG8_SB(b, h) + boff + n * 2048 + k * 1024); } while (0)
; #define PG8_MMA(ai, bj, At, Bt) do { __builtin_amdgcn_s_setprio(1); _Pragma("unroll") for (int m = 0; m < 4; ++m) _Pragma("unroll") for (int n = 0; n < 2; ++n) _Pragma("unroll") for (int k = 0; k < 2; ++k) \
;         acc[ai][bj][m][n] = __builtin_amdgcn_mfma_f32_16x16x32_bf16(Bt[n][k], At[m][k], acc[ai][bj][m][n], 0, 0, 0); __builtin_amdgcn_s_setprio(0); } while (0)
; #define PG8_WAIT_V(n) asm volatile("s_waitcnt vmcnt(" #n ")" ::: "memory")
; #define PG8_WAIT_L(n) asm volatile("s_waitcnt lgkmcnt(" #n ")" ::: "memory")
; #define PG8_BAR __builtin_amdgcn_s_barrier()
; #define PG8_SCHED __builtin_amdgcn_sched_barrier(0)
; template <class Epi>
; __device__ __forceinline__ void gemm_phase(const int TID, const int BID, LAS unsigned char* lds, const Gemm g, const StaticOrder& S, const Epi& E) {
;     ...
;             PG8_STAGE(PG8_SB(0, 1), b2 + hstepB, voffB);
;             PG8_WAIT_V(6); PG8_BAR; PG8_MMA(1, 1, At, B1); PG8_BAR;
;             PG8_LDB(B0, 1, 0); PG8_SCHED; PG8_LDA(At, 1, 0); PG8_STAGE(PG8_SA(0, 1), a2 + hstepA, voffA);
;             PG8_WAIT_L(8); PG8_BAR; PG8_WAIT_L(0); PG8_MMA(0, 0, At, B0); PG8_BAR; PG8_SCHED;
;             PG8_LDB(B1, 1, 1); PG8_STAGE(PG8_SB(1, 0), b3, voffB);
;             PG8_BAR; PG8_WAIT_L(0); PG8_MMA(0, 1, At, B1); PG8_BAR;
;             PG8_LDA(At, 1, 1); PG8_STAGE(PG8_SA(1, 0), a3, voffA);
;             PG8_BAR; PG8_WAIT_L(0); PG8_MMA(1, 0, At, B0); PG8_BAR; PG8_SCHED;
	s_add_u32 s74, s28, 0x80000
	s_addc_u32 s75, s29, 0
	s_mov_b32 m0, s49
	v_lshl_add_u64 v[134:135], s[74:75], 0, v[160:161]
	global_load_lds_dwordx4 v[134:135], off
	v_lshl_add_u64 v[134:135], s[74:75], 0, v[128:129]
	s_mov_b32 m0, s50
	s_nop 0
	global_load_lds_dwordx4 v[134:135], off
	s_waitcnt vmcnt(6)
	s_barrier
	s_setprio 1
	v_mfma_f32_16x16x32_bf16 v[52:55], v[216:219], v[166:169], v[52:55]
	v_mfma_f32_16x16x32_bf16 v[48:51], v[224:227], v[166:169], v[48:51]
	v_mfma_f32_16x16x32_bf16 v[36:39], v[216:219], v[174:177], v[36:39]
	v_mfma_f32_16x16x32_bf16 v[32:35], v[224:227], v[174:177], v[32:35]
	v_mfma_f32_16x16x32_bf16 v[20:23], v[216:219], v[182:185], v[20:23]
	v_mfma_f32_16x16x32_bf16 v[16:19], v[224:227], v[182:185], v[16:19]
	v_mfma_f32_16x16x32_bf16 v[4:7], v[216:219], v[208:211], v[4:7]
	v_mfma_f32_16x16x32_bf16 v[0:3], v[224:227], v[208:211], v[0:3]
	v_mfma_f32_16x16x32_bf16 v[52:55], v[220:223], v[170:173], v[52:55]
	v_mfma_f32_16x16x32_bf16 v[48:51], v[228:231], v[170:173], v[48:51]
	v_mfma_f32_16x16x32_bf16 v[36:39], v[220:223], v[178:181], v[36:39]
	v_mfma_f32_16x16x32_bf16 v[32:35], v[228:231], v[178:181], v[32:35]
	v_mfma_f32_16x16x32_bf16 v[20:23], v[220:223], v[196:199], v[20:23]
	v_mfma_f32_16x16x32_bf16 v[16:19], v[228:231], v[196:199], v[16:19]
	v_mfma_f32_16x16x32_bf16 v[4:7], v[220:223], v[212:215], v[4:7]
	v_mfma_f32_16x16x32_bf16 v[0:3], v[228:231], v[212:215], v[0:3]
	s_setprio 0
	v_add_u32_e32 v154, s38, v147
	s_barrier
	ds_read_b128 v[134:137], v154
	ds_read_b128 v[138:141], v154 offset:1024
	ds_read_b128 v[150:153], v154 offset:2048
	ds_read_b128 v[154:157], v154 offset:3072
	s_add_u32 s30, s30, 0x80000
	s_addc_u32 s31, s31, 0
	s_mov_b32 m0, s51
	v_lshl_add_u64 v[216:217], s[30:31], 0, v[160:161]
	ds_read_b128 v[166:169], v149 offset:32768
	ds_read_b128 v[170:173], v149 offset:33792
	ds_read_b128 v[174:177], v149 offset:34816
	ds_read_b128 v[178:181], v149 offset:35840
	ds_read_b128 v[182:185], v149 offset:36864
	ds_read_b128 v[196:199], v149 offset:37888
	ds_read_b128 v[208:211], v149 offset:38912
	ds_read_b128 v[212:215], v149 offset:39936
	global_load_lds_dwordx4 v[216:217], off
	v_lshl_add_u64 v[216:217], s[30:31], 0, v[128:129]
	s_mov_b32 m0, s52
	s_nop 0
	global_load_lds_dwordx4 v[216:217], off
	s_waitcnt lgkmcnt(8)
	s_barrier
	s_waitcnt lgkmcnt(0)
	s_setprio 1
	v_mfma_f32_16x16x32_bf16 v[124:127], v[134:137], v[166:169], v[124:127]
	v_mfma_f32_16x16x32_bf16 v[120:123], v[150:153], v[166:169], v[120:123]
	v_mfma_f32_16x16x32_bf16 v[108:111], v[134:137], v[174:177], v[108:111]
	v_mfma_f32_16x16x32_bf16 v[104:107], v[150:153], v[174:177], v[104:107]
	v_mfma_f32_16x16x32_bf16 v[92:95], v[134:137], v[182:185], v[92:95]
	v_mfma_f32_16x16x32_bf16 v[88:91], v[150:153], v[182:185], v[88:91]
	v_mfma_f32_16x16x32_bf16 v[76:79], v[134:137], v[208:211], v[76:79]
	v_mfma_f32_16x16x32_bf16 v[72:75], v[150:153], v[208:211], v[72:75]
	v_mfma_f32_16x16x32_bf16 v[124:127], v[138:141], v[170:173], v[124:127]
	v_mfma_f32_16x16x32_bf16 v[120:123], v[154:157], v[170:173], v[120:123]
	v_mfma_f32_16x16x32_bf16 v[108:111], v[138:141], v[178:181], v[108:111]
	v_mfma_f32_16x16x32_bf16 v[104:107], v[154:157], v[178:181], v[104:107]
	v_mfma_f32_16x16x32_bf16 v[92:95], v[138:141], v[196:199], v[92:95]
	v_mfma_f32_16x16x32_bf16 v[88:91], v[154:157], v[196:199], v[88:91]
	v_mfma_f32_16x16x32_bf16 v[76:79], v[138:141], v[212:215], v[76:79]
	v_mfma_f32_16x16x32_bf16 v[72:75], v[154:157], v[212:215], v[72:75]
	s_setprio 0
	s_barrier
	s_mov_b32 m0, s53
	v_add_u32_e32 v228, s39, v147
	v_lshl_add_u64 v[158:159], v[158:159], 0, s[90:91]
	ds_read_b128 v[216:219], v228
	ds_read_b128 v[220:223], v228 offset:1024
	ds_read_b128 v[224:227], v228 offset:2048
	ds_read_b128 v[228:231], v228 offset:3072
	global_load_lds_dwordx4 v[158:159], off
	v_lshl_add_u64 v[158:159], v[200:201], 0, s[90:91]
	s_mov_b32 m0, s54
	s_nop 0
	global_load_lds_dwordx4 v[158:159], off
	s_barrier
	s_waitcnt lgkmcnt(0)
	s_setprio 1
	v_mfma_f32_16x16x32_bf16 v[116:119], v[216:219], v[166:169], v[116:119]
	v_mfma_f32_16x16x32_bf16 v[112:115], v[224:227], v[166:169], v[112:115]
	v_mfma_f32_16x16x32_bf16 v[100:103], v[216:219], v[174:177], v[100:103]
	v_mfma_f32_16x16x32_bf16 v[96:99], v[224:227], v[174:177], v[96:99]
	v_mfma_f32_16x16x32_bf16 v[84:87], v[216:219], v[182:185], v[84:87]
	v_mfma_f32_16x16x32_bf16 v[80:83], v[224:227], v[182:185], v[80:83]
	v_mfma_f32_16x16x32_bf16 v[68:71], v[216:219], v[208:211], v[68:71]
	v_mfma_f32_16x16x32_bf16 v[64:67], v[224:227], v[208:211], v[64:67]
	v_mfma_f32_16x16x32_bf16 v[116:119], v[220:223], v[170:173], v[116:119]
	v_mfma_f32_16x16x32_bf16 v[112:115], v[228:231], v[170:173], v[112:115]
	v_mfma_f32_16x16x32_bf16 v[100:103], v[220:223], v[178:181], v[100:103]
	v_mfma_f32_16x16x32_bf16 v[96:99], v[228:231], v[178:181], v[96:99]
	v_mfma_f32_16x16x32_bf16 v[84:87], v[220:223], v[196:199], v[84:87]
	v_mfma_f32_16x16x32_bf16 v[80:83], v[228:231], v[196:199], v[80:83]
	v_mfma_f32_16x16x32_bf16 v[68:71], v[220:223], v[212:215], v[68:71]
	v_mfma_f32_16x16x32_bf16 v[64:67], v[228:231], v[212:215], v[64:67]
	s_setprio 0
	s_mov_b32 m0, s55
	v_lshl_add_u64 v[158:159], v[232:233], 0, s[90:91]
	s_barrier
	ds_read_b128 v[166:169], v149 offset:49152
	ds_read_b128 v[170:173], v149 offset:50176
	ds_read_b128 v[174:177], v149 offset:51200
	ds_read_b128 v[178:181], v149 offset:52224
	ds_read_b128 v[182:185], v149 offset:53248
	ds_read_b128 v[196:199], v149 offset:54272
	ds_read_b128 v[208:211], v149 offset:55296
	ds_read_b128 v[212:215], v149 offset:56320
	global_load_lds_dwordx4 v[158:159], off
	v_lshl_add_u64 v[158:159], v[234:235], 0, s[90:91]
	s_mov_b32 m0, s56
	s_nop 0
	global_load_lds_dwordx4 v[158:159], off
	s_barrier
; __device__ __forceinline__ float rinv_st(stat_t s, float invn) { return rsqrtf((float)((double)s * (1.0 / 4294967296.0)) * invn + 1e-6f); }
; #define PG8_STAGE(bufoff, gbase, voff) do { _Pragma("unroll") for (int _i = 0; _i < 2; ++_i) \
;         __builtin_amdgcn_global_load_lds((const unsigned*)((const char*)(gbase) + (voff)[_i]), (LAS unsigned*)(lds + (bufoff) + ldsw + _i * 8192), 16, 0, 0); } while (0)
; #define PG8_MMA(ai, bj, At, Bt) do { __builtin_amdgcn_s_setprio(1); _Pragma("unroll") for (int m = 0; m < 4; ++m) _Pragma("unroll") for (int n = 0; n < 2; ++n) _Pragma("unroll") for (int k = 0; k < 2; ++k) \
;         acc[ai][bj][m][n] = __builtin_amdgcn_mfma_f32_16x16x32_bf16(Bt[n][k], At[m][k], acc[ai][bj][m][n], 0, 0, 0); __builtin_amdgcn_s_setprio(0); } while (0)
; #define PG8_WAIT_V(n) asm volatile("s_waitcnt vmcnt(" #n ")" ::: "memory")
; #define PG8_WAIT_L(n) asm volatile("s_waitcnt lgkmcnt(" #n ")" ::: "memory")
; #define PG8_BAR __builtin_amdgcn_s_barrier()
; #define PG8_SCHED __builtin_amdgcn_sched_barrier(0)
; template <class Epi>
; __device__ __forceinline__ void gemm_phase(const int TID, const int BID, LAS unsigned char* lds, const Gemm g, const StaticOrder& S, const Epi& E) {
;     ...
;             PG8_BAR; PG8_WAIT_L(0); PG8_MMA(1, 0, At, B0); PG8_BAR; PG8_SCHED;
;             PG8_STAGE(PG8_SB(1, 1), b3 + hstepB, voffB);
;             PG8_WAIT_V(6); PG8_BAR; PG8_MMA(1, 1, At, B1); PG8_BAR;
;         }
;         E(acc, cur, wr, wc, fr, fq);
;     __device__ __forceinline__ void operator()(const f32x4 (&acc)[2][2][4][2], const Unit& u, int wr, int wc, int fr, int fq) const {
;         const int row0 = u.pm * BM + wr * 64 + fr, col0 = u.pn * BM + wc * 32 + 4 * fq;
; #pragma unroll
;         for (int ai = 0; ai < 2; ++ai)
; #pragma unroll
;             for (int m = 0; m < 4; ++m) {
;                 const int row = row0 + ai * HALF + m * 16; const float r = rinv_st(stats[row], 1.0f / 2048.0f);
;                 float* rowp = raw + (size_t)row * 256 + col0;
; #pragma unroll
;                 for (int bj = 0; bj < 2; ++bj)
; #pragma unroll
;                     for (int n = 0; n < 2; ++n) *(f32x4*)(rowp + bj * HALF + n * 16) = acc[ai][bj][m][n] * r;
	s_waitcnt lgkmcnt(0)
	s_setprio 1
	v_mfma_f32_16x16x32_bf16 v[60:63], v[134:137], v[166:169], v[60:63]
	v_mfma_f32_16x16x32_bf16 v[56:59], v[150:153], v[166:169], v[56:59]
	v_mfma_f32_16x16x32_bf16 v[44:47], v[134:137], v[174:177], v[44:47]
	v_mfma_f32_16x16x32_bf16 v[40:43], v[150:153], v[174:177], v[40:43]
	v_mfma_f32_16x16x32_bf16 v[28:31], v[134:137], v[182:185], v[28:31]
	v_mfma_f32_16x16x32_bf16 v[24:27], v[150:153], v[182:185], v[24:27]
	v_mfma_f32_16x16x32_bf16 v[12:15], v[134:137], v[208:211], v[12:15]
	v_mfma_f32_16x16x32_bf16 v[8:11], v[150:153], v[208:211], v[8:11]
	v_mfma_f32_16x16x32_bf16 v[60:63], v[138:141], v[170:173], v[60:63]
	v_mfma_f32_16x16x32_bf16 v[56:59], v[154:157], v[170:173], v[56:59]
	v_mfma_f32_16x16x32_bf16 v[44:47], v[138:141], v[178:181], v[44:47]
	v_mfma_f32_16x16x32_bf16 v[40:43], v[154:157], v[178:181], v[40:43]
	v_mfma_f32_16x16x32_bf16 v[28:31], v[138:141], v[196:199], v[28:31]
	v_mfma_f32_16x16x32_bf16 v[24:27], v[154:157], v[196:199], v[24:27]
	v_mfma_f32_16x16x32_bf16 v[12:15], v[138:141], v[212:215], v[12:15]
	v_mfma_f32_16x16x32_bf16 v[8:11], v[154:157], v[212:215], v[8:11]
	s_setprio 0
	s_barrier
	s_add_u32 s28, s28, 0x80080
	s_addc_u32 s29, s29, 0
	s_mov_b32 m0, s57
	v_lshl_add_u64 v[134:135], s[28:29], 0, v[160:161]
	global_load_lds_dwordx4 v[134:135], off
	v_lshl_add_u64 v[134:135], s[28:29], 0, v[128:129]
	s_mov_b32 m0, s58
	s_nop 0
	global_load_lds_dwordx4 v[134:135], off
	s_waitcnt vmcnt(6)
	s_barrier
	s_setprio 1
	v_mfma_f32_16x16x32_bf16 v[52:55], v[216:219], v[166:169], v[52:55]
	v_mfma_f32_16x16x32_bf16 v[48:51], v[224:227], v[166:169], v[48:51]
	v_mfma_f32_16x16x32_bf16 v[36:39], v[216:219], v[174:177], v[36:39]
	v_mfma_f32_16x16x32_bf16 v[32:35], v[224:227], v[174:177], v[32:35]
	v_mfma_f32_16x16x32_bf16 v[20:23], v[216:219], v[182:185], v[20:23]
	v_mfma_f32_16x16x32_bf16 v[16:19], v[224:227], v[182:185], v[16:19]
	v_mfma_f32_16x16x32_bf16 v[4:7], v[216:219], v[208:211], v[4:7]
	v_mfma_f32_16x16x32_bf16 v[0:3], v[224:227], v[208:211], v[0:3]
	v_mfma_f32_16x16x32_bf16 v[52:55], v[220:223], v[170:173], v[52:55]
	v_mfma_f32_16x16x32_bf16 v[48:51], v[228:231], v[170:173], v[48:51]
	v_mfma_f32_16x16x32_bf16 v[36:39], v[220:223], v[178:181], v[36:39]
	v_mfma_f32_16x16x32_bf16 v[32:35], v[228:231], v[178:181], v[32:35]
	v_mfma_f32_16x16x32_bf16 v[20:23], v[220:223], v[196:199], v[20:23]
	v_mfma_f32_16x16x32_bf16 v[16:19], v[228:231], v[196:199], v[16:19]
	v_mfma_f32_16x16x32_bf16 v[4:7], v[220:223], v[212:215], v[4:7]
	v_mfma_f32_16x16x32_bf16 v[0:3], v[228:231], v[212:215], v[0:3]
	s_setprio 0
	s_add_i32 s66, s66, 2
	s_add_u32 s26, s26, 0x100
	s_addc_u32 s27, s27, 0
	s_add_u32 s63, s63, 0x100
	s_addc_u32 s64, s64, 0
	s_cmp_gt_u32 s66, 5
	s_barrier
	s_cbranch_scc0 .LBB0_822
	v_lshl_add_u32 v140, s24, 8, v145
	v_ashrrev_i32_e32 v141, 31, v140
	v_lshl_add_u64 v[136:137], v[140:141], 3, s[10:11]
	global_load_dwordx2 v[138:139], v[136:137], off
	global_load_dwordx2 v[208:209], v[136:137], off offset:128
	global_load_dwordx2 v[210:211], v[136:137], off offset:256
	global_load_dwordx2 v[212:213], v[136:137], off offset:384
	global_load_dwordx2 v[214:215], v[136:137], off offset:1024
	global_load_dwordx2 v[216:217], v[136:137], off offset:1152
	global_load_dwordx2 v[218:219], v[136:137], off offset:1280
	global_load_dwordx2 v[220:221], v[136:137], off offset:1408
	v_lshl_or_b32 v134, s60, 8, v148
	v_ashrrev_i32_e32 v135, 31, v134
	s_mov_b32 s15, 0x20000
	s_mov_b64 s[26:27], 0x20000
	s_mov_b32 s60, s14
	s_mov_b32 s24, s16
	s_mov_b64 s[28:29], s[22:23]
	s_waitcnt vmcnt(0)
	v_cvt_f64_u32_e32 v[150:151], v139
	v_ldexp_f64 v[150:151], v[150:151], 32
	v_cvt_f64_u32_e32 v[138:139], v138
	v_add_f64 v[138:139], v[150:151], v[138:139]
	v_ldexp_f64 v[138:139], v[138:139], s93
	v_cvt_f32_f64_e32 v138, v[138:139]
	v_fmamk_f32 v138, v138, 0x3a000000, v189
	v_cmp_gt_f32_e32 vcc, s78, v138
	v_mul_f32_e32 v139, 0x4b800000, v138
	s_nop 0
	v_cndmask_b32_e32 v138, v138, v139, vcc
	v_rsq_f32_e32 v138, v138
	s_nop 0
	v_mul_f32_e32 v139, 0x45800000, v138
	v_cndmask_b32_e32 v150, v138, v139, vcc
	v_lshlrev_b64 v[138:139], 10, v[140:141]
	v_lshl_add_u64 v[152:153], s[12:13], 0, v[138:139]
	v_lshlrev_b64 v[138:139], 2, v[134:135]
	v_lshl_add_u64 v[134:135], v[152:153], 0, v[138:139]
	v_pk_mul_f32 v[114:115], v[114:115], v[150:151] op_sel_hi:[1,0]
	v_pk_mul_f32 v[112:113], v[112:113], v[150:151] op_sel_hi:[1,0]
	global_store_dwordx4 v[134:135], v[112:115], off offset:576
	v_pk_mul_f32 v[126:127], v[126:127], v[150:151] op_sel_hi:[1,0]
	v_pk_mul_f32 v[124:125], v[124:125], v[150:151] op_sel_hi:[1,0]
	v_or_b32_e32 v112, 16, v140
	v_pk_mul_f32 v[122:123], v[122:123], v[150:151] op_sel_hi:[1,0]
	v_pk_mul_f32 v[120:121], v[120:121], v[150:151] op_sel_hi:[1,0]
	v_pk_mul_f32 v[118:119], v[118:119], v[150:151] op_sel_hi:[1,0]
	v_pk_mul_f32 v[116:117], v[116:117], v[150:151] op_sel_hi:[1,0]
	v_ashrrev_i32_e32 v113, 31, v112
	global_store_dwordx4 v[134:135], v[124:127], off
	global_store_dwordx4 v[134:135], v[120:123], off offset:64
	global_store_dwordx4 v[134:135], v[116:119], off offset:512
	v_lshl_add_u64 v[114:115], v[112:113], 3, s[10:11]
	s_nop 1
	v_mov_b64_e32 v[114:115], v[208:209]
	v_lshlrev_b64 v[112:113], 10, v[112:113]
	v_lshl_add_u64 v[112:113], s[12:13], 0, v[112:113]
	v_lshl_add_u64 v[112:113], v[112:113], 0, v[138:139]
	v_cvt_f64_u32_e32 v[116:117], v115
	v_ldexp_f64 v[116:117], v[116:117], 32
	v_cvt_f64_u32_e32 v[114:115], v114
	v_add_f64 v[114:115], v[116:117], v[114:115]
	v_ldexp_f64 v[114:115], v[114:115], s93
	v_cvt_f32_f64_e32 v114, v[114:115]
	v_fmamk_f32 v114, v114, 0x3a000000, v189
	v_cmp_gt_f32_e32 vcc, s78, v114
; __device__ __forceinline__ float rinv_st(stat_t s, float invn) { return rsqrtf((float)((double)s * (1.0 / 4294967296.0)) * invn + 1e-6f); }
;     __device__ __forceinline__ void operator()(const f32x4 (&acc)[2][2][4][2], const Unit& u, int wr, int wc, int fr, int fq) const {
;     ...
;         for (int ai = 0; ai < 2; ++ai)
; #pragma unroll
;             for (int m = 0; m < 4; ++m) {
;                 const int row = row0 + ai * HALF + m * 16; const float r = rinv_st(stats[row], 1.0f / 2048.0f);
;                 float* rowp = raw + (size_t)row * 256 + col0;
; #pragma unroll
;                 for (int bj = 0; bj < 2; ++bj)
; #pragma unroll
;                     for (int n = 0; n < 2; ++n) *(f32x4*)(rowp + bj * HALF + n * 16) = acc[ai][bj][m][n] * r;
	v_mul_f32_e32 v115, 0x4b800000, v114
	s_nop 0
	v_cndmask_b32_e32 v114, v114, v115, vcc
	v_rsq_f32_e32 v114, v114
	s_nop 0
	v_mul_f32_e32 v115, 0x45800000, v114
	v_cndmask_b32_e32 v114, v114, v115, vcc
	v_pk_mul_f32 v[98:99], v[98:99], v[114:115] op_sel_hi:[1,0]
	v_pk_mul_f32 v[96:97], v[96:97], v[114:115] op_sel_hi:[1,0]
	global_store_dwordx4 v[112:113], v[96:99], off offset:576
	v_pk_mul_f32 v[110:111], v[110:111], v[114:115] op_sel_hi:[1,0]
	v_pk_mul_f32 v[108:109], v[108:109], v[114:115] op_sel_hi:[1,0]
	v_or_b32_e32 v96, 32, v140
	v_pk_mul_f32 v[106:107], v[106:107], v[114:115] op_sel_hi:[1,0]
	v_pk_mul_f32 v[104:105], v[104:105], v[114:115] op_sel_hi:[1,0]
	v_pk_mul_f32 v[102:103], v[102:103], v[114:115] op_sel_hi:[1,0]
	v_pk_mul_f32 v[100:101], v[100:101], v[114:115] op_sel_hi:[1,0]
	v_ashrrev_i32_e32 v97, 31, v96
	global_store_dwordx4 v[112:113], v[108:111], off
	global_store_dwordx4 v[112:113], v[104:107], off offset:64
	global_store_dwordx4 v[112:113], v[100:103], off offset:512
	v_lshl_add_u64 v[98:99], v[96:97], 3, s[10:11]
	s_nop 1
	v_mov_b64_e32 v[98:99], v[210:211]
	v_lshlrev_b64 v[96:97], 10, v[96:97]
	v_lshl_add_u64 v[96:97], s[12:13], 0, v[96:97]
	v_lshl_add_u64 v[96:97], v[96:97], 0, v[138:139]
	v_cvt_f64_u32_e32 v[100:101], v99
	v_ldexp_f64 v[100:101], v[100:101], 32
	v_cvt_f64_u32_e32 v[98:99], v98
	v_add_f64 v[98:99], v[100:101], v[98:99]
	v_ldexp_f64 v[98:99], v[98:99], s93
	v_cvt_f32_f64_e32 v98, v[98:99]
	v_fmamk_f32 v98, v98, 0x3a000000, v189
	v_cmp_gt_f32_e32 vcc, s78, v98
	v_mul_f32_e32 v99, 0x4b800000, v98
	s_nop 0
	v_cndmask_b32_e32 v98, v98, v99, vcc
	v_rsq_f32_e32 v98, v98
	s_nop 0
	v_mul_f32_e32 v99, 0x45800000, v98
	v_cndmask_b32_e32 v98, v98, v99, vcc
	v_pk_mul_f32 v[82:83], v[82:83], v[98:99] op_sel_hi:[1,0]
	v_pk_mul_f32 v[80:81], v[80:81], v[98:99] op_sel_hi:[1,0]
	global_store_dwordx4 v[96:97], v[80:83], off offset:576
	v_pk_mul_f32 v[94:95], v[94:95], v[98:99] op_sel_hi:[1,0]
	v_pk_mul_f32 v[92:93], v[92:93], v[98:99] op_sel_hi:[1,0]
	v_or_b32_e32 v80, 48, v140
	v_pk_mul_f32 v[90:91], v[90:91], v[98:99] op_sel_hi:[1,0]
	v_pk_mul_f32 v[88:89], v[88:89], v[98:99] op_sel_hi:[1,0]
	v_pk_mul_f32 v[86:87], v[86:87], v[98:99] op_sel_hi:[1,0]
	v_pk_mul_f32 v[84:85], v[84:85], v[98:99] op_sel_hi:[1,0]
	v_ashrrev_i32_e32 v81, 31, v80
	global_store_dwordx4 v[96:97], v[92:95], off
	global_store_dwordx4 v[96:97], v[88:91], off offset:64
	global_store_dwordx4 v[96:97], v[84:87], off offset:512
	v_lshl_add_u64 v[82:83], v[80:81], 3, s[10:11]
	s_nop 1
	v_mov_b64_e32 v[82:83], v[212:213]
	v_lshlrev_b64 v[80:81], 10, v[80:81]
	v_lshl_add_u64 v[80:81], s[12:13], 0, v[80:81]
	v_lshl_add_u64 v[80:81], v[80:81], 0, v[138:139]
	v_cvt_f64_u32_e32 v[84:85], v83
	v_ldexp_f64 v[84:85], v[84:85], 32
	v_cvt_f64_u32_e32 v[82:83], v82
	v_add_f64 v[82:83], v[84:85], v[82:83]
	v_ldexp_f64 v[82:83], v[82:83], s93
	v_cvt_f32_f64_e32 v82, v[82:83]
	v_fmamk_f32 v82, v82, 0x3a000000, v189
	v_cmp_gt_f32_e32 vcc, s78, v82
	v_mul_f32_e32 v83, 0x4b800000, v82
	s_nop 0
	v_cndmask_b32_e32 v82, v82, v83, vcc
	v_rsq_f32_e32 v82, v82
	s_nop 0
	v_mul_f32_e32 v83, 0x45800000, v82
	v_cndmask_b32_e32 v82, v82, v83, vcc
	v_pk_mul_f32 v[78:79], v[78:79], v[82:83] op_sel_hi:[1,0]
	v_pk_mul_f32 v[76:77], v[76:77], v[82:83] op_sel_hi:[1,0]
	v_pk_mul_f32 v[74:75], v[74:75], v[82:83] op_sel_hi:[1,0]
	v_pk_mul_f32 v[72:73], v[72:73], v[82:83] op_sel_hi:[1,0]
	v_pk_mul_f32 v[70:71], v[70:71], v[82:83] op_sel_hi:[1,0]
	v_pk_mul_f32 v[68:69], v[68:69], v[82:83] op_sel_hi:[1,0]
	v_pk_mul_f32 v[66:67], v[66:67], v[82:83] op_sel_hi:[1,0]
	v_pk_mul_f32 v[64:65], v[64:65], v[82:83] op_sel_hi:[1,0]
	global_store_dwordx4 v[80:81], v[76:79], off
	global_store_dwordx4 v[80:81], v[72:75], off offset:64
	global_store_dwordx4 v[80:81], v[68:71], off offset:512
	global_store_dwordx4 v[80:81], v[64:67], off offset:576
	s_nop 1
	v_mov_b64_e32 v[64:65], v[214:215]
	v_cvt_f64_u32_e32 v[66:67], v65
	v_ldexp_f64 v[66:67], v[66:67], 32
	v_cvt_f64_u32_e32 v[64:65], v64
	v_add_f64 v[64:65], v[66:67], v[64:65]
	v_ldexp_f64 v[64:65], v[64:65], s93
	v_cvt_f32_f64_e32 v64, v[64:65]
	v_fmamk_f32 v64, v64, 0x3a000000, v189
	v_cmp_gt_f32_e32 vcc, s78, v64
	v_mul_f32_e32 v65, 0x4b800000, v64
	v_lshl_add_u64 v[66:67], v[134:135], 0, s[26:27]
	v_cndmask_b32_e32 v64, v64, v65, vcc
	v_rsq_f32_e32 v64, v64
	s_mov_b64 s[26:27], 0x24000
	v_mul_f32_e32 v65, 0x45800000, v64
	v_cndmask_b32_e32 v64, v64, v65, vcc
	v_add_co_u32_e32 v68, vcc, s15, v134
	v_pk_mul_f32 v[62:63], v[62:63], v[64:65] op_sel_hi:[1,0]
	v_pk_mul_f32 v[60:61], v[60:61], v[64:65] op_sel_hi:[1,0]
	v_addc_co_u32_e32 v69, vcc, 0, v135, vcc
	v_pk_mul_f32 v[58:59], v[58:59], v[64:65] op_sel_hi:[1,0]
	v_pk_mul_f32 v[56:57], v[56:57], v[64:65] op_sel_hi:[1,0]
; __device__ __forceinline__ float rinv_st(stat_t s, float invn) { return rsqrtf((float)((double)s * (1.0 / 4294967296.0)) * invn + 1e-6f); }
; #define PG8_WAIT_V(n) asm volatile("s_waitcnt vmcnt(" #n ")" ::: "memory")
; #define PG8_BAR __builtin_amdgcn_s_barrier()
; template <class Epi>
; __device__ __forceinline__ void gemm_phase(const int TID, const int BID, LAS unsigned char* lds, const Gemm g, const StaticOrder& S, const Epi& E) {
;     ...
;         if (!has_next) break;
; #pragma unroll
;         for (int a = 0; a < 2; ++a)
; #pragma unroll
;             for (int b = 0; b < 2; ++b)
; #pragma unroll
;                 for (int m = 0; m < 4; ++m)
; #pragma unroll
;                     for (int n = 0; n < 2; ++n) acc[a][b][m][n] = (f32x4){0.f, 0.f, 0.f, 0.f};
;         cur = nxt; cA = nA; cB = nB; ++ui;
;     }
;     PG8_WAIT_V(0);
;     if (wr == 0) PG8_BAR;
;     PG8_BAR;
;     __device__ __forceinline__ void operator()(const f32x4 (&acc)[2][2][4][2], const Unit& u, int wr, int wc, int fr, int fq) const {
;     ...
;         for (int ai = 0; ai < 2; ++ai)
; #pragma unroll
;             for (int m = 0; m < 4; ++m) {
;                 const int row = row0 + ai * HALF + m * 16; const float r = rinv_st(stats[row], 1.0f / 2048.0f);
;                 float* rowp = raw + (size_t)row * 256 + col0;
; #pragma unroll
;                 for (int bj = 0; bj < 2; ++bj)
; #pragma unroll
;                     for (int n = 0; n < 2; ++n) *(f32x4*)(rowp + bj * HALF + n * 16) = acc[ai][bj][m][n] * r;
	v_pk_mul_f32 v[54:55], v[54:55], v[64:65] op_sel_hi:[1,0]
	v_pk_mul_f32 v[52:53], v[52:53], v[64:65] op_sel_hi:[1,0]
	v_pk_mul_f32 v[50:51], v[50:51], v[64:65] op_sel_hi:[1,0]
	v_pk_mul_f32 v[48:49], v[48:49], v[64:65] op_sel_hi:[1,0]
	global_store_dwordx4 v[68:69], v[60:63], off
	global_store_dwordx4 v[66:67], v[56:59], off offset:64
	global_store_dwordx4 v[66:67], v[52:55], off offset:512
	global_store_dwordx4 v[66:67], v[48:51], off offset:576
	s_nop 1
	v_mov_b64_e32 v[48:49], v[216:217]
	s_mov_b32 s15, 0x24000
	v_cvt_f64_u32_e32 v[50:51], v49
	v_ldexp_f64 v[50:51], v[50:51], 32
	v_cvt_f64_u32_e32 v[48:49], v48
	v_add_f64 v[48:49], v[50:51], v[48:49]
	v_ldexp_f64 v[48:49], v[48:49], s93
	v_cvt_f32_f64_e32 v48, v[48:49]
	v_fmamk_f32 v48, v48, 0x3a000000, v189
	v_cmp_gt_f32_e32 vcc, s78, v48
	v_mul_f32_e32 v49, 0x4b800000, v48
	v_lshl_add_u64 v[50:51], v[134:135], 0, s[26:27]
	v_cndmask_b32_e32 v48, v48, v49, vcc
	v_rsq_f32_e32 v48, v48
	s_mov_b64 s[26:27], 0x28000
	v_mul_f32_e32 v49, 0x45800000, v48
	v_cndmask_b32_e32 v48, v48, v49, vcc
	v_add_co_u32_e32 v52, vcc, s15, v134
	v_pk_mul_f32 v[46:47], v[46:47], v[48:49] op_sel_hi:[1,0]
	v_pk_mul_f32 v[44:45], v[44:45], v[48:49] op_sel_hi:[1,0]
	v_addc_co_u32_e32 v53, vcc, 0, v135, vcc
	v_pk_mul_f32 v[42:43], v[42:43], v[48:49] op_sel_hi:[1,0]
	v_pk_mul_f32 v[40:41], v[40:41], v[48:49] op_sel_hi:[1,0]
	v_pk_mul_f32 v[38:39], v[38:39], v[48:49] op_sel_hi:[1,0]
	v_pk_mul_f32 v[36:37], v[36:37], v[48:49] op_sel_hi:[1,0]
	v_pk_mul_f32 v[34:35], v[34:35], v[48:49] op_sel_hi:[1,0]
	v_pk_mul_f32 v[32:33], v[32:33], v[48:49] op_sel_hi:[1,0]
	global_store_dwordx4 v[52:53], v[44:47], off
	global_store_dwordx4 v[50:51], v[40:43], off offset:64
	global_store_dwordx4 v[50:51], v[36:39], off offset:512
	global_store_dwordx4 v[50:51], v[32:35], off offset:576
	s_nop 1
	v_mov_b64_e32 v[32:33], v[218:219]
	s_mov_b32 s15, 0x28000
	v_cvt_f64_u32_e32 v[34:35], v33
	v_ldexp_f64 v[34:35], v[34:35], 32
	v_cvt_f64_u32_e32 v[32:33], v32
	v_add_f64 v[32:33], v[34:35], v[32:33]
	v_ldexp_f64 v[32:33], v[32:33], s93
	v_cvt_f32_f64_e32 v32, v[32:33]
	v_fmamk_f32 v32, v32, 0x3a000000, v189
	v_cmp_gt_f32_e32 vcc, s78, v32
	v_mul_f32_e32 v33, 0x4b800000, v32
	v_lshl_add_u64 v[34:35], v[134:135], 0, s[26:27]
	v_cndmask_b32_e32 v32, v32, v33, vcc
	v_rsq_f32_e32 v32, v32
	s_mov_b64 s[26:27], 0x2c000
	v_mul_f32_e32 v33, 0x45800000, v32
	v_cndmask_b32_e32 v32, v32, v33, vcc
	v_add_co_u32_e32 v36, vcc, s15, v134
	v_pk_mul_f32 v[30:31], v[30:31], v[32:33] op_sel_hi:[1,0]
	v_pk_mul_f32 v[28:29], v[28:29], v[32:33] op_sel_hi:[1,0]
	v_addc_co_u32_e32 v37, vcc, 0, v135, vcc
	v_pk_mul_f32 v[26:27], v[26:27], v[32:33] op_sel_hi:[1,0]
	v_pk_mul_f32 v[24:25], v[24:25], v[32:33] op_sel_hi:[1,0]
	v_pk_mul_f32 v[22:23], v[22:23], v[32:33] op_sel_hi:[1,0]
	v_pk_mul_f32 v[20:21], v[20:21], v[32:33] op_sel_hi:[1,0]
	v_pk_mul_f32 v[18:19], v[18:19], v[32:33] op_sel_hi:[1,0]
	v_pk_mul_f32 v[16:17], v[16:17], v[32:33] op_sel_hi:[1,0]
	global_store_dwordx4 v[36:37], v[28:31], off
	global_store_dwordx4 v[34:35], v[24:27], off offset:64
	global_store_dwordx4 v[34:35], v[20:23], off offset:512
	global_store_dwordx4 v[34:35], v[16:19], off offset:576
	s_nop 1
	v_mov_b64_e32 v[16:17], v[220:221]
	s_mov_b32 s15, 0x2c000
	v_cvt_f64_u32_e32 v[18:19], v17
	v_ldexp_f64 v[18:19], v[18:19], 32
	v_cvt_f64_u32_e32 v[16:17], v16
	v_add_f64 v[16:17], v[18:19], v[16:17]
	v_ldexp_f64 v[16:17], v[16:17], s93
	v_cvt_f32_f64_e32 v16, v[16:17]
	v_fmamk_f32 v16, v16, 0x3a000000, v189
	v_cmp_gt_f32_e32 vcc, s78, v16
	v_mul_f32_e32 v17, 0x4b800000, v16
	v_lshl_add_u64 v[18:19], v[134:135], 0, s[26:27]
	v_cndmask_b32_e32 v16, v16, v17, vcc
	v_rsq_f32_e32 v16, v16
	s_mov_b64 s[26:27], s[20:21]
	v_mul_f32_e32 v17, 0x45800000, v16
	v_cndmask_b32_e32 v16, v16, v17, vcc
	v_add_co_u32_e32 v20, vcc, s15, v134
	v_pk_mul_f32 v[14:15], v[14:15], v[16:17] op_sel_hi:[1,0]
	s_nop 0
	v_addc_co_u32_e32 v21, vcc, 0, v135, vcc
	v_pk_mul_f32 v[12:13], v[12:13], v[16:17] op_sel_hi:[1,0]
	v_pk_mul_f32 v[10:11], v[10:11], v[16:17] op_sel_hi:[1,0]
	v_pk_mul_f32 v[8:9], v[8:9], v[16:17] op_sel_hi:[1,0]
	v_pk_mul_f32 v[6:7], v[6:7], v[16:17] op_sel_hi:[1,0]
	v_pk_mul_f32 v[4:5], v[4:5], v[16:17] op_sel_hi:[1,0]
	v_pk_mul_f32 v[2:3], v[2:3], v[16:17] op_sel_hi:[1,0]
	v_pk_mul_f32 v[0:1], v[0:1], v[16:17] op_sel_hi:[1,0]
	s_and_b64 vcc, exec, s[18:19]
	global_store_dwordx4 v[20:21], v[12:15], off
	global_store_dwordx4 v[18:19], v[8:11], off offset:64
	global_store_dwordx4 v[18:19], v[4:7], off offset:512
	global_store_dwordx4 v[18:19], v[0:3], off offset:576
	s_cbranch_vccz .LBB0_815
	s_waitcnt vmcnt(0)
	s_cmpk_gt_u32 s42, 0xff
	s_cbranch_scc1 .LBB0_805
	s_barrier
	s_branch .LBB0_805

; #define PG8_STAGE(bufoff, gbase, voff) do { _Pragma("unroll") for (int _i = 0; _i < 2; ++_i) \
;         __builtin_amdgcn_global_load_lds((const unsigned*)((const char*)(gbase) + (voff)[_i]), (LAS unsigned*)(lds + (bufoff) + ldsw + _i * 8192), 16, 0, 0); } while (0)
; #define PG8_LDA(dst, b, h) do { _Pragma("unroll") for (int m = 0; m < 4; ++m) _Pragma("unroll") for (int k = 0; k < 2; ++k) dst[m][k] = *(const LAS bf16x8*)(lds + PG8_SA(b, h) + aoff + m * 2048 + k * 1024); } while (0)
; #define PG8_LDB(dst, b, h) do { _Pragma("unroll") for (int n = 0; n < 2; ++n) _Pragma("unroll") for (int k = 0; k < 2; ++k) dst[n][k] = *(const LAS bf16x8*)(lds + PG8_SB(b, h) + boff + n * 2048 + k * 1024); } while (0)
; #define PG8_MMA(ai, bj, At, Bt) do { __builtin_amdgcn_s_setprio(1); _Pragma("unroll") for (int m = 0; m < 4; ++m) _Pragma("unroll") for (int n = 0; n < 2; ++n) _Pragma("unroll") for (int k = 0; k < 2; ++k) \
;         acc[ai][bj][m][n] = __builtin_amdgcn_mfma_f32_16x16x32_bf16(Bt[n][k], At[m][k], acc[ai][bj][m][n], 0, 0, 0); __builtin_amdgcn_s_setprio(0); } while (0)
; #define PG8_WAIT_V(n) asm volatile("s_waitcnt vmcnt(" #n ")" ::: "memory")
; #define PG8_WAIT_L(n) asm volatile("s_waitcnt lgkmcnt(" #n ")" ::: "memory")
; template <class Epi>
; __device__ __forceinline__ void gemm_phase(const int TID, const int BID, LAS unsigned char* lds, const Gemm g, const StaticOrder& S, const Epi& E) {
;     ...
;         for (int t = 0; t < nt; t += 2) {
;             const bool last = (t == nt - 2);
;             const char* a1 = cA + (size_t)(t + 1) * kstep;
;             const char* a2 = last ? nA : cA + (size_t)(t + 2) * kstep; const char* b2 = last ? nB : cB + (size_t)(t + 2) * kstep;
;             const char* a3 = a2 + kstep; const char* b3 = b2 + kstep;
;             PG8_LDB(B0, 0, 0); PG8_SCHED; PG8_LDA(At, 0, 0); PG8_STAGE(PG8_SA(1, 1), a1 + hstepA, voffA);
;             PG8_WAIT_L(8); PG8_BAR; PG8_WAIT_L(0); PG8_MMA(0, 0, At, B0); PG8_BAR; PG8_SCHED;
;             PG8_LDB(B1, 0, 1); PG8_STAGE(PG8_SB(0, 0), b2, voffB);
;             PG8_BAR; PG8_WAIT_L(0); PG8_MMA(0, 1, At, B1); PG8_BAR;
;             PG8_LDA(At, 0, 1); PG8_STAGE(PG8_SA(0, 0), a2, voffA);
;             PG8_BAR; PG8_WAIT_L(0); PG8_MMA(1, 0, At, B0); PG8_BAR; PG8_SCHED;
;             PG8_STAGE(PG8_SB(0, 1), b2 + hstepB, voffB);
;             PG8_WAIT_V(6); PG8_BAR; PG8_MMA(1, 1, At, B1); PG8_BAR;
.LBB0_864:
	v_add_u32_e32 v36, s43, v172
	ds_read_b128 v[8:11], v36
	ds_read_b128 v[12:15], v36 offset:1024
	ds_read_b128 v[32:35], v36 offset:2048
	ds_read_b128 v[36:39], v36 offset:3072
	s_add_u32 s36, s34, 0xfff80080
	s_addc_u32 s37, s35, -1
	s_cmp_eq_u32 s31, 28
	s_cselect_b32 s39, s0, s37
	s_cselect_b32 s38, s1, s36
	s_cselect_b32 s37, s4, s29
	s_cselect_b32 s36, s21, s23
	v_lshl_add_u64 v[158:159], s[34:35], 0, v[150:151]
	s_add_i32 m0, s46, 0xc000
	ds_read_b128 v[154:157], v174
	ds_read_b128 v[176:179], v174 offset:1024
	ds_read_b128 v[180:183], v174 offset:2048
	ds_read_b128 v[196:199], v174 offset:3072
	ds_read_b128 v[208:211], v174 offset:4096
	ds_read_b128 v[212:215], v174 offset:5120
	ds_read_b128 v[216:219], v174 offset:6144
	ds_read_b128 v[220:223], v174 offset:7168
	global_load_lds_dwordx4 v[158:159], off
	v_lshl_add_u64 v[158:159], s[34:35], 0, v[152:153]
	s_add_i32 m0, s46, 0xe000
	s_nop 0
	global_load_lds_dwordx4 v[158:159], off
	s_waitcnt lgkmcnt(8)
	s_barrier
	s_waitcnt lgkmcnt(0)
	s_setprio 1
	v_mfma_f32_16x16x32_bf16 v[140:143], v[8:11], v[154:157], v[140:143]
	v_mfma_f32_16x16x32_bf16 v[136:139], v[32:35], v[154:157], v[136:139]
	v_mfma_f32_16x16x32_bf16 v[124:127], v[8:11], v[180:183], v[124:127]
	v_mfma_f32_16x16x32_bf16 v[120:123], v[32:35], v[180:183], v[120:123]
	v_mfma_f32_16x16x32_bf16 v[108:111], v[8:11], v[208:211], v[108:111]
	v_mfma_f32_16x16x32_bf16 v[104:107], v[32:35], v[208:211], v[104:107]
	v_mfma_f32_16x16x32_bf16 v[92:95], v[8:11], v[216:219], v[92:95]
	v_mfma_f32_16x16x32_bf16 v[88:91], v[32:35], v[216:219], v[88:91]
	v_mfma_f32_16x16x32_bf16 v[140:143], v[12:15], v[176:179], v[140:143]
	v_mfma_f32_16x16x32_bf16 v[136:139], v[36:39], v[176:179], v[136:139]
	v_mfma_f32_16x16x32_bf16 v[124:127], v[12:15], v[196:199], v[124:127]
	v_mfma_f32_16x16x32_bf16 v[120:123], v[36:39], v[196:199], v[120:123]
	v_mfma_f32_16x16x32_bf16 v[108:111], v[12:15], v[212:215], v[108:111]
	v_mfma_f32_16x16x32_bf16 v[104:107], v[36:39], v[212:215], v[104:107]
	v_mfma_f32_16x16x32_bf16 v[92:95], v[12:15], v[220:223], v[92:95]
	v_mfma_f32_16x16x32_bf16 v[88:91], v[36:39], v[220:223], v[88:91]
	s_setprio 0
	s_barrier
	v_add_u32_e32 v158, s48, v172
	s_mov_b32 m0, s44
	ds_read_b128 v[224:227], v158
	ds_read_b128 v[228:231], v158 offset:1024
	ds_read_b128 v[232:235], v158 offset:2048
	ds_read_b128 v[236:239], v158 offset:3072
	v_lshl_add_u64 v[158:159], s[36:37], 0, v[160:161]
	global_load_lds_dwordx4 v[158:159], off
	v_lshl_add_u64 v[166:167], s[36:37], 0, v[148:149]
	s_mov_b32 m0, s45
	s_nop 0
	global_load_lds_dwordx4 v[166:167], off
	s_barrier
	s_waitcnt lgkmcnt(0)
	s_setprio 1
	v_mfma_f32_16x16x32_bf16 v[132:135], v[224:227], v[154:157], v[132:135]
	v_mfma_f32_16x16x32_bf16 v[128:131], v[232:235], v[154:157], v[128:131]
	v_mfma_f32_16x16x32_bf16 v[116:119], v[224:227], v[180:183], v[116:119]
	v_mfma_f32_16x16x32_bf16 v[112:115], v[232:235], v[180:183], v[112:115]
	v_mfma_f32_16x16x32_bf16 v[100:103], v[224:227], v[208:211], v[100:103]
	v_mfma_f32_16x16x32_bf16 v[96:99], v[232:235], v[208:211], v[96:99]
	v_mfma_f32_16x16x32_bf16 v[84:87], v[224:227], v[216:219], v[84:87]
	v_mfma_f32_16x16x32_bf16 v[80:83], v[232:235], v[216:219], v[80:83]
	v_mfma_f32_16x16x32_bf16 v[132:135], v[228:231], v[176:179], v[132:135]
	v_mfma_f32_16x16x32_bf16 v[128:131], v[236:239], v[176:179], v[128:131]
	v_mfma_f32_16x16x32_bf16 v[116:119], v[228:231], v[196:199], v[116:119]
	v_mfma_f32_16x16x32_bf16 v[112:115], v[236:239], v[196:199], v[112:115]
	v_mfma_f32_16x16x32_bf16 v[100:103], v[228:231], v[212:215], v[100:103]
	v_mfma_f32_16x16x32_bf16 v[96:99], v[236:239], v[212:215], v[96:99]
	v_mfma_f32_16x16x32_bf16 v[84:87], v[228:231], v[220:223], v[84:87]
	v_mfma_f32_16x16x32_bf16 v[80:83], v[236:239], v[220:223], v[80:83]
	s_setprio 0
	s_mov_b32 m0, s46
	v_lshl_add_u64 v[170:171], s[38:39], 0, v[144:145]
	s_barrier
	ds_read_b128 v[154:157], v174 offset:16384
	ds_read_b128 v[176:179], v174 offset:17408
	ds_read_b128 v[180:183], v174 offset:18432
	ds_read_b128 v[196:199], v174 offset:19456
	ds_read_b128 v[208:211], v174 offset:20480
	ds_read_b128 v[212:215], v174 offset:21504
	ds_read_b128 v[216:219], v174 offset:22528
	ds_read_b128 v[220:223], v174 offset:23552
	global_load_lds_dwordx4 v[170:171], off
	v_lshl_add_u64 v[184:185], s[38:39], 0, v[146:147]
	s_mov_b32 m0, s47
	s_nop 0
	global_load_lds_dwordx4 v[184:185], off
	s_barrier
	s_waitcnt lgkmcnt(0)
	s_setprio 1
	v_mfma_f32_16x16x32_bf16 v[76:79], v[8:11], v[154:157], v[76:79]
	v_mfma_f32_16x16x32_bf16 v[72:75], v[32:35], v[154:157], v[72:75]
	v_mfma_f32_16x16x32_bf16 v[60:63], v[8:11], v[180:183], v[60:63]
	v_mfma_f32_16x16x32_bf16 v[56:59], v[32:35], v[180:183], v[56:59]
	v_mfma_f32_16x16x32_bf16 v[44:47], v[8:11], v[208:211], v[44:47]
	v_mfma_f32_16x16x32_bf16 v[40:43], v[32:35], v[208:211], v[40:43]
	v_mfma_f32_16x16x32_bf16 v[8:11], v[8:11], v[216:219], v[20:23]
	v_mfma_f32_16x16x32_bf16 v[76:79], v[12:15], v[176:179], v[76:79]
	v_mfma_f32_16x16x32_bf16 v[72:75], v[36:39], v[176:179], v[72:75]
	v_mfma_f32_16x16x32_bf16 v[60:63], v[12:15], v[196:199], v[60:63]
	v_mfma_f32_16x16x32_bf16 v[56:59], v[36:39], v[196:199], v[56:59]
	v_mfma_f32_16x16x32_bf16 v[44:47], v[12:15], v[212:215], v[44:47]
	v_mfma_f32_16x16x32_bf16 v[40:43], v[36:39], v[212:215], v[40:43]
	v_mfma_f32_16x16x32_bf16 v[8:11], v[12:15], v[220:223], v[8:11]
	v_mfma_f32_16x16x32_bf16 v[12:15], v[32:35], v[216:219], v[16:19]
	v_mfma_f32_16x16x32_bf16 v[12:15], v[36:39], v[220:223], v[12:15]
	s_setprio 0
	s_barrier
; #define PG8_STAGE(bufoff, gbase, voff) do { _Pragma("unroll") for (int _i = 0; _i < 2; ++_i) \
;         __builtin_amdgcn_global_load_lds((const unsigned*)((const char*)(gbase) + (voff)[_i]), (LAS unsigned*)(lds + (bufoff) + ldsw + _i * 8192), 16, 0, 0); } while (0)
; #define PG8_LDA(dst, b, h) do { _Pragma("unroll") for (int m = 0; m < 4; ++m) _Pragma("unroll") for (int k = 0; k < 2; ++k) dst[m][k] = *(const LAS bf16x8*)(lds + PG8_SA(b, h) + aoff + m * 2048 + k * 1024); } while (0)
; #define PG8_LDB(dst, b, h) do { _Pragma("unroll") for (int n = 0; n < 2; ++n) _Pragma("unroll") for (int k = 0; k < 2; ++k) dst[n][k] = *(const LAS bf16x8*)(lds + PG8_SB(b, h) + boff + n * 2048 + k * 1024); } while (0)
; #define PG8_MMA(ai, bj, At, Bt) do { __builtin_amdgcn_s_setprio(1); _Pragma("unroll") for (int m = 0; m < 4; ++m) _Pragma("unroll") for (int n = 0; n < 2; ++n) _Pragma("unroll") for (int k = 0; k < 2; ++k) \
;         acc[ai][bj][m][n] = __builtin_amdgcn_mfma_f32_16x16x32_bf16(Bt[n][k], At[m][k], acc[ai][bj][m][n], 0, 0, 0); __builtin_amdgcn_s_setprio(0); } while (0)
; #define PG8_WAIT_V(n) asm volatile("s_waitcnt vmcnt(" #n ")" ::: "memory")
; #define PG8_WAIT_L(n) asm volatile("s_waitcnt lgkmcnt(" #n ")" ::: "memory")
; #define PG8_BAR __builtin_amdgcn_s_barrier()
; #define PG8_SCHED __builtin_amdgcn_sched_barrier(0)
; template <class Epi>
; __device__ __forceinline__ void gemm_phase(const int TID, const int BID, LAS unsigned char* lds, const Gemm g, const StaticOrder& S, const Epi& E) {
;     ...
;             PG8_STAGE(PG8_SB(0, 1), b2 + hstepB, voffB);
;             PG8_WAIT_V(6); PG8_BAR; PG8_MMA(1, 1, At, B1); PG8_BAR;
;             PG8_LDB(B0, 1, 0); PG8_SCHED; PG8_LDA(At, 1, 0); PG8_STAGE(PG8_SA(0, 1), a2 + hstepA, voffA);
;             PG8_WAIT_L(8); PG8_BAR; PG8_WAIT_L(0); PG8_MMA(0, 0, At, B0); PG8_BAR; PG8_SCHED;
;             PG8_LDB(B1, 1, 1); PG8_STAGE(PG8_SB(1, 0), b3, voffB);
;             PG8_BAR; PG8_WAIT_L(0); PG8_MMA(0, 1, At, B1); PG8_BAR;
;             PG8_LDA(At, 1, 1); PG8_STAGE(PG8_SA(1, 0), a3, voffA);
;             PG8_BAR; PG8_WAIT_L(0); PG8_MMA(1, 0, At, B0); PG8_BAR; PG8_SCHED;
	s_add_u32 s66, s36, 0x80000
	s_addc_u32 s67, s37, 0
	s_mov_b32 m0, s49
	v_lshl_add_u64 v[16:17], s[66:67], 0, v[160:161]
	global_load_lds_dwordx4 v[16:17], off
	v_lshl_add_u64 v[16:17], s[66:67], 0, v[148:149]
	s_mov_b32 m0, s50
	s_nop 0
	global_load_lds_dwordx4 v[16:17], off
	s_waitcnt vmcnt(6)
	s_barrier
	s_setprio 1
	v_mfma_f32_16x16x32_bf16 v[16:19], v[224:227], v[154:157], v[68:71]
	v_mfma_f32_16x16x32_bf16 v[32:35], v[228:231], v[176:179], v[16:19]
	v_mfma_f32_16x16x32_bf16 v[16:19], v[232:235], v[154:157], v[64:67]
	v_mfma_f32_16x16x32_bf16 v[36:39], v[236:239], v[176:179], v[16:19]
	v_mfma_f32_16x16x32_bf16 v[16:19], v[224:227], v[180:183], v[52:55]
	v_mfma_f32_16x16x32_bf16 v[52:55], v[228:231], v[196:199], v[16:19]
	v_mfma_f32_16x16x32_bf16 v[16:19], v[232:235], v[180:183], v[48:51]
	v_mfma_f32_16x16x32_bf16 v[48:51], v[236:239], v[196:199], v[16:19]
	v_mfma_f32_16x16x32_bf16 v[16:19], v[224:227], v[208:211], v[28:31]
	v_mfma_f32_16x16x32_bf16 v[28:31], v[228:231], v[212:215], v[16:19]
	v_mfma_f32_16x16x32_bf16 v[16:19], v[232:235], v[208:211], v[24:27]
	v_mfma_f32_16x16x32_bf16 v[4:7], v[224:227], v[216:219], v[4:7]
	v_mfma_f32_16x16x32_bf16 v[0:3], v[232:235], v[216:219], v[0:3]
	v_mfma_f32_16x16x32_bf16 v[24:27], v[236:239], v[212:215], v[16:19]
	v_mfma_f32_16x16x32_bf16 v[4:7], v[228:231], v[220:223], v[4:7]
	v_mfma_f32_16x16x32_bf16 v[0:3], v[236:239], v[220:223], v[0:3]
	s_setprio 0
	v_add_u32_e32 v68, s53, v172
	s_barrier
	ds_read_b128 v[16:19], v68
	ds_read_b128 v[20:23], v68 offset:1024
	ds_read_b128 v[64:67], v68 offset:2048
	ds_read_b128 v[68:71], v68 offset:3072
	s_add_u32 s38, s38, 0x80000
	s_addc_u32 s39, s39, 0
	s_mov_b32 m0, s51
	v_lshl_add_u64 v[200:201], s[38:39], 0, v[144:145]
	ds_read_b128 v[154:157], v174 offset:32768
	ds_read_b128 v[176:179], v174 offset:33792
	ds_read_b128 v[180:183], v174 offset:34816
	ds_read_b128 v[196:199], v174 offset:35840
	ds_read_b128 v[208:211], v174 offset:36864
	ds_read_b128 v[212:215], v174 offset:37888
	ds_read_b128 v[216:219], v174 offset:38912
	ds_read_b128 v[220:223], v174 offset:39936
	global_load_lds_dwordx4 v[200:201], off
	v_lshl_add_u64 v[200:201], s[38:39], 0, v[146:147]
	s_mov_b32 m0, s52
	s_nop 0
	global_load_lds_dwordx4 v[200:201], off
	s_waitcnt lgkmcnt(8)
	s_barrier
	s_waitcnt lgkmcnt(0)
	s_setprio 1
	v_mfma_f32_16x16x32_bf16 v[140:143], v[16:19], v[154:157], v[140:143]
	v_mfma_f32_16x16x32_bf16 v[136:139], v[64:67], v[154:157], v[136:139]
	v_mfma_f32_16x16x32_bf16 v[124:127], v[16:19], v[180:183], v[124:127]
	v_mfma_f32_16x16x32_bf16 v[120:123], v[64:67], v[180:183], v[120:123]
	v_mfma_f32_16x16x32_bf16 v[108:111], v[16:19], v[208:211], v[108:111]
	v_mfma_f32_16x16x32_bf16 v[104:107], v[64:67], v[208:211], v[104:107]
	v_mfma_f32_16x16x32_bf16 v[92:95], v[16:19], v[216:219], v[92:95]
	v_mfma_f32_16x16x32_bf16 v[88:91], v[64:67], v[216:219], v[88:91]
	v_mfma_f32_16x16x32_bf16 v[140:143], v[20:23], v[176:179], v[140:143]
	v_mfma_f32_16x16x32_bf16 v[136:139], v[68:71], v[176:179], v[136:139]
	v_mfma_f32_16x16x32_bf16 v[124:127], v[20:23], v[196:199], v[124:127]
	v_mfma_f32_16x16x32_bf16 v[120:123], v[68:71], v[196:199], v[120:123]
	v_mfma_f32_16x16x32_bf16 v[108:111], v[20:23], v[212:215], v[108:111]
	v_mfma_f32_16x16x32_bf16 v[104:107], v[68:71], v[212:215], v[104:107]
	v_mfma_f32_16x16x32_bf16 v[92:95], v[20:23], v[220:223], v[92:95]
	v_mfma_f32_16x16x32_bf16 v[88:91], v[68:71], v[220:223], v[88:91]
	s_setprio 0
	s_barrier
	s_mov_b32 m0, s54
	v_add_u32_e32 v168, s58, v172
	v_lshl_add_u64 v[158:159], v[158:159], 0, s[90:91]
	ds_read_b128 v[224:227], v168
	ds_read_b128 v[228:231], v168 offset:1024
	ds_read_b128 v[232:235], v168 offset:2048
	ds_read_b128 v[236:239], v168 offset:3072
	global_load_lds_dwordx4 v[158:159], off
	v_lshl_add_u64 v[158:159], v[166:167], 0, s[90:91]
	s_mov_b32 m0, s55
	s_nop 0
	global_load_lds_dwordx4 v[158:159], off
	s_barrier
	s_waitcnt lgkmcnt(0)
	s_setprio 1
	v_mfma_f32_16x16x32_bf16 v[132:135], v[224:227], v[154:157], v[132:135]
	v_mfma_f32_16x16x32_bf16 v[128:131], v[232:235], v[154:157], v[128:131]
	v_mfma_f32_16x16x32_bf16 v[116:119], v[224:227], v[180:183], v[116:119]
	v_mfma_f32_16x16x32_bf16 v[112:115], v[232:235], v[180:183], v[112:115]
	v_mfma_f32_16x16x32_bf16 v[100:103], v[224:227], v[208:211], v[100:103]
	v_mfma_f32_16x16x32_bf16 v[96:99], v[232:235], v[208:211], v[96:99]
	v_mfma_f32_16x16x32_bf16 v[84:87], v[224:227], v[216:219], v[84:87]
	v_mfma_f32_16x16x32_bf16 v[80:83], v[232:235], v[216:219], v[80:83]
	v_mfma_f32_16x16x32_bf16 v[132:135], v[228:231], v[176:179], v[132:135]
	v_mfma_f32_16x16x32_bf16 v[128:131], v[236:239], v[176:179], v[128:131]
	v_mfma_f32_16x16x32_bf16 v[116:119], v[228:231], v[196:199], v[116:119]
	v_mfma_f32_16x16x32_bf16 v[112:115], v[236:239], v[196:199], v[112:115]
	v_mfma_f32_16x16x32_bf16 v[100:103], v[228:231], v[212:215], v[100:103]
	v_mfma_f32_16x16x32_bf16 v[96:99], v[236:239], v[212:215], v[96:99]
	v_mfma_f32_16x16x32_bf16 v[84:87], v[228:231], v[220:223], v[84:87]
	v_mfma_f32_16x16x32_bf16 v[80:83], v[236:239], v[220:223], v[80:83]
	s_setprio 0
	s_mov_b32 m0, s56
	v_lshl_add_u64 v[158:159], v[170:171], 0, s[90:91]
	s_barrier
	ds_read_b128 v[154:157], v174 offset:49152
	ds_read_b128 v[176:179], v174 offset:50176
	ds_read_b128 v[180:183], v174 offset:51200
	ds_read_b128 v[196:199], v174 offset:52224
	ds_read_b128 v[208:211], v174 offset:53248
	ds_read_b128 v[212:215], v174 offset:54272
	ds_read_b128 v[216:219], v174 offset:55296
	ds_read_b128 v[220:223], v174 offset:56320
	global_load_lds_dwordx4 v[158:159], off
	v_lshl_add_u64 v[158:159], v[184:185], 0, s[90:91]
	s_mov_b32 m0, s57
	s_nop 0
	global_load_lds_dwordx4 v[158:159], off
	s_barrier
; __device__ __forceinline__ float rinv_st(stat_t s, float invn) { return rsqrtf((float)((double)s * (1.0 / 4294967296.0)) * invn + 1e-6f); }
; #define PG8_STAGE(bufoff, gbase, voff) do { _Pragma("unroll") for (int _i = 0; _i < 2; ++_i) \
;         __builtin_amdgcn_global_load_lds((const unsigned*)((const char*)(gbase) + (voff)[_i]), (LAS unsigned*)(lds + (bufoff) + ldsw + _i * 8192), 16, 0, 0); } while (0)
; #define PG8_MMA(ai, bj, At, Bt) do { __builtin_amdgcn_s_setprio(1); _Pragma("unroll") for (int m = 0; m < 4; ++m) _Pragma("unroll") for (int n = 0; n < 2; ++n) _Pragma("unroll") for (int k = 0; k < 2; ++k) \
;         acc[ai][bj][m][n] = __builtin_amdgcn_mfma_f32_16x16x32_bf16(Bt[n][k], At[m][k], acc[ai][bj][m][n], 0, 0, 0); __builtin_amdgcn_s_setprio(0); } while (0)
; template <class Epi>
; __device__ __forceinline__ void gemm_phase(const int TID, const int BID, LAS unsigned char* lds, const Gemm g, const StaticOrder& S, const Epi& E) {
;     ...
;             PG8_BAR; PG8_WAIT_L(0); PG8_MMA(1, 0, At, B0); PG8_BAR; PG8_SCHED;
;             PG8_STAGE(PG8_SB(1, 1), b3 + hstepB, voffB);
;             PG8_WAIT_V(6); PG8_BAR; PG8_MMA(1, 1, At, B1); PG8_BAR;
;         }
;         E(acc, cur, wr, wc, fr, fq);
;     __device__ __forceinline__ void operator()(const f32x4 (&acc)[2][2][4][2], const Unit& u, int wr, int wc, int fr, int fq) const {
;         const int row0 = u.pm * BM + wr * 64 + fr, col0 = u.pn * BM + wc * 32 + 8 * fq;
;         f32x4 bv[2][2];
; #pragma unroll
;         for (int bj = 0; bj < 2; ++bj)
; #pragma unroll
;             for (int n = 0; n < 2; ++n) bv[bj][n] = *(const f32x4*)(bias + col0 + bj * HALF + 4 * n);
;         const bool isv = u.pn >= 8;
; #pragma unroll
;         for (int ai = 0; ai < 2; ++ai)
; #pragma unroll
;             for (int m = 0; m < 4; ++m) {
;                 const int row = row0 + ai * HALF + m * 16; const float r = rinv_st(stats[row], 1.0f / 2048.0f);
;                 bf16_t* rowp = uv + (size_t)row * 4096 + col0; float ss = 0.f;
; #pragma unroll
;                 for (int bj = 0; bj < 2; ++bj) {
;                     const f32x4 v0 = acc[ai][bj][m][0] * r + bv[bj][0], v1 = acc[ai][bj][m][1] * r + bv[bj][1];
;                     const f32x2 a = gelu_pk((f32x2){v0[0], v0[1]}), b = gelu_pk((f32x2){v0[2], v0[3]}), c = gelu_pk((f32x2){v1[0], v1[1]}), d = gelu_pk((f32x2){v1[2], v1[3]});
	s_waitcnt lgkmcnt(0)
	s_setprio 1
	v_mfma_f32_16x16x32_bf16 v[76:79], v[16:19], v[154:157], v[76:79]
	v_mfma_f32_16x16x32_bf16 v[60:63], v[16:19], v[180:183], v[60:63]
	v_mfma_f32_16x16x32_bf16 v[44:47], v[16:19], v[208:211], v[44:47]
	v_mfma_f32_16x16x32_bf16 v[8:11], v[16:19], v[216:219], v[8:11]
	v_mfma_f32_16x16x32_bf16 v[76:79], v[20:23], v[176:179], v[76:79]
	v_mfma_f32_16x16x32_bf16 v[72:75], v[64:67], v[154:157], v[72:75]
	v_mfma_f32_16x16x32_bf16 v[60:63], v[20:23], v[196:199], v[60:63]
	v_mfma_f32_16x16x32_bf16 v[56:59], v[64:67], v[180:183], v[56:59]
	v_mfma_f32_16x16x32_bf16 v[44:47], v[20:23], v[212:215], v[44:47]
	v_mfma_f32_16x16x32_bf16 v[40:43], v[64:67], v[208:211], v[40:43]
	v_mfma_f32_16x16x32_bf16 v[20:23], v[20:23], v[220:223], v[8:11]
	v_mfma_f32_16x16x32_bf16 v[8:11], v[64:67], v[216:219], v[12:15]
	v_mfma_f32_16x16x32_bf16 v[72:75], v[68:71], v[176:179], v[72:75]
	v_mfma_f32_16x16x32_bf16 v[56:59], v[68:71], v[196:199], v[56:59]
	v_mfma_f32_16x16x32_bf16 v[40:43], v[68:71], v[212:215], v[40:43]
	v_mfma_f32_16x16x32_bf16 v[16:19], v[68:71], v[220:223], v[8:11]
	s_setprio 0
	s_barrier
	s_add_u32 s36, s36, 0x80080
	s_addc_u32 s37, s37, 0
	s_mov_b32 m0, s59
	v_lshl_add_u64 v[8:9], s[36:37], 0, v[160:161]
	global_load_lds_dwordx4 v[8:9], off
	v_lshl_add_u64 v[8:9], s[36:37], 0, v[148:149]
	s_mov_b32 m0, s60
	s_nop 0
	global_load_lds_dwordx4 v[8:9], off
	s_waitcnt vmcnt(6)
	s_barrier
	s_setprio 1
	v_mfma_f32_16x16x32_bf16 v[8:11], v[224:227], v[154:157], v[32:35]
	v_mfma_f32_16x16x32_bf16 v[68:71], v[228:231], v[176:179], v[8:11]
	v_mfma_f32_16x16x32_bf16 v[8:11], v[232:235], v[154:157], v[36:39]
	v_mfma_f32_16x16x32_bf16 v[64:67], v[236:239], v[176:179], v[8:11]
	v_mfma_f32_16x16x32_bf16 v[8:11], v[224:227], v[180:183], v[52:55]
	v_mfma_f32_16x16x32_bf16 v[52:55], v[228:231], v[196:199], v[8:11]
	v_mfma_f32_16x16x32_bf16 v[8:11], v[232:235], v[180:183], v[48:51]
	v_mfma_f32_16x16x32_bf16 v[48:51], v[236:239], v[196:199], v[8:11]
	v_mfma_f32_16x16x32_bf16 v[8:11], v[224:227], v[208:211], v[28:31]
	v_mfma_f32_16x16x32_bf16 v[28:31], v[228:231], v[212:215], v[8:11]
	v_mfma_f32_16x16x32_bf16 v[8:11], v[232:235], v[208:211], v[24:27]
	v_mfma_f32_16x16x32_bf16 v[4:7], v[224:227], v[216:219], v[4:7]
	v_mfma_f32_16x16x32_bf16 v[0:3], v[232:235], v[216:219], v[0:3]
	v_mfma_f32_16x16x32_bf16 v[24:27], v[236:239], v[212:215], v[8:11]
	v_mfma_f32_16x16x32_bf16 v[4:7], v[228:231], v[220:223], v[4:7]
	v_mfma_f32_16x16x32_bf16 v[0:3], v[236:239], v[220:223], v[0:3]
	s_setprio 0
	s_add_i32 s31, s31, 2
	s_add_u32 s34, s34, 0x100
	s_addc_u32 s35, s35, 0
	s_add_u32 s23, s23, 0x100
	s_addc_u32 s29, s29, 0
	s_cmp_gt_u32 s31, 29
	s_barrier
	s_cbranch_scc0 .LBB0_864
	v_readlane_b32 s0, v254, 32
	v_readlane_b32 s1, v254, 33
	s_load_dwordx2 s[0:1], s[0:1], 0x50
	v_lshl_or_b32 v154, s30, 8, v173
	v_lshl_add_u32 v156, s28, 8, v169
	v_ashrrev_i32_e32 v155, 31, v154
	v_ashrrev_i32_e32 v157, 31, v156
	s_waitcnt lgkmcnt(0)
	v_lshl_add_u64 v[12:13], v[154:155], 2, s[0:1]
	v_lshl_add_u64 v[158:159], v[156:157], 3, s[16:17]
	global_load_dwordx4 v[32:35], v[12:13], off offset:16
	global_load_dwordx4 v[36:39], v[12:13], off
	global_load_dwordx4 v[8:11], v[12:13], off offset:528
	s_nop 0
	global_load_dwordx4 v[12:15], v[12:13], off offset:512
	s_cmp_gt_i32 s30, 7
	global_load_dwordx2 v[166:167], v[158:159], off
	global_load_dwordx2 v[208:209], v[158:159], off offset:128
	global_load_dwordx2 v[210:211], v[158:159], off offset:256
	global_load_dwordx2 v[212:213], v[158:159], off offset:384
	global_load_dwordx2 v[214:215], v[158:159], off offset:1024
	global_load_dwordx2 v[216:217], v[158:159], off offset:1152
	global_load_dwordx2 v[218:219], v[158:159], off offset:1280
	global_load_dwordx2 v[220:221], v[158:159], off offset:1408
	s_mov_b32 s30, 0xbf38aa3b
	s_cselect_b64 s[0:1], -1, 0
	s_and_b64 s[28:29], s[8:9], s[0:1]
	s_mov_b32 s0, 0xbe11a98e
	s_mov_b32 s4, 0x3e027906
	s_waitcnt vmcnt(0)
	v_cvt_f64_u32_e32 v[170:171], v167
	v_ldexp_f64 v[170:171], v[170:171], 32
	v_cvt_f64_u32_e32 v[166:167], v166
	v_add_f64 v[166:167], v[170:171], v[166:167]
	v_ldexp_f64 v[166:167], v[166:167], s93
	v_cvt_f32_f64_e32 v166, v[166:167]
	v_fmamk_f32 v166, v166, 0x3a000000, v189
	v_cmp_gt_f32_e32 vcc, s78, v166
	v_mul_f32_e32 v167, 0x4b800000, v166
	s_nop 0
	v_cndmask_b32_e32 v166, v166, v167, vcc
	v_rsq_f32_e32 v166, v166
	s_nop 0
	v_mul_f32_e32 v167, 0x45800000, v166
	v_cndmask_b32_e32 v168, v166, v167, vcc
	v_pk_fma_f32 v[170:171], v[140:141], v[168:169], v[36:37] op_sel_hi:[1,0,1]
	v_pk_fma_f32 v[140:141], v[136:137], v[168:169], v[32:33] op_sel_hi:[1,0,1]
	v_and_b32_e32 v137, 0x7fffffff, v171
	v_and_b32_e32 v136, 0x7fffffff, v170
	v_pk_fma_f32 v[136:137], v[136:137], s[64:65], 1.0 op_sel_hi:[1,0,0]
	v_pk_mul_f32 v[180:181], v[170:171], v[170:171]
	v_rcp_f32_e32 v176, v136
	v_rcp_f32_e32 v177, v137
	v_mov_b64_e32 v[136:137], s[80:81]
	v_pk_mul_f32 v[180:181], v[180:181], s[30:31] op_sel_hi:[1,0]
	v_cmp_gt_f32_e32 vcc, 0, v170
	v_pk_fma_f32 v[178:179], v[176:177], s[74:75], v[136:137] op_sel_hi:[1,0,0]
	v_exp_f32_e32 v180, v180
	v_pk_fma_f32 v[178:179], v[176:177], v[178:179], s[86:87] op_sel_hi:[1,1,0]
	v_exp_f32_e32 v181, v181
	v_pk_fma_f32 v[178:179], v[176:177], v[178:179], s[0:1] op_sel_hi:[1,1,0]
	v_pk_fma_f32 v[142:143], v[142:143], v[168:169], v[38:39] op_sel_hi:[1,0,1]
	v_pk_fma_f32 v[178:179], v[176:177], v[178:179], s[4:5] op_sel_hi:[1,1,0]
	v_pk_fma_f32 v[138:139], v[138:139], v[168:169], v[34:35] op_sel_hi:[1,0,1]
	v_pk_mul_f32 v[176:177], v[176:177], v[178:179]
	v_pk_mul_f32 v[178:179], v[142:143], v[142:143]
	v_pk_mul_f32 v[176:177], v[180:181], v[176:177]
; __device__ __forceinline__ unsigned cvt_pk_bf16(float lo, float hi) { unsigned r; asm volatile("v_cvt_pk_bf16_f32 %0, %1, %2" : "=v"(r) : "v"(lo), "v"(hi)); return r; }
; __device__ __forceinline__ f32x2 gelu_pk(f32x2 v) {
;     const f32x2 av = __builtin_elementwise_abs(v), d = av * 0.2316418882f + 1.0f;
;     f32x2 t; t.x = __builtin_amdgcn_rcpf(d.x); t.y = __builtin_amdgcn_rcpf(d.y);
;     f32x2 q = t * 0.5307027145f + (-0.7265760135f); q = q * t + 0.7107068705f; q = q * t + (-0.142248368f); q = q * t + 0.127414796f; q = q * t;
;     const f32x2 s = (v * v) * (-0.72134752044f);
;     f32x2 e; e.x = __builtin_amdgcn_exp2f(s.x); e.y = __builtin_amdgcn_exp2f(s.y);
;     const f32x2 m = v * (q * e), r = v - m;
;     f32x2 o; o.x = v.x < 0.f ? m.x : r.x; o.y = v.y < 0.f ? m.y : r.y; return o;
; }
;     __device__ __forceinline__ void operator()(const f32x4 (&acc)[2][2][4][2], const Unit& u, int wr, int wc, int fr, int fq) const {
;     ...
;                 for (int bj = 0; bj < 2; ++bj) {
;                     const f32x4 v0 = acc[ai][bj][m][0] * r + bv[bj][0], v1 = acc[ai][bj][m][1] * r + bv[bj][1];
;                     const f32x2 a = gelu_pk((f32x2){v0[0], v0[1]}), b = gelu_pk((f32x2){v0[2], v0[3]}), c = gelu_pk((f32x2){v1[0], v1[1]}), d = gelu_pk((f32x2){v1[2], v1[3]});
;                     ss += a.x * a.x + a.y * a.y + b.x * b.x + b.y * b.y + c.x * c.x + c.y * c.y + d.x * d.x + d.y * d.y;
;                     u32x4 w; w.x = cvt_pk_bf16(a.x, a.y); w.y = cvt_pk_bf16(b.x, b.y); w.z = cvt_pk_bf16(c.x, c.y); w.w = cvt_pk_bf16(d.x, d.y);
;                     *(u32x4*)(rowp + bj * HALF) = w;
	v_pk_mul_f32 v[178:179], v[178:179], s[30:31] op_sel_hi:[1,0]
	v_pk_mul_f32 v[180:181], v[170:171], v[176:177]
	v_pk_fma_f32 v[176:177], v[170:171], v[176:177], v[170:171] neg_lo:[1,0,0] neg_hi:[1,0,0]
	v_exp_f32_e32 v178, v178
	v_cndmask_b32_e32 v170, v176, v180, vcc
	v_cmp_gt_f32_e32 vcc, 0, v171
	v_and_b32_e32 v176, 0x7fffffff, v142
	v_exp_f32_e32 v179, v179
	v_cndmask_b32_e32 v171, v177, v181, vcc
	v_and_b32_e32 v177, 0x7fffffff, v143
	v_pk_fma_f32 v[176:177], v[176:177], s[64:65], 1.0 op_sel_hi:[1,0,0]
	v_cmp_gt_f32_e32 vcc, 0, v142
	v_rcp_f32_e32 v176, v176
	v_rcp_f32_e32 v177, v177
	v_lshlrev_b64 v[166:167], 13, v[156:157]
	v_lshl_add_u64 v[166:167], s[14:15], 0, v[166:167]
	v_lshl_add_u64 v[166:167], v[154:155], 1, v[166:167]
	v_pk_fma_f32 v[180:181], v[176:177], s[74:75], v[136:137] op_sel_hi:[1,0,0]
	v_pk_fma_f32 v[132:133], v[132:133], v[168:169], v[12:13] op_sel_hi:[1,0,1]
	v_pk_fma_f32 v[180:181], v[176:177], v[180:181], s[86:87] op_sel_hi:[1,1,0]
	v_pk_fma_f32 v[134:135], v[134:135], v[168:169], v[14:15] op_sel_hi:[1,0,1]
	v_pk_fma_f32 v[180:181], v[176:177], v[180:181], s[0:1] op_sel_hi:[1,1,0]
	v_pk_fma_f32 v[128:129], v[128:129], v[168:169], v[8:9] op_sel_hi:[1,0,1]
	v_pk_fma_f32 v[180:181], v[176:177], v[180:181], s[4:5] op_sel_hi:[1,1,0]
	v_pk_fma_f32 v[130:131], v[130:131], v[168:169], v[10:11] op_sel_hi:[1,0,1]
	v_pk_mul_f32 v[176:177], v[176:177], v[180:181]
	s_nop 0
	v_pk_mul_f32 v[176:177], v[178:179], v[176:177]
	s_nop 0
	v_pk_mul_f32 v[178:179], v[142:143], v[176:177]
	v_pk_fma_f32 v[176:177], v[142:143], v[176:177], v[142:143] neg_lo:[1,0,0] neg_hi:[1,0,0]
	v_and_b32_e32 v142, 0x7fffffff, v140
	v_cndmask_b32_e32 v175, v176, v178, vcc
	v_cmp_gt_f32_e32 vcc, 0, v143
	v_and_b32_e32 v143, 0x7fffffff, v141
	v_pk_fma_f32 v[142:143], v[142:143], s[64:65], 1.0 op_sel_hi:[1,0,0]
	v_cndmask_b32_e32 v180, v177, v179, vcc
	v_rcp_f32_e32 v142, v142
	v_rcp_f32_e32 v143, v143
	v_pk_mul_f32 v[178:179], v[140:141], v[140:141]
	v_cmp_gt_f32_e32 vcc, 0, v140
	v_pk_mul_f32 v[178:179], v[178:179], s[30:31] op_sel_hi:[1,0]
	v_pk_fma_f32 v[176:177], v[142:143], s[74:75], v[136:137] op_sel_hi:[1,0,0]
	v_exp_f32_e32 v178, v178
	v_pk_fma_f32 v[176:177], v[142:143], v[176:177], s[86:87] op_sel_hi:[1,1,0]
	v_exp_f32_e32 v179, v179
	v_pk_fma_f32 v[176:177], v[142:143], v[176:177], s[0:1] op_sel_hi:[1,1,0]
	s_nop 0
	v_pk_fma_f32 v[176:177], v[142:143], v[176:177], s[4:5] op_sel_hi:[1,1,0]
	s_nop 0
	v_pk_mul_f32 v[142:143], v[142:143], v[176:177]
	v_pk_mul_f32 v[176:177], v[138:139], v[138:139]
	v_pk_mul_f32 v[142:143], v[178:179], v[142:143]
	s_nop 0
	v_pk_mul_f32 v[178:179], v[140:141], v[142:143]
	v_pk_fma_f32 v[142:143], v[140:141], v[142:143], v[140:141] neg_lo:[1,0,0] neg_hi:[1,0,0]
	v_and_b32_e32 v140, 0x7fffffff, v138
	v_cndmask_b32_e32 v178, v142, v178, vcc
	v_cmp_gt_f32_e32 vcc, 0, v141
	v_and_b32_e32 v141, 0x7fffffff, v139
	v_pk_fma_f32 v[140:141], v[140:141], s[64:65], 1.0 op_sel_hi:[1,0,0]
	v_cndmask_b32_e32 v179, v143, v179, vcc
	v_rcp_f32_e32 v140, v140
	v_rcp_f32_e32 v141, v141
	v_cmp_gt_f32_e32 vcc, 0, v138
	v_pk_fma_f32 v[142:143], v[140:141], s[74:75], v[136:137] op_sel_hi:[1,0,0]
	s_nop 0
	v_pk_fma_f32 v[142:143], v[140:141], v[142:143], s[86:87] op_sel_hi:[1,1,0]
	s_nop 0
	v_pk_fma_f32 v[142:143], v[140:141], v[142:143], s[0:1] op_sel_hi:[1,1,0]
	s_nop 0
	v_pk_fma_f32 v[142:143], v[140:141], v[142:143], s[4:5] op_sel_hi:[1,1,0]
	s_nop 0
	v_pk_mul_f32 v[140:141], v[140:141], v[142:143]
	v_pk_mul_f32 v[142:143], v[176:177], s[30:31] op_sel_hi:[1,0]
	v_mul_f32_e32 v176, v171, v171
	v_exp_f32_e32 v142, v142
	v_exp_f32_e32 v143, v143
	v_fmac_f32_e32 v176, v170, v170
	v_fmac_f32_e32 v176, v175, v175
	v_fmac_f32_e32 v176, v180, v180
	v_pk_mul_f32 v[140:141], v[142:143], v[140:141]
	v_fmac_f32_e32 v176, v178, v178
	v_pk_mul_f32 v[142:143], v[138:139], v[140:141]
	v_pk_fma_f32 v[140:141], v[138:139], v[140:141], v[138:139] neg_lo:[1,0,0] neg_hi:[1,0,0]
	v_fmac_f32_e32 v176, v179, v179
	v_cndmask_b32_e32 v142, v140, v142, vcc
	v_cmp_gt_f32_e32 vcc, 0, v139
	v_fmac_f32_e32 v176, v142, v142
	v_cvt_pk_bf16_f32 v138, v170, v171
	v_cvt_pk_bf16_f32 v139, v175, v180
	v_cvt_pk_bf16_f32 v140, v178, v179
	s_nop 0
	v_cndmask_b32_e32 v141, v141, v143, vcc
	v_fmac_f32_e32 v176, v141, v141
	v_cvt_pk_bf16_f32 v141, v142, v141
	global_store_dwordx4 v[166:167], v[138:141], off
	v_pk_mul_f32 v[142:143], v[132:133], v[132:133]
	v_cmp_gt_f32_e32 vcc, 0, v132
	v_and_b32_e32 v139, 0x7fffffff, v133
	v_and_b32_e32 v138, 0x7fffffff, v132
	v_pk_fma_f32 v[138:139], v[138:139], s[64:65], 1.0 op_sel_hi:[1,0,0]
	v_pk_mul_f32 v[142:143], v[142:143], s[30:31] op_sel_hi:[1,0]
	v_rcp_f32_e32 v138, v138
	v_rcp_f32_e32 v139, v139
	v_exp_f32_e32 v142, v142
	v_exp_f32_e32 v143, v143
	v_pk_fma_f32 v[140:141], v[138:139], s[74:75], v[136:137] op_sel_hi:[1,0,0]
	s_nop 0
	v_pk_fma_f32 v[140:141], v[138:139], v[140:141], s[86:87] op_sel_hi:[1,1,0]
	s_nop 0
	v_pk_fma_f32 v[140:141], v[138:139], v[140:141], s[0:1] op_sel_hi:[1,1,0]
	s_nop 0
	v_pk_fma_f32 v[140:141], v[138:139], v[140:141], s[4:5] op_sel_hi:[1,1,0]
	s_nop 0
	v_pk_mul_f32 v[138:139], v[138:139], v[140:141]
; __device__ __forceinline__ unsigned cvt_pk_bf16(float lo, float hi) { unsigned r; asm volatile("v_cvt_pk_bf16_f32 %0, %1, %2" : "=v"(r) : "v"(lo), "v"(hi)); return r; }
; __device__ __forceinline__ void stat_add(stat_t* p, float ss) { __hip_atomic_fetch_add(p, (stat_t)((double)ss * 4294967296.0), __ATOMIC_RELAXED, __HIP_MEMORY_SCOPE_AGENT); }
;     __device__ __forceinline__ void operator()(const f32x4 (&acc)[2][2][4][2], const Unit& u, int wr, int wc, int fr, int fq) const {
;     ...
;                 for (int bj = 0; bj < 2; ++bj) {
;                     const f32x4 v0 = acc[ai][bj][m][0] * r + bv[bj][0], v1 = acc[ai][bj][m][1] * r + bv[bj][1];
;                     const f32x2 a = gelu_pk((f32x2){v0[0], v0[1]}), b = gelu_pk((f32x2){v0[2], v0[3]}), c = gelu_pk((f32x2){v1[0], v1[1]}), d = gelu_pk((f32x2){v1[2], v1[3]});
;                     ss += a.x * a.x + a.y * a.y + b.x * b.x + b.y * b.y + c.x * c.x + c.y * c.y + d.x * d.x + d.y * d.y;
;                     u32x4 w; w.x = cvt_pk_bf16(a.x, a.y); w.y = cvt_pk_bf16(b.x, b.y); w.z = cvt_pk_bf16(c.x, c.y); w.w = cvt_pk_bf16(d.x, d.y);
;                     *(u32x4*)(rowp + bj * HALF) = w;
;                 }
;                 ss += __shfl_xor(ss, 16); ss += __shfl_xor(ss, 32);
;                 if (isv && fq == 0) stat_add(stats_v + row, ss);
	v_pk_mul_f32 v[140:141], v[134:135], v[134:135]
	v_pk_mul_f32 v[138:139], v[142:143], v[138:139]
	s_nop 0
	v_pk_mul_f32 v[142:143], v[132:133], v[138:139]
	v_pk_fma_f32 v[138:139], v[132:133], v[138:139], v[132:133] neg_lo:[1,0,0] neg_hi:[1,0,0]
	v_and_b32_e32 v132, 0x7fffffff, v134
	v_cndmask_b32_e32 v142, v138, v142, vcc
	v_cmp_gt_f32_e32 vcc, 0, v133
	v_and_b32_e32 v133, 0x7fffffff, v135
	v_pk_fma_f32 v[132:133], v[132:133], s[64:65], 1.0 op_sel_hi:[1,0,0]
	v_cndmask_b32_e32 v143, v139, v143, vcc
	v_rcp_f32_e32 v132, v132
	v_rcp_f32_e32 v133, v133
	v_cmp_gt_f32_e32 vcc, 0, v134
	v_pk_fma_f32 v[138:139], v[132:133], s[74:75], v[136:137] op_sel_hi:[1,0,0]
	s_nop 0
	v_pk_fma_f32 v[138:139], v[132:133], v[138:139], s[86:87] op_sel_hi:[1,1,0]
	s_nop 0
	v_pk_fma_f32 v[138:139], v[132:133], v[138:139], s[0:1] op_sel_hi:[1,1,0]
	s_nop 0
	v_pk_fma_f32 v[138:139], v[132:133], v[138:139], s[4:5] op_sel_hi:[1,1,0]
	s_nop 0
	v_pk_mul_f32 v[132:133], v[132:133], v[138:139]
	v_pk_mul_f32 v[138:139], v[140:141], s[30:31] op_sel_hi:[1,0]
	s_nop 0
	v_exp_f32_e32 v138, v138
	v_exp_f32_e32 v139, v139
	s_nop 0
	v_pk_mul_f32 v[132:133], v[138:139], v[132:133]
	s_nop 0
	v_pk_mul_f32 v[138:139], v[134:135], v[132:133]
	v_pk_fma_f32 v[132:133], v[134:135], v[132:133], v[134:135] neg_lo:[1,0,0] neg_hi:[1,0,0]
	s_nop 0
	v_cndmask_b32_e32 v140, v132, v138, vcc
	v_cmp_gt_f32_e32 vcc, 0, v135
	v_and_b32_e32 v132, 0x7fffffff, v128
	s_nop 0
	v_cndmask_b32_e32 v141, v133, v139, vcc
	v_and_b32_e32 v133, 0x7fffffff, v129
	v_pk_fma_f32 v[132:133], v[132:133], s[64:65], 1.0 op_sel_hi:[1,0,0]
	v_pk_mul_f32 v[138:139], v[128:129], v[128:129]
	v_rcp_f32_e32 v132, v132
	v_rcp_f32_e32 v133, v133
	v_pk_mul_f32 v[138:139], v[138:139], s[30:31] op_sel_hi:[1,0]
	v_cmp_gt_f32_e32 vcc, 0, v128
	v_exp_f32_e32 v138, v138
	v_pk_fma_f32 v[134:135], v[132:133], s[74:75], v[136:137] op_sel_hi:[1,0,0]
	v_exp_f32_e32 v139, v139
	v_pk_fma_f32 v[134:135], v[132:133], v[134:135], s[86:87] op_sel_hi:[1,1,0]
	s_nop 0
	v_pk_fma_f32 v[134:135], v[132:133], v[134:135], s[0:1] op_sel_hi:[1,1,0]
	s_nop 0
	v_pk_fma_f32 v[134:135], v[132:133], v[134:135], s[4:5] op_sel_hi:[1,1,0]
	s_nop 0
	v_pk_mul_f32 v[132:133], v[132:133], v[134:135]
	v_pk_mul_f32 v[134:135], v[130:131], v[130:131]
	v_pk_mul_f32 v[132:133], v[138:139], v[132:133]
	s_nop 0
	v_pk_mul_f32 v[138:139], v[128:129], v[132:133]
	v_pk_fma_f32 v[132:133], v[128:129], v[132:133], v[128:129] neg_lo:[1,0,0] neg_hi:[1,0,0]
	v_and_b32_e32 v128, 0x7fffffff, v130
	v_cndmask_b32_e32 v138, v132, v138, vcc
	v_cmp_gt_f32_e32 vcc, 0, v129
	v_and_b32_e32 v129, 0x7fffffff, v131
	v_pk_fma_f32 v[128:129], v[128:129], s[64:65], 1.0 op_sel_hi:[1,0,0]
	v_cndmask_b32_e32 v139, v133, v139, vcc
	v_rcp_f32_e32 v128, v128
	v_rcp_f32_e32 v129, v129
	v_cmp_gt_f32_e32 vcc, 0, v130
	v_pk_fma_f32 v[132:133], v[128:129], s[74:75], v[136:137] op_sel_hi:[1,0,0]
	s_nop 0
	v_pk_fma_f32 v[132:133], v[128:129], v[132:133], s[86:87] op_sel_hi:[1,1,0]
	s_nop 0
	v_pk_fma_f32 v[132:133], v[128:129], v[132:133], s[0:1] op_sel_hi:[1,1,0]
	s_nop 0
	v_pk_fma_f32 v[132:133], v[128:129], v[132:133], s[4:5] op_sel_hi:[1,1,0]
	s_nop 0
	v_pk_mul_f32 v[128:129], v[128:129], v[132:133]
	v_pk_mul_f32 v[132:133], v[134:135], s[30:31] op_sel_hi:[1,0]
	s_nop 0
	v_exp_f32_e32 v132, v132
	v_exp_f32_e32 v133, v133
	s_nop 0
	v_pk_mul_f32 v[128:129], v[132:133], v[128:129]
	s_nop 0
	v_pk_mul_f32 v[132:133], v[130:131], v[128:129]
	v_pk_fma_f32 v[128:129], v[130:131], v[128:129], v[130:131] neg_lo:[1,0,0] neg_hi:[1,0,0]
	s_nop 0
	v_cndmask_b32_e32 v132, v128, v132, vcc
	v_mul_f32_e32 v128, v143, v143
	v_fmac_f32_e32 v128, v142, v142
	v_fmac_f32_e32 v128, v140, v140
	v_fmac_f32_e32 v128, v141, v141
	v_fmac_f32_e32 v128, v138, v138
	v_cmp_gt_f32_e32 vcc, 0, v131
	v_fmac_f32_e32 v128, v139, v139
	v_fmac_f32_e32 v128, v132, v132
	v_cndmask_b32_e32 v131, v129, v133, vcc
	v_fmac_f32_e32 v128, v131, v131
	v_add_f32_e32 v134, v176, v128
	v_cvt_pk_bf16_f32 v128, v142, v143
	v_cvt_pk_bf16_f32 v129, v140, v141
	v_cvt_pk_bf16_f32 v130, v138, v139
	v_cvt_pk_bf16_f32 v131, v132, v131
	global_store_dwordx4 v[166:167], v[128:131], off offset:256
	s_nop 1
	v_and_b32_e32 v129, 64, v190
	v_xor_b32_e32 v128, 16, v190
	v_add_u32_e32 v129, 64, v129
	v_cmp_lt_i32_e32 vcc, v128, v129
	v_xor_b32_e32 v130, 32, v190
	s_nop 0
	v_cndmask_b32_e32 v128, v190, v128, vcc
	v_lshlrev_b32_e32 v133, 2, v128
	ds_bpermute_b32 v128, v133, v134
	v_cmp_lt_i32_e32 vcc, v130, v129
	s_waitcnt lgkmcnt(0)
	v_add_f32_e32 v128, v134, v128
	v_cndmask_b32_e32 v129, v190, v130, vcc
	v_lshlrev_b32_e32 v134, 2, v129
	ds_bpermute_b32 v129, v134, v128
	s_and_saveexec_b64 s[30:31], s[28:29]
	s_cbranch_execz .LBB0_867
	s_waitcnt lgkmcnt(0)
	v_add_f32_e32 v128, v128, v129
	v_cvt_f64_f32_e32 v[128:129], v128
	v_ldexp_f64 v[128:129], v[128:129], 32
	v_trunc_f64_e32 v[128:129], v[128:129]
	v_ldexp_f64 v[136:137], v[128:129], s93
	v_floor_f64_e32 v[136:137], v[136:137]
	v_fmac_f64_e32 v[128:129], 0xc1f00000, v[136:137]
	v_lshl_add_u64 v[130:131], v[156:157], 3, s[18:19]
	v_cvt_u32_f64_e32 v128, v[128:129]
	v_cvt_u32_f64_e32 v129, v[136:137]
	global_atomic_add_x2 v[130:131], v[128:129], off

; #define PG8_STAGE(bufoff, gbase, voff) do { _Pragma("unroll") for (int _i = 0; _i < 2; ++_i) \
;         __builtin_amdgcn_global_load_lds((const unsigned*)((const char*)(gbase) + (voff)[_i]), (LAS unsigned*)(lds + (bufoff) + ldsw + _i * 8192), 16, 0, 0); } while (0)
; #define PG8_LDA(dst, b, h) do { _Pragma("unroll") for (int m = 0; m < 4; ++m) _Pragma("unroll") for (int k = 0; k < 2; ++k) dst[m][k] = *(const LAS bf16x8*)(lds + PG8_SA(b, h) + aoff + m * 2048 + k * 1024); } while (0)
; #define PG8_LDB(dst, b, h) do { _Pragma("unroll") for (int n = 0; n < 2; ++n) _Pragma("unroll") for (int k = 0; k < 2; ++k) dst[n][k] = *(const LAS bf16x8*)(lds + PG8_SB(b, h) + boff + n * 2048 + k * 1024); } while (0)
; #define PG8_MMA(ai, bj, At, Bt) do { __builtin_amdgcn_s_setprio(1); _Pragma("unroll") for (int m = 0; m < 4; ++m) _Pragma("unroll") for (int n = 0; n < 2; ++n) _Pragma("unroll") for (int k = 0; k < 2; ++k) \
;         acc[ai][bj][m][n] = __builtin_amdgcn_mfma_f32_16x16x32_bf16(Bt[n][k], At[m][k], acc[ai][bj][m][n], 0, 0, 0); __builtin_amdgcn_s_setprio(0); } while (0)
; #define PG8_WAIT_V(n) asm volatile("s_waitcnt vmcnt(" #n ")" ::: "memory")
; #define PG8_WAIT_L(n) asm volatile("s_waitcnt lgkmcnt(" #n ")" ::: "memory")
; template <class Epi>
; __device__ __forceinline__ void gemm_phase(const int TID, const int BID, LAS unsigned char* lds, const Gemm g, const StaticOrder& S, const Epi& E) {
;     ...
;         for (int t = 0; t < nt; t += 2) {
;             const bool last = (t == nt - 2);
;             const char* a1 = cA + (size_t)(t + 1) * kstep;
;             const char* a2 = last ? nA : cA + (size_t)(t + 2) * kstep; const char* b2 = last ? nB : cB + (size_t)(t + 2) * kstep;
;             const char* a3 = a2 + kstep; const char* b3 = b2 + kstep;
;             PG8_LDB(B0, 0, 0); PG8_SCHED; PG8_LDA(At, 0, 0); PG8_STAGE(PG8_SA(1, 1), a1 + hstepA, voffA);
;             PG8_WAIT_L(8); PG8_BAR; PG8_WAIT_L(0); PG8_MMA(0, 0, At, B0); PG8_BAR; PG8_SCHED;
;             PG8_LDB(B1, 0, 1); PG8_STAGE(PG8_SB(0, 0), b2, voffB);
;             PG8_BAR; PG8_WAIT_L(0); PG8_MMA(0, 1, At, B1); PG8_BAR;
;             PG8_LDA(At, 0, 1); PG8_STAGE(PG8_SA(0, 0), a2, voffA);
;             PG8_BAR; PG8_WAIT_L(0); PG8_MMA(1, 0, At, B0); PG8_BAR; PG8_SCHED;
;             PG8_STAGE(PG8_SB(0, 1), b2 + hstepB, voffB);
;             PG8_WAIT_V(6); PG8_BAR; PG8_MMA(1, 1, At, B1); PG8_BAR;
.LBB0_925:
	v_add_u32_e32 v154, s31, v147
	ds_read_b128 v[138:141], v154
	ds_read_b128 v[142:145], v154 offset:1024
	ds_read_b128 v[150:153], v154 offset:2048
	ds_read_b128 v[154:157], v154 offset:3072
	s_add_u32 s36, s34, 0xfff80080
	s_addc_u32 s37, s35, -1
	s_cmp_eq_u32 s64, 28
	s_cselect_b32 s39, s1, s37
	s_cselect_b32 s38, s4, s36
	s_cselect_b32 s37, s17, s23
	s_cselect_b32 s36, s19, s22
	v_lshl_add_u64 v[158:159], s[34:35], 0, v[134:135]
	s_add_i32 m0, s48, 0xc000
	ds_read_b128 v[166:169], v149
	ds_read_b128 v[170:173], v149 offset:1024
	ds_read_b128 v[174:177], v149 offset:2048
	ds_read_b128 v[178:181], v149 offset:3072
	ds_read_b128 v[182:185], v149 offset:4096
	ds_read_b128 v[196:199], v149 offset:5120
	ds_read_b128 v[208:211], v149 offset:6144
	ds_read_b128 v[212:215], v149 offset:7168
	global_load_lds_dwordx4 v[158:159], off
	v_lshl_add_u64 v[158:159], s[34:35], 0, v[136:137]
	s_add_i32 m0, s48, 0xe000
	s_nop 0
	global_load_lds_dwordx4 v[158:159], off
	s_waitcnt lgkmcnt(8)
	s_barrier
	s_waitcnt lgkmcnt(0)
	s_setprio 1
	v_mfma_f32_16x16x32_bf16 v[124:127], v[138:141], v[166:169], v[124:127]
	v_mfma_f32_16x16x32_bf16 v[120:123], v[150:153], v[166:169], v[120:123]
	v_mfma_f32_16x16x32_bf16 v[108:111], v[138:141], v[174:177], v[108:111]
	v_mfma_f32_16x16x32_bf16 v[104:107], v[150:153], v[174:177], v[104:107]
	v_mfma_f32_16x16x32_bf16 v[92:95], v[138:141], v[182:185], v[92:95]
	v_mfma_f32_16x16x32_bf16 v[88:91], v[150:153], v[182:185], v[88:91]
	v_mfma_f32_16x16x32_bf16 v[76:79], v[138:141], v[208:211], v[76:79]
	v_mfma_f32_16x16x32_bf16 v[72:75], v[150:153], v[208:211], v[72:75]
	v_mfma_f32_16x16x32_bf16 v[124:127], v[142:145], v[170:173], v[124:127]
	v_mfma_f32_16x16x32_bf16 v[120:123], v[154:157], v[170:173], v[120:123]
	v_mfma_f32_16x16x32_bf16 v[108:111], v[142:145], v[178:181], v[108:111]
	v_mfma_f32_16x16x32_bf16 v[104:107], v[154:157], v[178:181], v[104:107]
	v_mfma_f32_16x16x32_bf16 v[92:95], v[142:145], v[196:199], v[92:95]
	v_mfma_f32_16x16x32_bf16 v[88:91], v[154:157], v[196:199], v[88:91]
	v_mfma_f32_16x16x32_bf16 v[76:79], v[142:145], v[212:215], v[76:79]
	v_mfma_f32_16x16x32_bf16 v[72:75], v[154:157], v[212:215], v[72:75]
	s_setprio 0
	s_barrier
	v_add_u32_e32 v158, s50, v147
	s_mov_b32 m0, s46
	ds_read_b128 v[216:219], v158
	ds_read_b128 v[220:223], v158 offset:1024
	ds_read_b128 v[224:227], v158 offset:2048
	ds_read_b128 v[228:231], v158 offset:3072
	v_lshl_add_u64 v[158:159], s[36:37], 0, v[160:161]
	global_load_lds_dwordx4 v[158:159], off
	v_lshl_add_u64 v[200:201], s[36:37], 0, v[132:133]
	s_mov_b32 m0, s47
	s_nop 0
	global_load_lds_dwordx4 v[200:201], off
	s_barrier
	s_waitcnt lgkmcnt(0)
	s_setprio 1
	v_mfma_f32_16x16x32_bf16 v[116:119], v[216:219], v[166:169], v[116:119]
	v_mfma_f32_16x16x32_bf16 v[112:115], v[224:227], v[166:169], v[112:115]
	v_mfma_f32_16x16x32_bf16 v[100:103], v[216:219], v[174:177], v[100:103]
	v_mfma_f32_16x16x32_bf16 v[96:99], v[224:227], v[174:177], v[96:99]
	v_mfma_f32_16x16x32_bf16 v[84:87], v[216:219], v[182:185], v[84:87]
	v_mfma_f32_16x16x32_bf16 v[80:83], v[224:227], v[182:185], v[80:83]
	v_mfma_f32_16x16x32_bf16 v[68:71], v[216:219], v[208:211], v[68:71]
	v_mfma_f32_16x16x32_bf16 v[64:67], v[224:227], v[208:211], v[64:67]
	v_mfma_f32_16x16x32_bf16 v[116:119], v[220:223], v[170:173], v[116:119]
	v_mfma_f32_16x16x32_bf16 v[112:115], v[228:231], v[170:173], v[112:115]
	v_mfma_f32_16x16x32_bf16 v[100:103], v[220:223], v[178:181], v[100:103]
	v_mfma_f32_16x16x32_bf16 v[96:99], v[228:231], v[178:181], v[96:99]
	v_mfma_f32_16x16x32_bf16 v[84:87], v[220:223], v[196:199], v[84:87]
	v_mfma_f32_16x16x32_bf16 v[80:83], v[228:231], v[196:199], v[80:83]
	v_mfma_f32_16x16x32_bf16 v[68:71], v[220:223], v[212:215], v[68:71]
	v_mfma_f32_16x16x32_bf16 v[64:67], v[228:231], v[212:215], v[64:67]
	s_setprio 0
	s_mov_b32 m0, s48
	v_lshl_add_u64 v[232:233], s[38:39], 0, v[128:129]
	s_barrier
	ds_read_b128 v[166:169], v149 offset:16384
	ds_read_b128 v[170:173], v149 offset:17408
	ds_read_b128 v[174:177], v149 offset:18432
	ds_read_b128 v[178:181], v149 offset:19456
	ds_read_b128 v[182:185], v149 offset:20480
	ds_read_b128 v[196:199], v149 offset:21504
	ds_read_b128 v[208:211], v149 offset:22528
	ds_read_b128 v[212:215], v149 offset:23552
	global_load_lds_dwordx4 v[232:233], off
	v_lshl_add_u64 v[234:235], s[38:39], 0, v[130:131]
	s_mov_b32 m0, s49
	s_nop 0
	global_load_lds_dwordx4 v[234:235], off
	s_barrier
	s_waitcnt lgkmcnt(0)
	s_setprio 1
	v_mfma_f32_16x16x32_bf16 v[60:63], v[138:141], v[166:169], v[60:63]
	v_mfma_f32_16x16x32_bf16 v[56:59], v[150:153], v[166:169], v[56:59]
	v_mfma_f32_16x16x32_bf16 v[44:47], v[138:141], v[174:177], v[44:47]
	v_mfma_f32_16x16x32_bf16 v[40:43], v[150:153], v[174:177], v[40:43]
	v_mfma_f32_16x16x32_bf16 v[28:31], v[138:141], v[182:185], v[28:31]
	v_mfma_f32_16x16x32_bf16 v[24:27], v[150:153], v[182:185], v[24:27]
	v_mfma_f32_16x16x32_bf16 v[12:15], v[138:141], v[208:211], v[12:15]
	v_mfma_f32_16x16x32_bf16 v[8:11], v[150:153], v[208:211], v[8:11]
	v_mfma_f32_16x16x32_bf16 v[60:63], v[142:145], v[170:173], v[60:63]
	v_mfma_f32_16x16x32_bf16 v[56:59], v[154:157], v[170:173], v[56:59]
	v_mfma_f32_16x16x32_bf16 v[44:47], v[142:145], v[178:181], v[44:47]
	v_mfma_f32_16x16x32_bf16 v[40:43], v[154:157], v[178:181], v[40:43]
	v_mfma_f32_16x16x32_bf16 v[28:31], v[142:145], v[196:199], v[28:31]
	v_mfma_f32_16x16x32_bf16 v[24:27], v[154:157], v[196:199], v[24:27]
	v_mfma_f32_16x16x32_bf16 v[12:15], v[142:145], v[212:215], v[12:15]
	v_mfma_f32_16x16x32_bf16 v[8:11], v[154:157], v[212:215], v[8:11]
	s_setprio 0
	s_barrier
; #define PG8_STAGE(bufoff, gbase, voff) do { _Pragma("unroll") for (int _i = 0; _i < 2; ++_i) \
;         __builtin_amdgcn_global_load_lds((const unsigned*)((const char*)(gbase) + (voff)[_i]), (LAS unsigned*)(lds + (bufoff) + ldsw + _i * 8192), 16, 0, 0); } while (0)
; #define PG8_LDA(dst, b, h) do { _Pragma("unroll") for (int m = 0; m < 4; ++m) _Pragma("unroll") for (int k = 0; k < 2; ++k) dst[m][k] = *(const LAS bf16x8*)(lds + PG8_SA(b, h) + aoff + m * 2048 + k * 1024); } while (0)
; #define PG8_LDB(dst, b, h) do { _Pragma("unroll") for (int n = 0; n < 2; ++n) _Pragma("unroll") for (int k = 0; k < 2; ++k) dst[n][k] = *(const LAS bf16x8*)(lds + PG8_SB(b, h) + boff + n * 2048 + k * 1024); } while (0)
; #define PG8_MMA(ai, bj, At, Bt) do { __builtin_amdgcn_s_setprio(1); _Pragma("unroll") for (int m = 0; m < 4; ++m) _Pragma("unroll") for (int n = 0; n < 2; ++n) _Pragma("unroll") for (int k = 0; k < 2; ++k) \
;         acc[ai][bj][m][n] = __builtin_amdgcn_mfma_f32_16x16x32_bf16(Bt[n][k], At[m][k], acc[ai][bj][m][n], 0, 0, 0); __builtin_amdgcn_s_setprio(0); } while (0)
; #define PG8_WAIT_V(n) asm volatile("s_waitcnt vmcnt(" #n ")" ::: "memory")
; #define PG8_WAIT_L(n) asm volatile("s_waitcnt lgkmcnt(" #n ")" ::: "memory")
; #define PG8_BAR __builtin_amdgcn_s_barrier()
; #define PG8_SCHED __builtin_amdgcn_sched_barrier(0)
; template <class Epi>
; __device__ __forceinline__ void gemm_phase(const int TID, const int BID, LAS unsigned char* lds, const Gemm g, const StaticOrder& S, const Epi& E) {
;     ...
;             PG8_STAGE(PG8_SB(0, 1), b2 + hstepB, voffB);
;             PG8_WAIT_V(6); PG8_BAR; PG8_MMA(1, 1, At, B1); PG8_BAR;
;             PG8_LDB(B0, 1, 0); PG8_SCHED; PG8_LDA(At, 1, 0); PG8_STAGE(PG8_SA(0, 1), a2 + hstepA, voffA);
;             PG8_WAIT_L(8); PG8_BAR; PG8_WAIT_L(0); PG8_MMA(0, 0, At, B0); PG8_BAR; PG8_SCHED;
;             PG8_LDB(B1, 1, 1); PG8_STAGE(PG8_SB(1, 0), b3, voffB);
;             PG8_BAR; PG8_WAIT_L(0); PG8_MMA(0, 1, At, B1); PG8_BAR;
;             PG8_LDA(At, 1, 1); PG8_STAGE(PG8_SA(1, 0), a3, voffA);
;             PG8_BAR; PG8_WAIT_L(0); PG8_MMA(1, 0, At, B0); PG8_BAR; PG8_SCHED;
	s_add_u32 s66, s36, 0x80000
	s_addc_u32 s67, s37, 0
	s_mov_b32 m0, s51
	v_lshl_add_u64 v[138:139], s[66:67], 0, v[160:161]
	global_load_lds_dwordx4 v[138:139], off
	v_lshl_add_u64 v[138:139], s[66:67], 0, v[132:133]
	s_mov_b32 m0, s52
	s_nop 0
	global_load_lds_dwordx4 v[138:139], off
	s_waitcnt vmcnt(6)
	s_barrier
	s_setprio 1
	v_mfma_f32_16x16x32_bf16 v[52:55], v[216:219], v[166:169], v[52:55]
	v_mfma_f32_16x16x32_bf16 v[48:51], v[224:227], v[166:169], v[48:51]
	v_mfma_f32_16x16x32_bf16 v[36:39], v[216:219], v[174:177], v[36:39]
	v_mfma_f32_16x16x32_bf16 v[32:35], v[224:227], v[174:177], v[32:35]
	v_mfma_f32_16x16x32_bf16 v[20:23], v[216:219], v[182:185], v[20:23]
	v_mfma_f32_16x16x32_bf16 v[16:19], v[224:227], v[182:185], v[16:19]
	v_mfma_f32_16x16x32_bf16 v[4:7], v[216:219], v[208:211], v[4:7]
	v_mfma_f32_16x16x32_bf16 v[0:3], v[224:227], v[208:211], v[0:3]
	v_mfma_f32_16x16x32_bf16 v[52:55], v[220:223], v[170:173], v[52:55]
	v_mfma_f32_16x16x32_bf16 v[48:51], v[228:231], v[170:173], v[48:51]
	v_mfma_f32_16x16x32_bf16 v[36:39], v[220:223], v[178:181], v[36:39]
	v_mfma_f32_16x16x32_bf16 v[32:35], v[228:231], v[178:181], v[32:35]
	v_mfma_f32_16x16x32_bf16 v[20:23], v[220:223], v[196:199], v[20:23]
	v_mfma_f32_16x16x32_bf16 v[16:19], v[228:231], v[196:199], v[16:19]
	v_mfma_f32_16x16x32_bf16 v[4:7], v[220:223], v[212:215], v[4:7]
	v_mfma_f32_16x16x32_bf16 v[0:3], v[228:231], v[212:215], v[0:3]
	s_setprio 0
	v_add_u32_e32 v154, s55, v147
	s_barrier
	ds_read_b128 v[138:141], v154
	ds_read_b128 v[142:145], v154 offset:1024
	ds_read_b128 v[150:153], v154 offset:2048
	ds_read_b128 v[154:157], v154 offset:3072
	s_add_u32 s38, s38, 0x80000
	s_addc_u32 s39, s39, 0
	s_mov_b32 m0, s53
	v_lshl_add_u64 v[216:217], s[38:39], 0, v[128:129]
	ds_read_b128 v[166:169], v149 offset:32768
	ds_read_b128 v[170:173], v149 offset:33792
	ds_read_b128 v[174:177], v149 offset:34816
	ds_read_b128 v[178:181], v149 offset:35840
	ds_read_b128 v[182:185], v149 offset:36864
	ds_read_b128 v[196:199], v149 offset:37888
	ds_read_b128 v[208:211], v149 offset:38912
	ds_read_b128 v[212:215], v149 offset:39936
	global_load_lds_dwordx4 v[216:217], off
	v_lshl_add_u64 v[216:217], s[38:39], 0, v[130:131]
	s_mov_b32 m0, s54
	s_nop 0
	global_load_lds_dwordx4 v[216:217], off
	s_waitcnt lgkmcnt(8)
	s_barrier
	s_waitcnt lgkmcnt(0)
	s_setprio 1
	v_mfma_f32_16x16x32_bf16 v[124:127], v[138:141], v[166:169], v[124:127]
	v_mfma_f32_16x16x32_bf16 v[120:123], v[150:153], v[166:169], v[120:123]
	v_mfma_f32_16x16x32_bf16 v[108:111], v[138:141], v[174:177], v[108:111]
	v_mfma_f32_16x16x32_bf16 v[104:107], v[150:153], v[174:177], v[104:107]
	v_mfma_f32_16x16x32_bf16 v[92:95], v[138:141], v[182:185], v[92:95]
	v_mfma_f32_16x16x32_bf16 v[88:91], v[150:153], v[182:185], v[88:91]
	v_mfma_f32_16x16x32_bf16 v[76:79], v[138:141], v[208:211], v[76:79]
	v_mfma_f32_16x16x32_bf16 v[72:75], v[150:153], v[208:211], v[72:75]
	v_mfma_f32_16x16x32_bf16 v[124:127], v[142:145], v[170:173], v[124:127]
	v_mfma_f32_16x16x32_bf16 v[120:123], v[154:157], v[170:173], v[120:123]
	v_mfma_f32_16x16x32_bf16 v[108:111], v[142:145], v[178:181], v[108:111]
	v_mfma_f32_16x16x32_bf16 v[104:107], v[154:157], v[178:181], v[104:107]
	v_mfma_f32_16x16x32_bf16 v[92:95], v[142:145], v[196:199], v[92:95]
	v_mfma_f32_16x16x32_bf16 v[88:91], v[154:157], v[196:199], v[88:91]
	v_mfma_f32_16x16x32_bf16 v[76:79], v[142:145], v[212:215], v[76:79]
	v_mfma_f32_16x16x32_bf16 v[72:75], v[154:157], v[212:215], v[72:75]
	s_setprio 0
	s_barrier
	s_mov_b32 m0, s56
	v_add_u32_e32 v228, s60, v147
	v_lshl_add_u64 v[158:159], v[158:159], 0, s[90:91]
	ds_read_b128 v[216:219], v228
	ds_read_b128 v[220:223], v228 offset:1024
	ds_read_b128 v[224:227], v228 offset:2048
	ds_read_b128 v[228:231], v228 offset:3072
	global_load_lds_dwordx4 v[158:159], off
	v_lshl_add_u64 v[158:159], v[200:201], 0, s[90:91]
	s_mov_b32 m0, s57
	s_nop 0
	global_load_lds_dwordx4 v[158:159], off
	s_barrier
	s_waitcnt lgkmcnt(0)
	s_setprio 1
	v_mfma_f32_16x16x32_bf16 v[116:119], v[216:219], v[166:169], v[116:119]
	v_mfma_f32_16x16x32_bf16 v[112:115], v[224:227], v[166:169], v[112:115]
	v_mfma_f32_16x16x32_bf16 v[100:103], v[216:219], v[174:177], v[100:103]
	v_mfma_f32_16x16x32_bf16 v[96:99], v[224:227], v[174:177], v[96:99]
	v_mfma_f32_16x16x32_bf16 v[84:87], v[216:219], v[182:185], v[84:87]
	v_mfma_f32_16x16x32_bf16 v[80:83], v[224:227], v[182:185], v[80:83]
	v_mfma_f32_16x16x32_bf16 v[68:71], v[216:219], v[208:211], v[68:71]
	v_mfma_f32_16x16x32_bf16 v[64:67], v[224:227], v[208:211], v[64:67]
	v_mfma_f32_16x16x32_bf16 v[116:119], v[220:223], v[170:173], v[116:119]
	v_mfma_f32_16x16x32_bf16 v[112:115], v[228:231], v[170:173], v[112:115]
	v_mfma_f32_16x16x32_bf16 v[100:103], v[220:223], v[178:181], v[100:103]
	v_mfma_f32_16x16x32_bf16 v[96:99], v[228:231], v[178:181], v[96:99]
	v_mfma_f32_16x16x32_bf16 v[84:87], v[220:223], v[196:199], v[84:87]
	v_mfma_f32_16x16x32_bf16 v[80:83], v[228:231], v[196:199], v[80:83]
	v_mfma_f32_16x16x32_bf16 v[68:71], v[220:223], v[212:215], v[68:71]
	v_mfma_f32_16x16x32_bf16 v[64:67], v[228:231], v[212:215], v[64:67]
	s_setprio 0
	s_mov_b32 m0, s58
	v_lshl_add_u64 v[158:159], v[232:233], 0, s[90:91]
	s_barrier
	ds_read_b128 v[166:169], v149 offset:49152
	ds_read_b128 v[170:173], v149 offset:50176
	ds_read_b128 v[174:177], v149 offset:51200
	ds_read_b128 v[178:181], v149 offset:52224
	ds_read_b128 v[182:185], v149 offset:53248
	ds_read_b128 v[196:199], v149 offset:54272
	ds_read_b128 v[208:211], v149 offset:55296
	ds_read_b128 v[212:215], v149 offset:56320
	global_load_lds_dwordx4 v[158:159], off
	v_lshl_add_u64 v[158:159], v[234:235], 0, s[90:91]
	s_mov_b32 m0, s59
	s_nop 0
	global_load_lds_dwordx4 v[158:159], off
	s_barrier
; __device__ __forceinline__ unsigned cvt_pk_bf16(float lo, float hi) { unsigned r; asm volatile("v_cvt_pk_bf16_f32 %0, %1, %2" : "=v"(r) : "v"(lo), "v"(hi)); return r; }
; __device__ __forceinline__ float rinv_st(stat_t s, float invn) { return rsqrtf((float)((double)s * (1.0 / 4294967296.0)) * invn + 1e-6f); }
; #define PG8_STAGE(bufoff, gbase, voff) do { _Pragma("unroll") for (int _i = 0; _i < 2; ++_i) \
;         __builtin_amdgcn_global_load_lds((const unsigned*)((const char*)(gbase) + (voff)[_i]), (LAS unsigned*)(lds + (bufoff) + ldsw + _i * 8192), 16, 0, 0); } while (0)
; #define PG8_WAIT_V(n) asm volatile("s_waitcnt vmcnt(" #n ")" ::: "memory")
; #define PG8_WAIT_L(n) asm volatile("s_waitcnt lgkmcnt(" #n ")" ::: "memory")
; #define PG8_BAR __builtin_amdgcn_s_barrier()
; #define PG8_SCHED __builtin_amdgcn_sched_barrier(0)
; template <class Epi>
; __device__ __forceinline__ void gemm_phase(const int TID, const int BID, LAS unsigned char* lds, const Gemm g, const StaticOrder& S, const Epi& E) {
;     ...
;             PG8_BAR; PG8_WAIT_L(0); PG8_MMA(1, 0, At, B0); PG8_BAR; PG8_SCHED;
;             PG8_STAGE(PG8_SB(1, 1), b3 + hstepB, voffB);
;             PG8_WAIT_V(6); PG8_BAR; PG8_MMA(1, 1, At, B1); PG8_BAR;
;         }
;         E(acc, cur, wr, wc, fr, fq);
;     __device__ __forceinline__ void operator()(const f32x4 (&acc)[2][2][4][2], const Unit& u, int wr, int wc, int fr, int fq) const {
;         const int row0 = u.pm * BM + wr * 64 + fr, col0 = u.pn * BM + wc * 32 + 8 * fq;
; #pragma unroll
;         for (int ai = 0; ai < 2; ++ai)
; #pragma unroll
;             for (int m = 0; m < 4; ++m) {
;                 const int row = row0 + ai * HALF + m * 16; const float r = rinv_st(stats[row], 1.0f / 2048.0f);
;                 bf16_t* rowp = U + (size_t)row * FF + col0;
; #pragma unroll
;                 for (int bj = 0; bj < 2; ++bj) {
;                     f32x4 v0 = acc[ai][bj][m][0] * r, v1 = acc[ai][bj][m][1] * r;
; #pragma unroll
;                     for (int j = 0; j < 4; ++j) { const float a = fmaxf(v0[j], 0.f), b = fmaxf(v1[j], 0.f); v0[j] = a * a; v1[j] = b * b; }
;                     u32x4 w; w.x = cvt_pk_bf16(v0[0], v0[1]); w.y = cvt_pk_bf16(v0[2], v0[3]); w.z = cvt_pk_bf16(v1[0], v1[1]); w.w = cvt_pk_bf16(v1[2], v1[3]);
;                     *(u32x4*)(rowp + bj * HALF) = w;
	s_waitcnt lgkmcnt(0)
	s_setprio 1
	v_mfma_f32_16x16x32_bf16 v[60:63], v[138:141], v[166:169], v[60:63]
	v_mfma_f32_16x16x32_bf16 v[56:59], v[150:153], v[166:169], v[56:59]
	v_mfma_f32_16x16x32_bf16 v[44:47], v[138:141], v[174:177], v[44:47]
	v_mfma_f32_16x16x32_bf16 v[40:43], v[150:153], v[174:177], v[40:43]
	v_mfma_f32_16x16x32_bf16 v[28:31], v[138:141], v[182:185], v[28:31]
	v_mfma_f32_16x16x32_bf16 v[24:27], v[150:153], v[182:185], v[24:27]
	v_mfma_f32_16x16x32_bf16 v[12:15], v[138:141], v[208:211], v[12:15]
	v_mfma_f32_16x16x32_bf16 v[8:11], v[150:153], v[208:211], v[8:11]
	v_mfma_f32_16x16x32_bf16 v[60:63], v[142:145], v[170:173], v[60:63]
	v_mfma_f32_16x16x32_bf16 v[56:59], v[154:157], v[170:173], v[56:59]
	v_mfma_f32_16x16x32_bf16 v[44:47], v[142:145], v[178:181], v[44:47]
	v_mfma_f32_16x16x32_bf16 v[40:43], v[154:157], v[178:181], v[40:43]
	v_mfma_f32_16x16x32_bf16 v[28:31], v[142:145], v[196:199], v[28:31]
	v_mfma_f32_16x16x32_bf16 v[24:27], v[154:157], v[196:199], v[24:27]
	v_mfma_f32_16x16x32_bf16 v[12:15], v[142:145], v[212:215], v[12:15]
	v_mfma_f32_16x16x32_bf16 v[8:11], v[154:157], v[212:215], v[8:11]
	s_setprio 0
	s_barrier
	s_add_u32 s36, s36, 0x80080
	s_addc_u32 s37, s37, 0
	s_mov_b32 m0, s61
	v_lshl_add_u64 v[138:139], s[36:37], 0, v[160:161]
	global_load_lds_dwordx4 v[138:139], off
	v_lshl_add_u64 v[138:139], s[36:37], 0, v[132:133]
	s_mov_b32 m0, s62
	s_nop 0
	global_load_lds_dwordx4 v[138:139], off
	s_waitcnt vmcnt(6)
	s_barrier
	s_setprio 1
	v_mfma_f32_16x16x32_bf16 v[52:55], v[216:219], v[166:169], v[52:55]
	v_mfma_f32_16x16x32_bf16 v[48:51], v[224:227], v[166:169], v[48:51]
	v_mfma_f32_16x16x32_bf16 v[36:39], v[216:219], v[174:177], v[36:39]
	v_mfma_f32_16x16x32_bf16 v[32:35], v[224:227], v[174:177], v[32:35]
	v_mfma_f32_16x16x32_bf16 v[20:23], v[216:219], v[182:185], v[20:23]
	v_mfma_f32_16x16x32_bf16 v[16:19], v[224:227], v[182:185], v[16:19]
	v_mfma_f32_16x16x32_bf16 v[4:7], v[216:219], v[208:211], v[4:7]
	v_mfma_f32_16x16x32_bf16 v[0:3], v[224:227], v[208:211], v[0:3]
	v_mfma_f32_16x16x32_bf16 v[52:55], v[220:223], v[170:173], v[52:55]
	v_mfma_f32_16x16x32_bf16 v[48:51], v[228:231], v[170:173], v[48:51]
	v_mfma_f32_16x16x32_bf16 v[36:39], v[220:223], v[178:181], v[36:39]
	v_mfma_f32_16x16x32_bf16 v[32:35], v[228:231], v[178:181], v[32:35]
	v_mfma_f32_16x16x32_bf16 v[20:23], v[220:223], v[196:199], v[20:23]
	v_mfma_f32_16x16x32_bf16 v[16:19], v[228:231], v[196:199], v[16:19]
	v_mfma_f32_16x16x32_bf16 v[4:7], v[220:223], v[212:215], v[4:7]
	v_mfma_f32_16x16x32_bf16 v[0:3], v[228:231], v[212:215], v[0:3]
	s_setprio 0
	s_add_i32 s64, s64, 2
	s_add_u32 s34, s34, 0x100
	s_addc_u32 s35, s35, 0
	s_add_u32 s22, s22, 0x100
	s_addc_u32 s23, s23, 0
	s_cmp_gt_u32 s64, 29
	s_barrier
	s_cbranch_scc0 .LBB0_925
	v_lshl_add_u32 v142, s30, 8, v146
	v_ashrrev_i32_e32 v143, 31, v142
	v_lshl_add_u64 v[138:139], v[142:143], 3, s[10:11]
	v_lshl_or_b32 v140, s0, 8, v148
	v_ashrrev_i32_e32 v141, 31, v140
	s_mov_b64 s[0:1], 0x200000
	s_mov_b32 s30, s18
	s_mov_b64 s[36:37], s[28:29]
	s_mov_b64 s[34:35], s[26:27]
	v_mov_b64_e32 v[144:145], v[236:237]
	v_cvt_f64_u32_e32 v[150:151], v145
	v_ldexp_f64 v[150:151], v[150:151], 32
	v_cvt_f64_u32_e32 v[144:145], v144
	v_add_f64 v[144:145], v[150:151], v[144:145]
	v_ldexp_f64 v[144:145], v[144:145], s93
	v_cvt_f32_f64_e32 v144, v[144:145]
	v_fmamk_f32 v144, v144, 0x3a000000, v189
	v_cmp_gt_f32_e32 vcc, s78, v144
	v_mul_f32_e32 v145, 0x4b800000, v144
	s_nop 0
	v_cndmask_b32_e32 v144, v144, v145, vcc
	v_rsq_f32_e32 v144, v144
	s_nop 0
	v_mul_f32_e32 v145, 0x45800000, v144
	v_cndmask_b32_e32 v150, v144, v145, vcc
	v_pk_mul_f32 v[120:121], v[120:121], v[150:151] op_sel_hi:[1,0]
	v_pk_mul_f32 v[124:125], v[124:125], v[150:151] op_sel_hi:[1,0]
	v_pk_mul_f32 v[122:123], v[122:123], v[150:151] op_sel_hi:[1,0]
	v_max_f32_e32 v120, 0, v120
	v_lshlrev_b64 v[144:145], 14, v[142:143]
	v_pk_mul_f32 v[126:127], v[126:127], v[150:151] op_sel_hi:[1,0]
	v_mul_f32_e32 v143, v120, v120
	v_max_f32_e32 v120, 0, v125
	v_max_f32_e32 v121, 0, v121
	v_max_f32_e32 v122, 0, v122
	v_lshl_add_u64 v[152:153], s[14:15], 0, v[144:145]
	v_lshlrev_b64 v[144:145], 1, v[140:141]
	v_max_f32_e32 v124, 0, v124
	v_mul_f32_e32 v120, v120, v120
	v_mul_f32_e32 v125, v121, v121
	v_max_f32_e32 v121, 0, v126
	v_mul_f32_e32 v126, v122, v122
	v_max_f32_e32 v122, 0, v127
	v_max_f32_e32 v123, 0, v123
	v_pk_mul_f32 v[114:115], v[114:115], v[150:151] op_sel_hi:[1,0]
	v_pk_mul_f32 v[112:113], v[112:113], v[150:151] op_sel_hi:[1,0]
	v_lshl_add_u64 v[140:141], v[152:153], 0, v[144:145]
	v_mul_f32_e32 v124, v124, v124
	v_mul_f32_e32 v121, v121, v121
	v_mul_f32_e32 v122, v122, v122
	v_mul_f32_e32 v123, v123, v123
	v_cvt_pk_bf16_f32 v120, v124, v120
	v_pk_mul_f32 v[118:119], v[118:119], v[150:151] op_sel_hi:[1,0]
	v_pk_mul_f32 v[116:117], v[116:117], v[150:151] op_sel_hi:[1,0]
	v_max_f32_e32 v112, 0, v112
	v_max_f32_e32 v113, 0, v113
	v_max_f32_e32 v114, 0, v114
	v_cvt_pk_bf16_f32 v121, v121, v122
	v_cvt_pk_bf16_f32 v122, v143, v125
	v_cvt_pk_bf16_f32 v123, v126, v123
	global_store_dwordx4 v[140:141], v[120:123], off
	v_max_f32_e32 v115, 0, v115
	v_max_f32_e32 v116, 0, v116
	v_mul_f32_e32 v120, v112, v112
	v_max_f32_e32 v112, 0, v117
	v_mul_f32_e32 v117, v113, v113
	v_max_f32_e32 v113, 0, v118
	v_mul_f32_e32 v118, v114, v114
	v_max_f32_e32 v114, 0, v119
	v_mul_f32_e32 v112, v112, v112
	v_mul_f32_e32 v113, v113, v113
	v_mul_f32_e32 v114, v114, v114
	v_mul_f32_e32 v115, v115, v115
	v_mul_f32_e32 v116, v116, v116
	v_cvt_pk_bf16_f32 v112, v116, v112
	v_cvt_pk_bf16_f32 v113, v113, v114
	v_cvt_pk_bf16_f32 v114, v120, v117
	v_cvt_pk_bf16_f32 v115, v118, v115
; __device__ __forceinline__ unsigned cvt_pk_bf16(float lo, float hi) { unsigned r; asm volatile("v_cvt_pk_bf16_f32 %0, %1, %2" : "=v"(r) : "v"(lo), "v"(hi)); return r; }
; __device__ __forceinline__ float rinv_st(stat_t s, float invn) { return rsqrtf((float)((double)s * (1.0 / 4294967296.0)) * invn + 1e-6f); }
;     __device__ __forceinline__ void operator()(const f32x4 (&acc)[2][2][4][2], const Unit& u, int wr, int wc, int fr, int fq) const {
;     ...
;             for (int m = 0; m < 4; ++m) {
;                 const int row = row0 + ai * HALF + m * 16; const float r = rinv_st(stats[row], 1.0f / 2048.0f);
;                 bf16_t* rowp = U + (size_t)row * FF + col0;
; #pragma unroll
;                 for (int bj = 0; bj < 2; ++bj) {
;                     f32x4 v0 = acc[ai][bj][m][0] * r, v1 = acc[ai][bj][m][1] * r;
; #pragma unroll
;                     for (int j = 0; j < 4; ++j) { const float a = fmaxf(v0[j], 0.f), b = fmaxf(v1[j], 0.f); v0[j] = a * a; v1[j] = b * b; }
;                     u32x4 w; w.x = cvt_pk_bf16(v0[0], v0[1]); w.y = cvt_pk_bf16(v0[2], v0[3]); w.z = cvt_pk_bf16(v1[0], v1[1]); w.w = cvt_pk_bf16(v1[2], v1[3]);
;                     *(u32x4*)(rowp + bj * HALF) = w;
;                 }
	global_store_dwordx4 v[140:141], v[112:115], off offset:256
	s_nop 1
	v_mov_b64_e32 v[114:115], v[238:239]
	v_cvt_f64_u32_e32 v[116:117], v115
	v_ldexp_f64 v[116:117], v[116:117], 32
	v_cvt_f64_u32_e32 v[114:115], v114
	v_add_f64 v[114:115], v[116:117], v[114:115]
	v_ldexp_f64 v[114:115], v[114:115], s93
	v_cvt_f32_f64_e32 v114, v[114:115]
	v_fmamk_f32 v114, v114, 0x3a000000, v189
	v_cmp_gt_f32_e32 vcc, s78, v114
	v_mul_f32_e32 v115, 0x4b800000, v114
	v_or_b32_e32 v112, 16, v142
	v_cndmask_b32_e32 v114, v114, v115, vcc
	v_rsq_f32_e32 v114, v114
	v_ashrrev_i32_e32 v113, 31, v112
	v_lshlrev_b64 v[112:113], 14, v[112:113]
	v_lshl_add_u64 v[112:113], s[14:15], 0, v[112:113]
	v_mul_f32_e32 v115, 0x45800000, v114
	v_cndmask_b32_e32 v114, v114, v115, vcc
	v_pk_mul_f32 v[104:105], v[104:105], v[114:115] op_sel_hi:[1,0]
	v_pk_mul_f32 v[108:109], v[108:109], v[114:115] op_sel_hi:[1,0]
	v_pk_mul_f32 v[106:107], v[106:107], v[114:115] op_sel_hi:[1,0]
	v_max_f32_e32 v104, 0, v104
	v_pk_mul_f32 v[110:111], v[110:111], v[114:115] op_sel_hi:[1,0]
	v_mul_f32_e32 v115, v104, v104
	v_max_f32_e32 v104, 0, v109
	v_max_f32_e32 v105, 0, v105
	v_max_f32_e32 v106, 0, v106
	v_max_f32_e32 v108, 0, v108
	v_mul_f32_e32 v104, v104, v104
	v_mul_f32_e32 v109, v105, v105
	v_max_f32_e32 v105, 0, v110
	v_mul_f32_e32 v110, v106, v106
	v_max_f32_e32 v106, 0, v111
	v_max_f32_e32 v107, 0, v107
	v_pk_mul_f32 v[98:99], v[98:99], v[114:115] op_sel_hi:[1,0]
	v_pk_mul_f32 v[96:97], v[96:97], v[114:115] op_sel_hi:[1,0]
	v_lshl_add_u64 v[112:113], v[112:113], 0, v[144:145]
	v_mul_f32_e32 v108, v108, v108
	v_mul_f32_e32 v105, v105, v105
	v_mul_f32_e32 v106, v106, v106
	v_mul_f32_e32 v107, v107, v107
	v_cvt_pk_bf16_f32 v104, v108, v104
	v_pk_mul_f32 v[102:103], v[102:103], v[114:115] op_sel_hi:[1,0]
	v_pk_mul_f32 v[100:101], v[100:101], v[114:115] op_sel_hi:[1,0]
	v_max_f32_e32 v96, 0, v96
	v_max_f32_e32 v97, 0, v97
	v_max_f32_e32 v98, 0, v98
	v_cvt_pk_bf16_f32 v105, v105, v106
	v_cvt_pk_bf16_f32 v106, v115, v109
	v_cvt_pk_bf16_f32 v107, v110, v107
	global_store_dwordx4 v[112:113], v[104:107], off
	v_max_f32_e32 v99, 0, v99
	v_max_f32_e32 v100, 0, v100
	v_mul_f32_e32 v104, v96, v96
	v_max_f32_e32 v96, 0, v101
	v_mul_f32_e32 v101, v97, v97
	v_max_f32_e32 v97, 0, v102
	v_mul_f32_e32 v102, v98, v98
	v_max_f32_e32 v98, 0, v103
	v_mul_f32_e32 v96, v96, v96
	v_mul_f32_e32 v97, v97, v97
	v_mul_f32_e32 v98, v98, v98
	v_mul_f32_e32 v99, v99, v99
	v_mul_f32_e32 v100, v100, v100
	v_cvt_pk_bf16_f32 v96, v100, v96
	v_cvt_pk_bf16_f32 v97, v97, v98
	v_cvt_pk_bf16_f32 v98, v104, v101
	v_cvt_pk_bf16_f32 v99, v102, v99
	global_store_dwordx4 v[112:113], v[96:99], off offset:256
	s_nop 1
	v_mov_b64_e32 v[98:99], v[240:241]
	v_cvt_f64_u32_e32 v[100:101], v99
	v_ldexp_f64 v[100:101], v[100:101], 32
	v_cvt_f64_u32_e32 v[98:99], v98
	v_add_f64 v[98:99], v[100:101], v[98:99]
	v_ldexp_f64 v[98:99], v[98:99], s93
	v_cvt_f32_f64_e32 v98, v[98:99]
	v_fmamk_f32 v98, v98, 0x3a000000, v189
	v_cmp_gt_f32_e32 vcc, s78, v98
	v_mul_f32_e32 v99, 0x4b800000, v98
	v_or_b32_e32 v96, 32, v142
	v_cndmask_b32_e32 v98, v98, v99, vcc
	v_rsq_f32_e32 v98, v98
	v_ashrrev_i32_e32 v97, 31, v96
	v_lshlrev_b64 v[96:97], 14, v[96:97]
	v_lshl_add_u64 v[96:97], s[14:15], 0, v[96:97]
	v_mul_f32_e32 v99, 0x45800000, v98
	v_cndmask_b32_e32 v98, v98, v99, vcc
	v_pk_mul_f32 v[88:89], v[88:89], v[98:99] op_sel_hi:[1,0]
	v_pk_mul_f32 v[92:93], v[92:93], v[98:99] op_sel_hi:[1,0]
	v_pk_mul_f32 v[90:91], v[90:91], v[98:99] op_sel_hi:[1,0]
	v_max_f32_e32 v88, 0, v88
	v_pk_mul_f32 v[94:95], v[94:95], v[98:99] op_sel_hi:[1,0]
	v_mul_f32_e32 v99, v88, v88
	v_max_f32_e32 v88, 0, v93
	v_max_f32_e32 v89, 0, v89
	v_max_f32_e32 v90, 0, v90
	v_max_f32_e32 v92, 0, v92
	v_mul_f32_e32 v88, v88, v88
	v_mul_f32_e32 v93, v89, v89
	v_max_f32_e32 v89, 0, v94
	v_mul_f32_e32 v94, v90, v90
	v_max_f32_e32 v90, 0, v95
	v_max_f32_e32 v91, 0, v91
	v_pk_mul_f32 v[82:83], v[82:83], v[98:99] op_sel_hi:[1,0]
	v_pk_mul_f32 v[80:81], v[80:81], v[98:99] op_sel_hi:[1,0]
	v_lshl_add_u64 v[96:97], v[96:97], 0, v[144:145]
	v_mul_f32_e32 v92, v92, v92
	v_mul_f32_e32 v89, v89, v89
	v_mul_f32_e32 v90, v90, v90
	v_mul_f32_e32 v91, v91, v91
	v_cvt_pk_bf16_f32 v88, v92, v88
	v_pk_mul_f32 v[86:87], v[86:87], v[98:99] op_sel_hi:[1,0]
	v_pk_mul_f32 v[84:85], v[84:85], v[98:99] op_sel_hi:[1,0]
	v_max_f32_e32 v80, 0, v80
	v_max_f32_e32 v81, 0, v81
	v_max_f32_e32 v82, 0, v82
	v_cvt_pk_bf16_f32 v89, v89, v90
	v_cvt_pk_bf16_f32 v90, v99, v93
	v_cvt_pk_bf16_f32 v91, v94, v91
	global_store_dwordx4 v[96:97], v[88:91], off
	v_max_f32_e32 v83, 0, v83
	v_max_f32_e32 v84, 0, v84
	v_mul_f32_e32 v88, v80, v80
	v_max_f32_e32 v80, 0, v85
	v_mul_f32_e32 v85, v81, v81
	v_max_f32_e32 v81, 0, v86
	v_mul_f32_e32 v86, v82, v82
	v_max_f32_e32 v82, 0, v87
	v_mul_f32_e32 v80, v80, v80
	v_mul_f32_e32 v81, v81, v81
	v_mul_f32_e32 v82, v82, v82
	v_mul_f32_e32 v83, v83, v83
	v_mul_f32_e32 v84, v84, v84
	v_cvt_pk_bf16_f32 v80, v84, v80
	v_cvt_pk_bf16_f32 v81, v81, v82
	v_cvt_pk_bf16_f32 v82, v88, v85
	v_cvt_pk_bf16_f32 v83, v86, v83
	global_store_dwordx4 v[96:97], v[80:83], off offset:256
	s_nop 1
	v_mov_b64_e32 v[82:83], v[242:243]
	v_cvt_f64_u32_e32 v[84:85], v83
	v_ldexp_f64 v[84:85], v[84:85], 32
	v_cvt_f64_u32_e32 v[82:83], v82
	v_add_f64 v[82:83], v[84:85], v[82:83]
	v_ldexp_f64 v[82:83], v[82:83], s93
	v_cvt_f32_f64_e32 v82, v[82:83]
	v_fmamk_f32 v82, v82, 0x3a000000, v189
	v_cmp_gt_f32_e32 vcc, s78, v82
	v_mul_f32_e32 v83, 0x4b800000, v82
	v_or_b32_e32 v80, 48, v142
	v_cndmask_b32_e32 v82, v82, v83, vcc
	v_rsq_f32_e32 v82, v82
	v_ashrrev_i32_e32 v81, 31, v80
	v_lshlrev_b64 v[80:81], 14, v[80:81]
; __device__ __forceinline__ unsigned cvt_pk_bf16(float lo, float hi) { unsigned r; asm volatile("v_cvt_pk_bf16_f32 %0, %1, %2" : "=v"(r) : "v"(lo), "v"(hi)); return r; }
; __device__ __forceinline__ float rinv_st(stat_t s, float invn) { return rsqrtf((float)((double)s * (1.0 / 4294967296.0)) * invn + 1e-6f); }
;     __device__ __forceinline__ void operator()(const f32x4 (&acc)[2][2][4][2], const Unit& u, int wr, int wc, int fr, int fq) const {
;     ...
;             for (int m = 0; m < 4; ++m) {
;                 const int row = row0 + ai * HALF + m * 16; const float r = rinv_st(stats[row], 1.0f / 2048.0f);
;                 bf16_t* rowp = U + (size_t)row * FF + col0;
; #pragma unroll
;                 for (int bj = 0; bj < 2; ++bj) {
;                     f32x4 v0 = acc[ai][bj][m][0] * r, v1 = acc[ai][bj][m][1] * r;
; #pragma unroll
;                     for (int j = 0; j < 4; ++j) { const float a = fmaxf(v0[j], 0.f), b = fmaxf(v1[j], 0.f); v0[j] = a * a; v1[j] = b * b; }
;                     u32x4 w; w.x = cvt_pk_bf16(v0[0], v0[1]); w.y = cvt_pk_bf16(v0[2], v0[3]); w.z = cvt_pk_bf16(v1[0], v1[1]); w.w = cvt_pk_bf16(v1[2], v1[3]);
;                     *(u32x4*)(rowp + bj * HALF) = w;
;                 }
	v_lshl_add_u64 v[80:81], s[14:15], 0, v[80:81]
	v_mul_f32_e32 v83, 0x45800000, v82
	v_cndmask_b32_e32 v82, v82, v83, vcc
	v_pk_mul_f32 v[72:73], v[72:73], v[82:83] op_sel_hi:[1,0]
	v_pk_mul_f32 v[76:77], v[76:77], v[82:83] op_sel_hi:[1,0]
	v_pk_mul_f32 v[74:75], v[74:75], v[82:83] op_sel_hi:[1,0]
	v_max_f32_e32 v72, 0, v72
	v_pk_mul_f32 v[78:79], v[78:79], v[82:83] op_sel_hi:[1,0]
	v_mul_f32_e32 v83, v72, v72
	v_max_f32_e32 v72, 0, v77
	v_max_f32_e32 v73, 0, v73
	v_max_f32_e32 v74, 0, v74
	v_max_f32_e32 v76, 0, v76
	v_mul_f32_e32 v72, v72, v72
	v_mul_f32_e32 v77, v73, v73
	v_max_f32_e32 v73, 0, v78
	v_mul_f32_e32 v78, v74, v74
	v_max_f32_e32 v74, 0, v79
	v_max_f32_e32 v75, 0, v75
	v_pk_mul_f32 v[66:67], v[66:67], v[82:83] op_sel_hi:[1,0]
	v_pk_mul_f32 v[64:65], v[64:65], v[82:83] op_sel_hi:[1,0]
	v_lshl_add_u64 v[80:81], v[80:81], 0, v[144:145]
	v_mul_f32_e32 v76, v76, v76
	v_mul_f32_e32 v73, v73, v73
	v_mul_f32_e32 v74, v74, v74
	v_mul_f32_e32 v75, v75, v75
	v_cvt_pk_bf16_f32 v72, v76, v72
	v_pk_mul_f32 v[70:71], v[70:71], v[82:83] op_sel_hi:[1,0]
	v_pk_mul_f32 v[68:69], v[68:69], v[82:83] op_sel_hi:[1,0]
	v_max_f32_e32 v64, 0, v64
	v_max_f32_e32 v65, 0, v65
	v_max_f32_e32 v66, 0, v66
	v_cvt_pk_bf16_f32 v73, v73, v74
	v_cvt_pk_bf16_f32 v74, v83, v77
	v_cvt_pk_bf16_f32 v75, v78, v75
	global_store_dwordx4 v[80:81], v[72:75], off
	v_max_f32_e32 v67, 0, v67
	v_max_f32_e32 v68, 0, v68
	v_mul_f32_e32 v72, v64, v64
	v_max_f32_e32 v64, 0, v69
	v_mul_f32_e32 v69, v65, v65
	v_max_f32_e32 v65, 0, v70
	v_mul_f32_e32 v70, v66, v66
	v_max_f32_e32 v66, 0, v71
	v_mul_f32_e32 v64, v64, v64
	v_mul_f32_e32 v65, v65, v65
	v_mul_f32_e32 v66, v66, v66
	v_mul_f32_e32 v67, v67, v67
	v_mul_f32_e32 v68, v68, v68
	v_cvt_pk_bf16_f32 v64, v68, v64
	v_cvt_pk_bf16_f32 v65, v65, v66
	v_cvt_pk_bf16_f32 v66, v72, v69
	v_cvt_pk_bf16_f32 v67, v70, v67
	global_store_dwordx4 v[80:81], v[64:67], off offset:256
	s_nop 1
	v_mov_b64_e32 v[64:65], v[244:245]
	v_cvt_f64_u32_e32 v[66:67], v65
	v_ldexp_f64 v[66:67], v[66:67], 32
	v_cvt_f64_u32_e32 v[64:65], v64
	v_add_f64 v[64:65], v[66:67], v[64:65]
	v_ldexp_f64 v[64:65], v[64:65], s93
	v_cvt_f32_f64_e32 v64, v[64:65]
	v_fmamk_f32 v64, v64, 0x3a000000, v189
	v_cmp_gt_f32_e32 vcc, s78, v64
	v_mul_f32_e32 v65, 0x4b800000, v64
	s_nop 0
	v_cndmask_b32_e32 v64, v64, v65, vcc
	v_rsq_f32_e32 v64, v64
	s_nop 0
	v_mul_f32_e32 v65, 0x45800000, v64
	v_cndmask_b32_e32 v66, v64, v65, vcc
	v_pk_mul_f32 v[56:57], v[56:57], v[66:67] op_sel_hi:[1,0]
	v_pk_mul_f32 v[60:61], v[60:61], v[66:67] op_sel_hi:[1,0]
	v_pk_mul_f32 v[58:59], v[58:59], v[66:67] op_sel_hi:[1,0]
	v_max_f32_e32 v56, 0, v56
	v_pk_mul_f32 v[62:63], v[62:63], v[66:67] op_sel_hi:[1,0]
	v_max_f32_e32 v60, 0, v60
	v_mul_f32_e32 v67, v56, v56
	v_max_f32_e32 v56, 0, v61
	v_max_f32_e32 v57, 0, v57
	v_max_f32_e32 v58, 0, v58
	v_lshl_add_u64 v[64:65], v[140:141], 0, s[0:1]
	v_mul_f32_e32 v60, v60, v60
	v_mul_f32_e32 v56, v56, v56
	v_mul_f32_e32 v61, v57, v57
	v_max_f32_e32 v57, 0, v62
	v_mul_f32_e32 v62, v58, v58
	v_max_f32_e32 v58, 0, v63
	s_mov_b32 s0, 0x200000
	v_mul_f32_e32 v57, v57, v57
	v_max_f32_e32 v59, 0, v59
	v_mul_f32_e32 v58, v58, v58
	v_cvt_pk_bf16_f32 v56, v60, v56
	v_add_co_u32_e32 v60, vcc, s0, v140
	v_pk_mul_f32 v[50:51], v[50:51], v[66:67] op_sel_hi:[1,0]
	v_pk_mul_f32 v[48:49], v[48:49], v[66:67] op_sel_hi:[1,0]
	v_mul_f32_e32 v59, v59, v59
	v_cvt_pk_bf16_f32 v57, v57, v58
	v_cvt_pk_bf16_f32 v58, v67, v61
	v_addc_co_u32_e32 v61, vcc, 0, v141, vcc
	v_pk_mul_f32 v[54:55], v[54:55], v[66:67] op_sel_hi:[1,0]
	v_pk_mul_f32 v[52:53], v[52:53], v[66:67] op_sel_hi:[1,0]
	v_max_f32_e32 v48, 0, v48
	v_max_f32_e32 v49, 0, v49
	v_max_f32_e32 v50, 0, v50
	v_cvt_pk_bf16_f32 v59, v62, v59
	global_store_dwordx4 v[60:61], v[56:59], off
	v_max_f32_e32 v51, 0, v51
	v_max_f32_e32 v52, 0, v52
	v_mul_f32_e32 v56, v48, v48
	v_max_f32_e32 v48, 0, v53
	v_mul_f32_e32 v53, v49, v49
	v_max_f32_e32 v49, 0, v54
	v_mul_f32_e32 v54, v50, v50
	v_max_f32_e32 v50, 0, v55
	v_mul_f32_e32 v48, v48, v48
	v_mul_f32_e32 v49, v49, v49
	v_mul_f32_e32 v50, v50, v50
	v_mul_f32_e32 v51, v51, v51
	v_mul_f32_e32 v52, v52, v52
	v_cvt_pk_bf16_f32 v48, v52, v48
	v_cvt_pk_bf16_f32 v49, v49, v50
	v_cvt_pk_bf16_f32 v50, v56, v53
	v_cvt_pk_bf16_f32 v51, v54, v51
	global_store_dwordx4 v[64:65], v[48:51], off offset:256
	s_nop 1
	v_mov_b64_e32 v[48:49], v[246:247]
	s_mov_b64 s[0:1], 0x240000
	v_cvt_f64_u32_e32 v[50:51], v49
	v_ldexp_f64 v[50:51], v[50:51], 32
	v_cvt_f64_u32_e32 v[48:49], v48
	v_add_f64 v[48:49], v[50:51], v[48:49]
	v_ldexp_f64 v[48:49], v[48:49], s93
	v_cvt_f32_f64_e32 v48, v[48:49]
	v_fmamk_f32 v48, v48, 0x3a000000, v189
	v_cmp_gt_f32_e32 vcc, s78, v48
	v_mul_f32_e32 v49, 0x4b800000, v48
	s_nop 0
	v_cndmask_b32_e32 v48, v48, v49, vcc
	v_rsq_f32_e32 v48, v48
	s_nop 0
	v_mul_f32_e32 v49, 0x45800000, v48
	v_cndmask_b32_e32 v50, v48, v49, vcc
	v_pk_mul_f32 v[40:41], v[40:41], v[50:51] op_sel_hi:[1,0]
	v_pk_mul_f32 v[44:45], v[44:45], v[50:51] op_sel_hi:[1,0]
	v_pk_mul_f32 v[42:43], v[42:43], v[50:51] op_sel_hi:[1,0]
	v_max_f32_e32 v40, 0, v40
	v_pk_mul_f32 v[46:47], v[46:47], v[50:51] op_sel_hi:[1,0]
	v_max_f32_e32 v44, 0, v44
	v_mul_f32_e32 v51, v40, v40
	v_max_f32_e32 v40, 0, v45
	v_max_f32_e32 v41, 0, v41
	v_max_f32_e32 v42, 0, v42
	v_lshl_add_u64 v[48:49], v[140:141], 0, s[0:1]
	v_mul_f32_e32 v44, v44, v44
	v_mul_f32_e32 v40, v40, v40
	v_mul_f32_e32 v45, v41, v41
	v_max_f32_e32 v41, 0, v46
	v_mul_f32_e32 v46, v42, v42
	v_max_f32_e32 v42, 0, v47
	s_mov_b32 s0, 0x240000
	v_mul_f32_e32 v41, v41, v41
	v_max_f32_e32 v43, 0, v43
	v_mul_f32_e32 v42, v42, v42
	v_cvt_pk_bf16_f32 v40, v44, v40
	v_add_co_u32_e32 v44, vcc, s0, v140
; __device__ __forceinline__ unsigned cvt_pk_bf16(float lo, float hi) { unsigned r; asm volatile("v_cvt_pk_bf16_f32 %0, %1, %2" : "=v"(r) : "v"(lo), "v"(hi)); return r; }
; __device__ __forceinline__ float rinv_st(stat_t s, float invn) { return rsqrtf((float)((double)s * (1.0 / 4294967296.0)) * invn + 1e-6f); }
; #define PG8_WAIT_V(n) asm volatile("s_waitcnt vmcnt(" #n ")" ::: "memory")
; #define PG8_BAR __builtin_amdgcn_s_barrier()
; template <class Epi>
; __device__ __forceinline__ void gemm_phase(const int TID, const int BID, LAS unsigned char* lds, const Gemm g, const StaticOrder& S, const Epi& E) {
;     ...
;         if (!has_next) break;
; #pragma unroll
;         for (int a = 0; a < 2; ++a)
; #pragma unroll
;             for (int b = 0; b < 2; ++b)
; #pragma unroll
;                 for (int m = 0; m < 4; ++m)
; #pragma unroll
;                     for (int n = 0; n < 2; ++n) acc[a][b][m][n] = (f32x4){0.f, 0.f, 0.f, 0.f};
;         cur = nxt; cA = nA; cB = nB; ++ui;
;     }
;     PG8_WAIT_V(0);
;     if (wr == 0) PG8_BAR;
;     PG8_BAR;
;     __device__ __forceinline__ void operator()(const f32x4 (&acc)[2][2][4][2], const Unit& u, int wr, int wc, int fr, int fq) const {
;     ...
;             for (int m = 0; m < 4; ++m) {
;                 const int row = row0 + ai * HALF + m * 16; const float r = rinv_st(stats[row], 1.0f / 2048.0f);
;                 bf16_t* rowp = U + (size_t)row * FF + col0;
; #pragma unroll
;                 for (int bj = 0; bj < 2; ++bj) {
;                     f32x4 v0 = acc[ai][bj][m][0] * r, v1 = acc[ai][bj][m][1] * r;
; #pragma unroll
;                     for (int j = 0; j < 4; ++j) { const float a = fmaxf(v0[j], 0.f), b = fmaxf(v1[j], 0.f); v0[j] = a * a; v1[j] = b * b; }
;                     u32x4 w; w.x = cvt_pk_bf16(v0[0], v0[1]); w.y = cvt_pk_bf16(v0[2], v0[3]); w.z = cvt_pk_bf16(v1[0], v1[1]); w.w = cvt_pk_bf16(v1[2], v1[3]);
;                     *(u32x4*)(rowp + bj * HALF) = w;
;                 }
	v_pk_mul_f32 v[34:35], v[34:35], v[50:51] op_sel_hi:[1,0]
	v_pk_mul_f32 v[32:33], v[32:33], v[50:51] op_sel_hi:[1,0]
	v_mul_f32_e32 v43, v43, v43
	v_cvt_pk_bf16_f32 v41, v41, v42
	v_cvt_pk_bf16_f32 v42, v51, v45
	v_addc_co_u32_e32 v45, vcc, 0, v141, vcc
	v_pk_mul_f32 v[38:39], v[38:39], v[50:51] op_sel_hi:[1,0]
	v_pk_mul_f32 v[36:37], v[36:37], v[50:51] op_sel_hi:[1,0]
	v_max_f32_e32 v32, 0, v32
	v_max_f32_e32 v33, 0, v33
	v_max_f32_e32 v34, 0, v34
	v_cvt_pk_bf16_f32 v43, v46, v43
	global_store_dwordx4 v[44:45], v[40:43], off
	v_max_f32_e32 v35, 0, v35
	v_max_f32_e32 v36, 0, v36
	v_mul_f32_e32 v40, v32, v32
	v_max_f32_e32 v32, 0, v37
	v_mul_f32_e32 v37, v33, v33
	v_max_f32_e32 v33, 0, v38
	v_mul_f32_e32 v38, v34, v34
	v_max_f32_e32 v34, 0, v39
	v_mul_f32_e32 v32, v32, v32
	v_mul_f32_e32 v33, v33, v33
	v_mul_f32_e32 v34, v34, v34
	v_mul_f32_e32 v35, v35, v35
	v_mul_f32_e32 v36, v36, v36
	v_cvt_pk_bf16_f32 v32, v36, v32
	v_cvt_pk_bf16_f32 v33, v33, v34
	v_cvt_pk_bf16_f32 v34, v40, v37
	v_cvt_pk_bf16_f32 v35, v38, v35
	global_store_dwordx4 v[48:49], v[32:35], off offset:256
	s_nop 1
	v_mov_b64_e32 v[32:33], v[248:249]
	s_mov_b64 s[0:1], 0x280000
	v_cvt_f64_u32_e32 v[34:35], v33
	v_ldexp_f64 v[34:35], v[34:35], 32
	v_cvt_f64_u32_e32 v[32:33], v32
	v_add_f64 v[32:33], v[34:35], v[32:33]
	v_ldexp_f64 v[32:33], v[32:33], s93
	v_cvt_f32_f64_e32 v32, v[32:33]
	v_fmamk_f32 v32, v32, 0x3a000000, v189
	v_cmp_gt_f32_e32 vcc, s78, v32
	v_mul_f32_e32 v33, 0x4b800000, v32
	s_nop 0
	v_cndmask_b32_e32 v32, v32, v33, vcc
	v_rsq_f32_e32 v32, v32
	s_nop 0
	v_mul_f32_e32 v33, 0x45800000, v32
	v_cndmask_b32_e32 v34, v32, v33, vcc
	v_pk_mul_f32 v[24:25], v[24:25], v[34:35] op_sel_hi:[1,0]
	v_pk_mul_f32 v[28:29], v[28:29], v[34:35] op_sel_hi:[1,0]
	v_pk_mul_f32 v[26:27], v[26:27], v[34:35] op_sel_hi:[1,0]
	v_max_f32_e32 v24, 0, v24
	v_pk_mul_f32 v[30:31], v[30:31], v[34:35] op_sel_hi:[1,0]
	v_max_f32_e32 v28, 0, v28
	v_mul_f32_e32 v35, v24, v24
	v_max_f32_e32 v24, 0, v29
	v_max_f32_e32 v25, 0, v25
	v_max_f32_e32 v26, 0, v26
	v_lshl_add_u64 v[32:33], v[140:141], 0, s[0:1]
	v_mul_f32_e32 v28, v28, v28
	v_mul_f32_e32 v24, v24, v24
	v_mul_f32_e32 v29, v25, v25
	v_max_f32_e32 v25, 0, v30
	v_mul_f32_e32 v30, v26, v26
	v_max_f32_e32 v26, 0, v31
	s_mov_b32 s0, 0x280000
	v_mul_f32_e32 v25, v25, v25
	v_max_f32_e32 v27, 0, v27
	v_mul_f32_e32 v26, v26, v26
	v_cvt_pk_bf16_f32 v24, v28, v24
	v_add_co_u32_e32 v28, vcc, s0, v140
	v_pk_mul_f32 v[18:19], v[18:19], v[34:35] op_sel_hi:[1,0]
	v_pk_mul_f32 v[16:17], v[16:17], v[34:35] op_sel_hi:[1,0]
	v_mul_f32_e32 v27, v27, v27
	v_cvt_pk_bf16_f32 v25, v25, v26
	v_cvt_pk_bf16_f32 v26, v35, v29
	v_addc_co_u32_e32 v29, vcc, 0, v141, vcc
	v_pk_mul_f32 v[22:23], v[22:23], v[34:35] op_sel_hi:[1,0]
	v_pk_mul_f32 v[20:21], v[20:21], v[34:35] op_sel_hi:[1,0]
	v_max_f32_e32 v16, 0, v16
	v_max_f32_e32 v17, 0, v17
	v_max_f32_e32 v18, 0, v18
	v_cvt_pk_bf16_f32 v27, v30, v27
	global_store_dwordx4 v[28:29], v[24:27], off
	v_max_f32_e32 v19, 0, v19
	v_max_f32_e32 v20, 0, v20
	v_mul_f32_e32 v24, v16, v16
	v_max_f32_e32 v16, 0, v21
	v_mul_f32_e32 v21, v17, v17
	v_max_f32_e32 v17, 0, v22
	v_mul_f32_e32 v22, v18, v18
	v_max_f32_e32 v18, 0, v23
	v_mul_f32_e32 v16, v16, v16
	v_mul_f32_e32 v17, v17, v17
	v_mul_f32_e32 v18, v18, v18
	v_mul_f32_e32 v19, v19, v19
	v_mul_f32_e32 v20, v20, v20
	v_cvt_pk_bf16_f32 v16, v20, v16
	v_cvt_pk_bf16_f32 v17, v17, v18
	v_cvt_pk_bf16_f32 v18, v24, v21
	v_cvt_pk_bf16_f32 v19, v22, v19
	global_store_dwordx4 v[32:33], v[16:19], off offset:256
	s_nop 1
	v_mov_b64_e32 v[16:17], v[250:251]
	s_mov_b64 s[0:1], 0x2c0000
	v_cvt_f64_u32_e32 v[18:19], v17
	v_ldexp_f64 v[18:19], v[18:19], 32
	v_cvt_f64_u32_e32 v[16:17], v16
	v_add_f64 v[16:17], v[18:19], v[16:17]
	v_ldexp_f64 v[16:17], v[16:17], s93
	v_cvt_f32_f64_e32 v16, v[16:17]
	v_fmamk_f32 v16, v16, 0x3a000000, v189
	v_cmp_gt_f32_e32 vcc, s78, v16
	v_mul_f32_e32 v17, 0x4b800000, v16
	v_lshl_add_u64 v[18:19], v[140:141], 0, s[0:1]
	v_cndmask_b32_e32 v16, v16, v17, vcc
	v_rsq_f32_e32 v16, v16
	s_mov_b32 s0, 0x2c0000
	v_mul_f32_e32 v17, 0x45800000, v16
	v_cndmask_b32_e32 v16, v16, v17, vcc
	v_pk_mul_f32 v[8:9], v[8:9], v[16:17] op_sel_hi:[1,0]
	v_pk_mul_f32 v[12:13], v[12:13], v[16:17] op_sel_hi:[1,0]
	v_pk_mul_f32 v[10:11], v[10:11], v[16:17] op_sel_hi:[1,0]
	v_max_f32_e32 v8, 0, v8
	v_pk_mul_f32 v[14:15], v[14:15], v[16:17] op_sel_hi:[1,0]
	v_max_f32_e32 v12, 0, v12
	v_mul_f32_e32 v17, v8, v8
	v_max_f32_e32 v8, 0, v13
	v_max_f32_e32 v9, 0, v9
	v_max_f32_e32 v10, 0, v10
	v_mul_f32_e32 v12, v12, v12
	v_mul_f32_e32 v8, v8, v8
	v_mul_f32_e32 v13, v9, v9
	v_max_f32_e32 v9, 0, v14
	v_mul_f32_e32 v14, v10, v10
	v_max_f32_e32 v10, 0, v15
	v_mul_f32_e32 v9, v9, v9
	v_max_f32_e32 v11, 0, v11
	v_mul_f32_e32 v10, v10, v10
	v_cvt_pk_bf16_f32 v8, v12, v8
	v_add_co_u32_e32 v12, vcc, s0, v140
	v_pk_mul_f32 v[2:3], v[2:3], v[16:17] op_sel_hi:[1,0]
	v_pk_mul_f32 v[0:1], v[0:1], v[16:17] op_sel_hi:[1,0]
	v_mul_f32_e32 v11, v11, v11
	v_cvt_pk_bf16_f32 v9, v9, v10
	v_cvt_pk_bf16_f32 v10, v17, v13
	v_addc_co_u32_e32 v13, vcc, 0, v141, vcc
	v_pk_mul_f32 v[6:7], v[6:7], v[16:17] op_sel_hi:[1,0]
	v_pk_mul_f32 v[4:5], v[4:5], v[16:17] op_sel_hi:[1,0]
	v_max_f32_e32 v0, 0, v0
	v_max_f32_e32 v1, 0, v1
	v_max_f32_e32 v2, 0, v2
	v_cvt_pk_bf16_f32 v11, v14, v11
	global_store_dwordx4 v[12:13], v[8:11], off
	v_max_f32_e32 v3, 0, v3
	v_max_f32_e32 v4, 0, v4
	v_mul_f32_e32 v8, v0, v0
	v_max_f32_e32 v0, 0, v5
	v_mul_f32_e32 v5, v1, v1
	v_max_f32_e32 v1, 0, v6
	v_mul_f32_e32 v6, v2, v2
	v_max_f32_e32 v2, 0, v7
	v_mul_f32_e32 v0, v0, v0
	v_mul_f32_e32 v1, v1, v1
	v_mul_f32_e32 v2, v2, v2
	v_mul_f32_e32 v3, v3, v3
	s_and_b64 vcc, exec, s[8:9]
	s_mov_b32 s0, s16
	v_mul_f32_e32 v4, v4, v4
	v_cvt_pk_bf16_f32 v0, v4, v0
	v_cvt_pk_bf16_f32 v1, v1, v2
	v_cvt_pk_bf16_f32 v2, v8, v5
	v_cvt_pk_bf16_f32 v3, v6, v3
	global_store_dwordx4 v[18:19], v[0:3], off offset:256
	s_cbranch_vccz .LBB0_918
	s_waitcnt vmcnt(0)
	s_cmpk_gt_u32 s42, 0xff
	s_cbranch_scc1 .LBB0_929
	s_barrier

; #define PG8_STAGE(bufoff, gbase, voff) do { _Pragma("unroll") for (int _i = 0; _i < 2; ++_i) \
;         __builtin_amdgcn_global_load_lds((const unsigned*)((const char*)(gbase) + (voff)[_i]), (LAS unsigned*)(lds + (bufoff) + ldsw + _i * 8192), 16, 0, 0); } while (0)
; #define PG8_LDA(dst, b, h) do { _Pragma("unroll") for (int m = 0; m < 4; ++m) _Pragma("unroll") for (int k = 0; k < 2; ++k) dst[m][k] = *(const LAS bf16x8*)(lds + PG8_SA(b, h) + aoff + m * 2048 + k * 1024); } while (0)
; #define PG8_LDB(dst, b, h) do { _Pragma("unroll") for (int n = 0; n < 2; ++n) _Pragma("unroll") for (int k = 0; k < 2; ++k) dst[n][k] = *(const LAS bf16x8*)(lds + PG8_SB(b, h) + boff + n * 2048 + k * 1024); } while (0)
; #define PG8_MMA(ai, bj, At, Bt) do { __builtin_amdgcn_s_setprio(1); _Pragma("unroll") for (int m = 0; m < 4; ++m) _Pragma("unroll") for (int n = 0; n < 2; ++n) _Pragma("unroll") for (int k = 0; k < 2; ++k) \
;         acc[ai][bj][m][n] = __builtin_amdgcn_mfma_f32_16x16x32_bf16(Bt[n][k], At[m][k], acc[ai][bj][m][n], 0, 0, 0); __builtin_amdgcn_s_setprio(0); } while (0)
; #define PG8_WAIT_L(n) asm volatile("s_waitcnt lgkmcnt(" #n ")" ::: "memory")
; #define PG8_BAR __builtin_amdgcn_s_barrier()
; #define PG8_SCHED __builtin_amdgcn_sched_barrier(0)
; template <class Epi>
; __device__ __forceinline__ void gemm_phase(const int TID, const int BID, LAS unsigned char* lds, const Gemm g, const StaticOrder& S, const Epi& E) {
;     ...
;         for (int t = 0; t < nt; t += 2) {
;             const bool last = (t == nt - 2);
;             const char* a1 = cA + (size_t)(t + 1) * kstep;
;             const char* a2 = last ? nA : cA + (size_t)(t + 2) * kstep; const char* b2 = last ? nB : cB + (size_t)(t + 2) * kstep;
;             const char* a3 = a2 + kstep; const char* b3 = b2 + kstep;
;             PG8_LDB(B0, 0, 0); PG8_SCHED; PG8_LDA(At, 0, 0); PG8_STAGE(PG8_SA(1, 1), a1 + hstepA, voffA);
;             PG8_WAIT_L(8); PG8_BAR; PG8_WAIT_L(0); PG8_MMA(0, 0, At, B0); PG8_BAR; PG8_SCHED;
;             PG8_LDB(B1, 0, 1); PG8_STAGE(PG8_SB(0, 0), b2, voffB);
;             PG8_BAR; PG8_WAIT_L(0); PG8_MMA(0, 1, At, B1); PG8_BAR;
;             PG8_LDA(At, 0, 1); PG8_STAGE(PG8_SA(0, 0), a2, voffA);
;             PG8_BAR; PG8_WAIT_L(0); PG8_MMA(1, 0, At, B0); PG8_BAR; PG8_SCHED;
.LBB0_955:
	v_add_u32_e32 v68, s63, v198
	ds_read_b128 v[48:51], v68
	ds_read_b128 v[52:55], v68 offset:1024
	ds_read_b128 v[60:63], v68 offset:2048
	ds_read_b128 v[68:71], v68 offset:3072
	s_add_i32 vcc_lo, s14, 2
	s_add_u32 s16, s12, 0x80
	s_addc_u32 s15, s13, 0
	s_cmp_eq_u32 s88, s14
	s_cselect_b32 s14, s50, s16
	s_cselect_b32 s15, s51, s15
	s_cselect_b32 s17, s53, s19
	s_cselect_b32 s16, s52, s18
	v_lshl_add_u64 v[182:183], s[12:13], 0, v[166:167]
	s_add_i32 m0, s76, 0xc000
	ds_read_b128 v[144:147], v200
	ds_read_b128 v[148:151], v200 offset:1024
	ds_read_b128 v[170:173], v200 offset:2048
	ds_read_b128 v[174:177], v200 offset:3072
	ds_read_b128 v[178:181], v200 offset:4096
	ds_read_b128 v[208:211], v200 offset:5120
	ds_read_b128 v[212:215], v200 offset:6144
	ds_read_b128 v[216:219], v200 offset:7168
	global_load_lds_dwordx4 v[182:183], off
	v_lshl_add_u64 v[182:183], s[12:13], 0, v[168:169]
	s_add_i32 m0, s76, 0xe000
	s_nop 0
	global_load_lds_dwordx4 v[182:183], off
	s_waitcnt lgkmcnt(8)
	s_barrier
	s_waitcnt lgkmcnt(0)
	s_setprio 1
	v_mfma_f32_16x16x32_bf16 v[140:143], v[48:51], v[144:147], v[140:143]
	v_mfma_f32_16x16x32_bf16 v[136:139], v[60:63], v[144:147], v[136:139]
	v_mfma_f32_16x16x32_bf16 v[124:127], v[48:51], v[170:173], v[124:127]
	v_mfma_f32_16x16x32_bf16 v[120:123], v[60:63], v[170:173], v[120:123]
	v_mfma_f32_16x16x32_bf16 v[108:111], v[48:51], v[178:181], v[108:111]
	v_mfma_f32_16x16x32_bf16 v[104:107], v[60:63], v[178:181], v[104:107]
	v_mfma_f32_16x16x32_bf16 v[92:95], v[48:51], v[212:215], v[92:95]
	v_mfma_f32_16x16x32_bf16 v[88:91], v[60:63], v[212:215], v[88:91]
	v_mfma_f32_16x16x32_bf16 v[140:143], v[52:55], v[148:151], v[140:143]
	v_mfma_f32_16x16x32_bf16 v[136:139], v[68:71], v[148:151], v[136:139]
	v_mfma_f32_16x16x32_bf16 v[124:127], v[52:55], v[174:177], v[124:127]
	v_mfma_f32_16x16x32_bf16 v[120:123], v[68:71], v[174:177], v[120:123]
	v_mfma_f32_16x16x32_bf16 v[108:111], v[52:55], v[208:211], v[108:111]
	v_mfma_f32_16x16x32_bf16 v[104:107], v[68:71], v[208:211], v[104:107]
	v_mfma_f32_16x16x32_bf16 v[92:95], v[52:55], v[216:219], v[92:95]
	v_mfma_f32_16x16x32_bf16 v[88:91], v[68:71], v[216:219], v[88:91]
	s_setprio 0
	s_barrier
	v_add_u32_e32 v182, s80, v198
	s_mov_b32 m0, s0
	ds_read_b128 v[220:223], v182
	ds_read_b128 v[224:227], v182 offset:1024
	ds_read_b128 v[228:231], v182 offset:2048
	ds_read_b128 v[232:235], v182 offset:3072
	v_lshl_add_u64 v[182:183], s[16:17], 0, v[160:161]
	global_load_lds_dwordx4 v[182:183], off
	v_lshl_add_u64 v[236:237], s[16:17], 0, v[158:159]
	s_mov_b32 m0, s1
	s_nop 0
	global_load_lds_dwordx4 v[236:237], off
	s_barrier
	s_waitcnt lgkmcnt(0)
	s_setprio 1
	v_mfma_f32_16x16x32_bf16 v[132:135], v[220:223], v[144:147], v[132:135]
	v_mfma_f32_16x16x32_bf16 v[128:131], v[228:231], v[144:147], v[128:131]
	v_mfma_f32_16x16x32_bf16 v[116:119], v[220:223], v[170:173], v[116:119]
	v_mfma_f32_16x16x32_bf16 v[112:115], v[228:231], v[170:173], v[112:115]
	v_mfma_f32_16x16x32_bf16 v[100:103], v[220:223], v[178:181], v[100:103]
	v_mfma_f32_16x16x32_bf16 v[96:99], v[228:231], v[178:181], v[96:99]
	v_mfma_f32_16x16x32_bf16 v[84:87], v[220:223], v[212:215], v[84:87]
	v_mfma_f32_16x16x32_bf16 v[80:83], v[228:231], v[212:215], v[80:83]
	v_mfma_f32_16x16x32_bf16 v[132:135], v[224:227], v[148:151], v[132:135]
	v_mfma_f32_16x16x32_bf16 v[128:131], v[232:235], v[148:151], v[128:131]
	v_mfma_f32_16x16x32_bf16 v[116:119], v[224:227], v[174:177], v[116:119]
	v_mfma_f32_16x16x32_bf16 v[112:115], v[232:235], v[174:177], v[112:115]
	v_mfma_f32_16x16x32_bf16 v[100:103], v[224:227], v[208:211], v[100:103]
	v_mfma_f32_16x16x32_bf16 v[96:99], v[232:235], v[208:211], v[96:99]
	v_mfma_f32_16x16x32_bf16 v[84:87], v[224:227], v[216:219], v[84:87]
	v_mfma_f32_16x16x32_bf16 v[80:83], v[232:235], v[216:219], v[80:83]
	s_setprio 0
	s_mov_b32 m0, s76
	v_lshl_add_u64 v[238:239], s[14:15], 0, v[154:155]
	s_barrier
	ds_read_b128 v[144:147], v200 offset:16384
	ds_read_b128 v[148:151], v200 offset:17408
	ds_read_b128 v[170:173], v200 offset:18432
	ds_read_b128 v[174:177], v200 offset:19456
	ds_read_b128 v[178:181], v200 offset:20480
	ds_read_b128 v[208:211], v200 offset:21504
	ds_read_b128 v[212:215], v200 offset:22528
	ds_read_b128 v[216:219], v200 offset:23552
	global_load_lds_dwordx4 v[238:239], off
	v_lshl_add_u64 v[240:241], s[14:15], 0, v[156:157]
	s_mov_b32 m0, s22
	s_nop 0
	global_load_lds_dwordx4 v[240:241], off
	s_barrier
	s_waitcnt lgkmcnt(0)
	s_setprio 1
	v_mfma_f32_16x16x32_bf16 v[76:79], v[48:51], v[144:147], v[76:79]
	v_mfma_f32_16x16x32_bf16 v[72:75], v[60:63], v[144:147], v[72:75]
	v_mfma_f32_16x16x32_bf16 v[44:47], v[48:51], v[170:173], v[44:47]
	v_mfma_f32_16x16x32_bf16 v[40:43], v[60:63], v[170:173], v[40:43]
	v_mfma_f32_16x16x32_bf16 v[28:31], v[48:51], v[178:181], v[28:31]
	v_mfma_f32_16x16x32_bf16 v[24:27], v[60:63], v[178:181], v[24:27]
	v_mfma_f32_16x16x32_bf16 v[12:15], v[48:51], v[212:215], v[12:15]
	v_mfma_f32_16x16x32_bf16 v[8:11], v[60:63], v[212:215], v[8:11]
	v_mfma_f32_16x16x32_bf16 v[76:79], v[52:55], v[148:151], v[76:79]
	v_mfma_f32_16x16x32_bf16 v[72:75], v[68:71], v[148:151], v[72:75]
	v_mfma_f32_16x16x32_bf16 v[44:47], v[52:55], v[174:177], v[44:47]
	v_mfma_f32_16x16x32_bf16 v[40:43], v[68:71], v[174:177], v[40:43]
	v_mfma_f32_16x16x32_bf16 v[28:31], v[52:55], v[208:211], v[28:31]
	v_mfma_f32_16x16x32_bf16 v[24:27], v[68:71], v[208:211], v[24:27]
	v_mfma_f32_16x16x32_bf16 v[12:15], v[52:55], v[216:219], v[12:15]
	v_mfma_f32_16x16x32_bf16 v[8:11], v[68:71], v[216:219], v[8:11]
	s_setprio 0
	s_barrier
; #define PG8_STAGE(bufoff, gbase, voff) do { _Pragma("unroll") for (int _i = 0; _i < 2; ++_i) \
;         __builtin_amdgcn_global_load_lds((const unsigned*)((const char*)(gbase) + (voff)[_i]), (LAS unsigned*)(lds + (bufoff) + ldsw + _i * 8192), 16, 0, 0); } while (0)
; #define PG8_LDA(dst, b, h) do { _Pragma("unroll") for (int m = 0; m < 4; ++m) _Pragma("unroll") for (int k = 0; k < 2; ++k) dst[m][k] = *(const LAS bf16x8*)(lds + PG8_SA(b, h) + aoff + m * 2048 + k * 1024); } while (0)
; #define PG8_LDB(dst, b, h) do { _Pragma("unroll") for (int n = 0; n < 2; ++n) _Pragma("unroll") for (int k = 0; k < 2; ++k) dst[n][k] = *(const LAS bf16x8*)(lds + PG8_SB(b, h) + boff + n * 2048 + k * 1024); } while (0)
; #define PG8_MMA(ai, bj, At, Bt) do { __builtin_amdgcn_s_setprio(1); _Pragma("unroll") for (int m = 0; m < 4; ++m) _Pragma("unroll") for (int n = 0; n < 2; ++n) _Pragma("unroll") for (int k = 0; k < 2; ++k) \
;         acc[ai][bj][m][n] = __builtin_amdgcn_mfma_f32_16x16x32_bf16(Bt[n][k], At[m][k], acc[ai][bj][m][n], 0, 0, 0); __builtin_amdgcn_s_setprio(0); } while (0)
; #define PG8_WAIT_V(n) asm volatile("s_waitcnt vmcnt(" #n ")" ::: "memory")
; #define PG8_WAIT_L(n) asm volatile("s_waitcnt lgkmcnt(" #n ")" ::: "memory")
; #define PG8_BAR __builtin_amdgcn_s_barrier()
; #define PG8_SCHED __builtin_amdgcn_sched_barrier(0)
; template <class Epi>
; __device__ __forceinline__ void gemm_phase(const int TID, const int BID, LAS unsigned char* lds, const Gemm g, const StaticOrder& S, const Epi& E) {
;     ...
;             PG8_STAGE(PG8_SB(0, 1), b2 + hstepB, voffB);
;             PG8_WAIT_V(6); PG8_BAR; PG8_MMA(1, 1, At, B1); PG8_BAR;
;             PG8_LDB(B0, 1, 0); PG8_SCHED; PG8_LDA(At, 1, 0); PG8_STAGE(PG8_SA(0, 1), a2 + hstepA, voffA);
;             PG8_WAIT_L(8); PG8_BAR; PG8_WAIT_L(0); PG8_MMA(0, 0, At, B0); PG8_BAR; PG8_SCHED;
;             PG8_LDB(B1, 1, 1); PG8_STAGE(PG8_SB(1, 0), b3, voffB);
;             PG8_BAR; PG8_WAIT_L(0); PG8_MMA(0, 1, At, B1); PG8_BAR;
	s_add_u32 s16, s16, s58
	s_addc_u32 s17, s17, 0
	s_mov_b32 m0, s71
	v_lshl_add_u64 v[242:243], s[16:17], 0, v[160:161]
	global_load_lds_dwordx4 v[242:243], off
	v_lshl_add_u64 v[244:245], s[16:17], 0, v[158:159]
	s_mov_b32 m0, s23
	s_nop 0
	global_load_lds_dwordx4 v[244:245], off
	s_waitcnt vmcnt(6)
	s_barrier
	s_setprio 1
	v_mfma_f32_16x16x32_bf16 v[36:39], v[220:223], v[170:173], v[36:39]
	v_mfma_f32_16x16x32_bf16 v[32:35], v[228:231], v[170:173], v[32:35]
	v_mfma_f32_16x16x32_bf16 v[20:23], v[220:223], v[178:181], v[20:23]
	v_mfma_f32_16x16x32_bf16 v[16:19], v[228:231], v[178:181], v[16:19]
	v_mfma_f32_16x16x32_bf16 v[4:7], v[220:223], v[212:215], v[4:7]
	v_mfma_f32_16x16x32_bf16 v[0:3], v[228:231], v[212:215], v[0:3]
	v_mfma_f32_16x16x32_bf16 v[48:51], v[220:223], v[144:147], v[64:67]
	v_mfma_f32_16x16x32_bf16 v[52:55], v[228:231], v[144:147], v[56:59]
	v_mfma_f32_16x16x32_bf16 v[36:39], v[224:227], v[174:177], v[36:39]
	v_mfma_f32_16x16x32_bf16 v[32:35], v[232:235], v[174:177], v[32:35]
	v_mfma_f32_16x16x32_bf16 v[20:23], v[224:227], v[208:211], v[20:23]
	v_mfma_f32_16x16x32_bf16 v[16:19], v[232:235], v[208:211], v[16:19]
	v_mfma_f32_16x16x32_bf16 v[4:7], v[224:227], v[216:219], v[4:7]
	v_mfma_f32_16x16x32_bf16 v[0:3], v[232:235], v[216:219], v[0:3]
	v_mfma_f32_16x16x32_bf16 v[48:51], v[224:227], v[148:151], v[48:51]
	v_mfma_f32_16x16x32_bf16 v[52:55], v[232:235], v[148:151], v[52:55]
	s_setprio 0
	v_add_u32_e32 v68, s81, v198
	s_barrier
	ds_read_b128 v[56:59], v68
	ds_read_b128 v[60:63], v68 offset:1024
	ds_read_b128 v[64:67], v68 offset:2048
	ds_read_b128 v[68:71], v68 offset:3072
	s_add_u32 s14, s14, s36
	s_addc_u32 s15, s15, 0
	s_mov_b32 m0, s96
	v_lshl_add_u64 v[220:221], s[14:15], 0, v[154:155]
	ds_read_b128 v[144:147], v200 offset:32768
	ds_read_b128 v[148:151], v200 offset:33792
	ds_read_b128 v[170:173], v200 offset:34816
	ds_read_b128 v[174:177], v200 offset:35840
	ds_read_b128 v[178:181], v200 offset:36864
	ds_read_b128 v[208:211], v200 offset:37888
	ds_read_b128 v[212:215], v200 offset:38912
	ds_read_b128 v[216:219], v200 offset:39936
	global_load_lds_dwordx4 v[220:221], off
	v_lshl_add_u64 v[220:221], s[14:15], 0, v[156:157]
	s_mov_b32 m0, s97
	s_nop 0
	global_load_lds_dwordx4 v[220:221], off
	s_waitcnt lgkmcnt(8)
	s_barrier
	s_waitcnt lgkmcnt(0)
	s_setprio 1
	v_mfma_f32_16x16x32_bf16 v[140:143], v[56:59], v[144:147], v[140:143]
	v_mfma_f32_16x16x32_bf16 v[136:139], v[64:67], v[144:147], v[136:139]
	v_mfma_f32_16x16x32_bf16 v[124:127], v[56:59], v[170:173], v[124:127]
	v_mfma_f32_16x16x32_bf16 v[120:123], v[64:67], v[170:173], v[120:123]
	v_mfma_f32_16x16x32_bf16 v[108:111], v[56:59], v[178:181], v[108:111]
	v_mfma_f32_16x16x32_bf16 v[104:107], v[64:67], v[178:181], v[104:107]
	v_mfma_f32_16x16x32_bf16 v[92:95], v[56:59], v[212:215], v[92:95]
	v_mfma_f32_16x16x32_bf16 v[88:91], v[64:67], v[212:215], v[88:91]
	v_mfma_f32_16x16x32_bf16 v[140:143], v[60:63], v[148:151], v[140:143]
	v_mfma_f32_16x16x32_bf16 v[136:139], v[68:71], v[148:151], v[136:139]
	v_mfma_f32_16x16x32_bf16 v[124:127], v[60:63], v[174:177], v[124:127]
	v_mfma_f32_16x16x32_bf16 v[120:123], v[68:71], v[174:177], v[120:123]
	v_mfma_f32_16x16x32_bf16 v[108:111], v[60:63], v[208:211], v[108:111]
	v_mfma_f32_16x16x32_bf16 v[104:107], v[68:71], v[208:211], v[104:107]
	v_mfma_f32_16x16x32_bf16 v[92:95], v[60:63], v[216:219], v[92:95]
	v_mfma_f32_16x16x32_bf16 v[88:91], v[68:71], v[216:219], v[88:91]
	s_setprio 0
	s_barrier
	s_mov_b32 m0, s66
	v_add_u32_e32 v201, s87, v198
	v_lshl_add_u64 v[182:183], v[182:183], 0, s[90:91]
	ds_read_b128 v[220:223], v201
	ds_read_b128 v[224:227], v201 offset:1024
	ds_read_b128 v[228:231], v201 offset:2048
	ds_read_b128 v[232:235], v201 offset:3072
	global_load_lds_dwordx4 v[182:183], off
	v_lshl_add_u64 v[182:183], v[236:237], 0, s[90:91]
	s_mov_b32 m0, s92
	s_nop 0
	global_load_lds_dwordx4 v[182:183], off
	s_barrier
; #define PG8_STAGE(bufoff, gbase, voff) do { _Pragma("unroll") for (int _i = 0; _i < 2; ++_i) \
;         __builtin_amdgcn_global_load_lds((const unsigned*)((const char*)(gbase) + (voff)[_i]), (LAS unsigned*)(lds + (bufoff) + ldsw + _i * 8192), 16, 0, 0); } while (0)
; #define PG8_LDA(dst, b, h) do { _Pragma("unroll") for (int m = 0; m < 4; ++m) _Pragma("unroll") for (int k = 0; k < 2; ++k) dst[m][k] = *(const LAS bf16x8*)(lds + PG8_SA(b, h) + aoff + m * 2048 + k * 1024); } while (0)
; #define PG8_MMA(ai, bj, At, Bt) do { __builtin_amdgcn_s_setprio(1); _Pragma("unroll") for (int m = 0; m < 4; ++m) _Pragma("unroll") for (int n = 0; n < 2; ++n) _Pragma("unroll") for (int k = 0; k < 2; ++k) \
;         acc[ai][bj][m][n] = __builtin_amdgcn_mfma_f32_16x16x32_bf16(Bt[n][k], At[m][k], acc[ai][bj][m][n], 0, 0, 0); __builtin_amdgcn_s_setprio(0); } while (0)
; #define PG8_WAIT_V(n) asm volatile("s_waitcnt vmcnt(" #n ")" ::: "memory")
; #define PG8_WAIT_L(n) asm volatile("s_waitcnt lgkmcnt(" #n ")" ::: "memory")
; #define PG8_BAR __builtin_amdgcn_s_barrier()
; #define PG8_SCHED __builtin_amdgcn_sched_barrier(0)
; template <class Epi>
; __device__ __forceinline__ void gemm_phase(const int TID, const int BID, LAS unsigned char* lds, const Gemm g, const StaticOrder& S, const Epi& E) {
;     ...
;             PG8_BAR; PG8_WAIT_L(0); PG8_MMA(0, 1, At, B1); PG8_BAR;
;             PG8_LDA(At, 1, 1); PG8_STAGE(PG8_SA(1, 0), a3, voffA);
;             PG8_BAR; PG8_WAIT_L(0); PG8_MMA(1, 0, At, B0); PG8_BAR; PG8_SCHED;
;             PG8_STAGE(PG8_SB(1, 1), b3 + hstepB, voffB);
;             PG8_WAIT_V(6); PG8_BAR; PG8_MMA(1, 1, At, B1); PG8_BAR;
;     __device__ __forceinline__ void operator()(const f32x4 (&acc)[2][2][4][2], const Unit& u, int wr, int wc, int fr, int fq) const {
;     ...
;             for (int n = 0; n < 2; ++n) cs[bj][n] = colscale ? *(const f32x4*)(colscale + col0 + bj * HALF + 4 * n) : (f32x4){1.f, 1.f, 1.f, 1.f};
	s_waitcnt lgkmcnt(0)
	s_setprio 1
	v_mfma_f32_16x16x32_bf16 v[132:135], v[220:223], v[144:147], v[132:135]
	v_mfma_f32_16x16x32_bf16 v[128:131], v[228:231], v[144:147], v[128:131]
	v_mfma_f32_16x16x32_bf16 v[116:119], v[220:223], v[170:173], v[116:119]
	v_mfma_f32_16x16x32_bf16 v[112:115], v[228:231], v[170:173], v[112:115]
	v_mfma_f32_16x16x32_bf16 v[100:103], v[220:223], v[178:181], v[100:103]
	v_mfma_f32_16x16x32_bf16 v[96:99], v[228:231], v[178:181], v[96:99]
	v_mfma_f32_16x16x32_bf16 v[84:87], v[220:223], v[212:215], v[84:87]
	v_mfma_f32_16x16x32_bf16 v[80:83], v[228:231], v[212:215], v[80:83]
	v_mfma_f32_16x16x32_bf16 v[132:135], v[224:227], v[148:151], v[132:135]
	v_mfma_f32_16x16x32_bf16 v[128:131], v[232:235], v[148:151], v[128:131]
	v_mfma_f32_16x16x32_bf16 v[116:119], v[224:227], v[174:177], v[116:119]
	v_mfma_f32_16x16x32_bf16 v[112:115], v[232:235], v[174:177], v[112:115]
	v_mfma_f32_16x16x32_bf16 v[100:103], v[224:227], v[208:211], v[100:103]
	v_mfma_f32_16x16x32_bf16 v[96:99], v[232:235], v[208:211], v[96:99]
	v_mfma_f32_16x16x32_bf16 v[84:87], v[224:227], v[216:219], v[84:87]
	v_mfma_f32_16x16x32_bf16 v[80:83], v[232:235], v[216:219], v[80:83]
	s_setprio 0
	s_mov_b32 m0, s4
	v_lshl_add_u64 v[182:183], v[238:239], 0, s[90:91]
	s_barrier
	ds_read_b128 v[144:147], v200 offset:49152
	ds_read_b128 v[148:151], v200 offset:50176
	ds_read_b128 v[170:173], v200 offset:51200
	ds_read_b128 v[174:177], v200 offset:52224
	ds_read_b128 v[178:181], v200 offset:53248
	ds_read_b128 v[208:211], v200 offset:54272
	ds_read_b128 v[212:215], v200 offset:55296
	ds_read_b128 v[216:219], v200 offset:56320
	global_load_lds_dwordx4 v[182:183], off
	v_lshl_add_u64 v[182:183], v[240:241], 0, s[90:91]
	s_mov_b32 m0, s64
	s_nop 0
	global_load_lds_dwordx4 v[182:183], off
	s_barrier
	s_waitcnt lgkmcnt(0)
	s_setprio 1
	v_mfma_f32_16x16x32_bf16 v[76:79], v[56:59], v[144:147], v[76:79]
	v_mfma_f32_16x16x32_bf16 v[72:75], v[64:67], v[144:147], v[72:75]
	v_mfma_f32_16x16x32_bf16 v[44:47], v[56:59], v[170:173], v[44:47]
	v_mfma_f32_16x16x32_bf16 v[40:43], v[64:67], v[170:173], v[40:43]
	v_mfma_f32_16x16x32_bf16 v[28:31], v[56:59], v[178:181], v[28:31]
	v_mfma_f32_16x16x32_bf16 v[24:27], v[64:67], v[178:181], v[24:27]
	v_mfma_f32_16x16x32_bf16 v[12:15], v[56:59], v[212:215], v[12:15]
	v_mfma_f32_16x16x32_bf16 v[8:11], v[64:67], v[212:215], v[8:11]
	v_mfma_f32_16x16x32_bf16 v[76:79], v[60:63], v[148:151], v[76:79]
	v_mfma_f32_16x16x32_bf16 v[72:75], v[68:71], v[148:151], v[72:75]
	v_mfma_f32_16x16x32_bf16 v[44:47], v[60:63], v[174:177], v[44:47]
	v_mfma_f32_16x16x32_bf16 v[40:43], v[68:71], v[174:177], v[40:43]
	v_mfma_f32_16x16x32_bf16 v[28:31], v[60:63], v[208:211], v[28:31]
	v_mfma_f32_16x16x32_bf16 v[24:27], v[68:71], v[208:211], v[24:27]
	v_mfma_f32_16x16x32_bf16 v[12:15], v[60:63], v[216:219], v[12:15]
	v_mfma_f32_16x16x32_bf16 v[8:11], v[68:71], v[216:219], v[8:11]
	s_setprio 0
	s_barrier
	s_mov_b32 m0, s74
	v_lshl_add_u64 v[56:57], v[242:243], 0, s[90:91]
	global_load_lds_dwordx4 v[56:57], off
	v_lshl_add_u64 v[56:57], v[244:245], 0, s[90:91]
	s_mov_b32 m0, s95
	s_nop 0
	global_load_lds_dwordx4 v[56:57], off
	s_waitcnt vmcnt(6)
	s_barrier
	s_setprio 1
	v_mfma_f32_16x16x32_bf16 v[48:51], v[220:223], v[144:147], v[48:51]
	v_mfma_f32_16x16x32_bf16 v[64:67], v[224:227], v[148:151], v[48:51]
	v_mfma_f32_16x16x32_bf16 v[48:51], v[228:231], v[144:147], v[52:55]
	v_mfma_f32_16x16x32_bf16 v[36:39], v[220:223], v[170:173], v[36:39]
	v_mfma_f32_16x16x32_bf16 v[32:35], v[228:231], v[170:173], v[32:35]
	v_mfma_f32_16x16x32_bf16 v[20:23], v[220:223], v[178:181], v[20:23]
	v_mfma_f32_16x16x32_bf16 v[16:19], v[228:231], v[178:181], v[16:19]
	v_mfma_f32_16x16x32_bf16 v[4:7], v[220:223], v[212:215], v[4:7]
	v_mfma_f32_16x16x32_bf16 v[0:3], v[228:231], v[212:215], v[0:3]
	v_mfma_f32_16x16x32_bf16 v[56:59], v[232:235], v[148:151], v[48:51]
	v_mfma_f32_16x16x32_bf16 v[36:39], v[224:227], v[174:177], v[36:39]
	v_mfma_f32_16x16x32_bf16 v[32:35], v[232:235], v[174:177], v[32:35]
	v_mfma_f32_16x16x32_bf16 v[20:23], v[224:227], v[208:211], v[20:23]
	v_mfma_f32_16x16x32_bf16 v[16:19], v[232:235], v[208:211], v[16:19]
	v_mfma_f32_16x16x32_bf16 v[4:7], v[224:227], v[216:219], v[4:7]
	v_mfma_f32_16x16x32_bf16 v[0:3], v[232:235], v[216:219], v[0:3]
	s_setprio 0
	s_add_u32 s12, s12, 0x100
	s_addc_u32 s13, s13, 0
	s_add_u32 s18, s18, 0x100
	s_addc_u32 s19, s19, 0
	s_cmp_ge_u32 vcc_lo, s57
	s_mov_b32 s14, vcc_lo
	s_barrier
	s_cbranch_scc0 .LBB0_955
	v_lshl_add_u32 v174, s55, 8, v199
	v_ashrrev_i32_e32 v175, 31, v174
	v_mov_b32_e32 v60, 1.0
	v_cndmask_b32_e64 v48, 0, 1, s[40:41]
	v_lshl_add_u64 v[144:145], v[174:175], 2, s[26:27]
	v_cmp_ne_u32_e64 s[12:13], 1, v48
	s_andn2_b64 vcc, exec, s[40:41]
	v_mov_b32_e32 v68, 1.0
	v_mov_b32_e32 v69, v60
	v_mov_b32_e32 v70, 1.0
	v_mov_b32_e32 v71, 1.0
	s_cbranch_vccnz .LBB0_958
	global_load_dwordx4 v[68:71], v[144:145], off
